# every P0 store written through (sub-key splits too): the first grid barrier needs no L2 write-back, buffer_wbl2 dropped from its arrive
# baseline (speedup 1.0000x reference)
; __device__ __forceinline__ float sbf2f(short v) { return __uint_as_float(((unsigned)(unsigned short)v) << 16); }
; __global__ void __launch_bounds__(NTHR, 2) k_main(Args a) {
;     ...
;         for (int i = gtid; i < 2 * 128 * 64; i += gthreads) { const float kf = a.peer_sub_keys[i]; const short h = bfs(kf); KH[i] = (bf16)h; KL[i] = (bf16)bfs(kf - sbf2f(h)); }
.LBB0_13:
	global_load_dword v1, v[6:7], off
	v_add_co_u32_e32 v10, vcc, 0x10000, v8
	v_add_u32_e32 v4, s56, v4
	s_nop 0
	v_addc_co_u32_e32 v11, vcc, 0, v9, vcc
	v_cmp_lt_i32_e32 vcc, s3, v4
	v_lshl_add_u64 v[6:7], v[6:7], 0, s[4:5]
	s_or_b64 s[12:13], vcc, s[12:13]
	s_waitcnt vmcnt(0)
	v_cvt_pk_bf16_f32 v3, v1, s0
	global_store_short v[8:9], v3, off sc1
	v_lshlrev_b32_e32 v3, 16, v3
	v_sub_f32_e32 v1, v1, v3
	v_lshl_add_u64 v[8:9], v[8:9], 0, s[10:11]
	v_cvt_pk_bf16_f32 v1, v1, s0
	global_store_short v[10:11], v1, off sc1
	s_andn2_b64 exec, exec, s[12:13]
	s_cbranch_execnz .LBB0_13

; __device__ __forceinline__ unsigned xb_add(unsigned* p, unsigned v) { return __hip_atomic_fetch_add(p, v, __ATOMIC_RELAXED, __HIP_MEMORY_SCOPE_AGENT); }
; __device__ __forceinline__ void xcd_barrier(const XcdBarrier& b) {
;     ...
;         const unsigned old = xb_add(&bar[XB_XSUB(b.x)], 1u);
;         const unsigned gen = old / nloc;
;         if (old + 1u == (gen + 1u) * nloc) {
;             __builtin_amdgcn_fence(__ATOMIC_RELEASE, "agent");
;             asm volatile("s_waitcnt vmcnt(0)" ::: "memory");
;             const unsigned og = xb_add(&bar[XB_TOP], 1u);
.LBB0_50:
	s_or_b64 exec, exec, s[10:11]
	v_cvt_f32_u32_e32 v5, v3
	s_waitcnt vmcnt(0)
	v_readfirstlane_b32 s3, v4
	v_sub_u32_e32 v4, 0, v3
	v_rcp_iflag_f32_e32 v5, v5
	v_add_u32_e32 v6, s3, v1
	v_mul_f32_e32 v5, 0x4f7ffffe, v5
	v_cvt_u32_f32_e32 v5, v5
	v_mul_lo_u32 v1, v4, v5
	v_mul_hi_u32 v1, v5, v1
	v_add_u32_e32 v1, v5, v1
	v_mul_hi_u32 v1, v6, v1
	v_mul_lo_u32 v4, v1, v3
	v_sub_u32_e32 v4, v6, v4
	v_add_u32_e32 v5, 1, v1
	v_cmp_ge_u32_e32 vcc, v4, v3
	s_nop 1
	v_cndmask_b32_e32 v1, v1, v5, vcc
	v_sub_u32_e32 v5, v4, v3
	v_cndmask_b32_e32 v4, v4, v5, vcc
	v_add_u32_e32 v5, 1, v1
	v_cmp_ge_u32_e32 vcc, v4, v3
	v_add_u32_e32 v4, 1, v6
	s_nop 0
	v_cndmask_b32_e32 v1, v1, v5, vcc
	v_mul_lo_u32 v5, v3, v1
	v_add_u32_e32 v3, v5, v3
	v_cmp_eq_u32_e32 vcc, v4, v3
	s_and_saveexec_b64 s[8:9], vcc
	s_cbranch_execz .LBB0_86
	s_mov_b64 s[10:11], exec
	s_waitcnt lgkmcnt(0)
	s_waitcnt vmcnt(0)
	v_mbcnt_lo_u32_b32 v3, s10, 0
	v_mbcnt_hi_u32_b32 v3, s11, v3
	v_cmp_eq_u32_e32 vcc, 0, v3
	s_and_saveexec_b64 s[12:13], vcc
	s_cbranch_execz .LBB0_53
	s_bcnt1_i32_b64 s3, s[10:11]
	v_mov_b32_e32 v4, 0x3000
	v_mov_b32_e32 v5, s3
	global_atomic_add v4, v4, v5, s[90:91] offset:1024 sc0

; #define LAS __attribute__((address_space(3)))
; #define MFMA32(a, b, c) __builtin_amdgcn_mfma_f32_32x32x16_bf16((a), (b), (c), 0, 0, 0)
; __device__ __forceinline__ void route_task(int task, int tl0, const bf16* QP  , const LAS bf16* KHL, LAS unsigned short* EL, LAS float* GL, int lane) {
;     const int r = lane & 31, hi = lane >> 5, t = 4 * task + (r >> 3), head = r & 7;
;     int top[2][16]; bf16x8 qa[2][4];
;     { unsigned qo = (unsigned)t * (unsigned)D + (unsigned)(head * 128 + 8 * hi); asm volatile("" : "+v"(qo)); const bf16* qp = QP + qo;
; #pragma unroll
;       for (int hf = 0; hf < 2; ++hf)
; #pragma unroll
;         for (int ks = 0; ks < 4; ++ks) qa[hf][ks] = ldg8(qp + 64 * hf + 16 * ks); }
; #pragma unroll
;     for (int half = 0; half < 2; ++half) {
;         int cur[16];
; #pragma unroll
;         for (int kt = 0; kt < 4; ++kt) {
;             f32x16 X;
; #pragma unroll
;             for (int i = 0; i < 16; ++i) X[i] = 8.f;
;             const LAS bf16* khp = KHL + (half * 128 + 32 * kt + r) * 72 + 8 * hi;
; #pragma unroll
;             for (int ks = 0; ks < 4; ++ks) {
;                 const bf16x8 kh = lds8(khp + 16 * ks);
;                 X = MFMA32(kh, qa[half][ks], X);
;             }
;             int grp[16];
; #pragma unroll
;             for (int i = 0; i < 16; ++i) grp[i] = (int)((__float_as_uint(X[i]) | 127u) - (unsigned)(32 * kt + (i & 3) + 8 * (i >> 2)));
;             sort16_desc(grp);
; __global__ void __launch_bounds__(NTHR, 2) k_main(Args a) {
;     ...
;             for (int i = tid; i < 2 * 128 * 8; i += NTHR) {
;                 const int pc = i & 7, key = (i >> 3) & 127, hf = (i >> 10) & 1, hl = i >> 11;
;                 *(LAS v4u*)(KHL + ((hl * 2 + hf) * 128 + key) * 72 + pc * 8) = *(const v4u*)((hl ? KL : KH) + (size_t)(hf * 128 + key) * 64 + pc * 8);
;             }
;             __syncthreads();
.LBB0_665:
	v_mov_b32_e32 v20, s53
	v_mov_b32_e32 v21, s49
	v_mov_b32_e32 v22, s52
	v_mov_b32_e32 v23, s48
	v_lshlrev_b32_e32 v24, 4, v19
	v_cmp_gt_u32_e32 vcc, s54, v19
	v_lshlrev_b32_e32 v25, 1, v18
	v_and_b32_e32 v82, 0x7f80, v24
	v_cndmask_b32_e32 v21, v20, v21, vcc
	v_cndmask_b32_e32 v20, v22, v23, vcc
	v_lshl_add_u64 v[20:21], v[20:21], 0, v[82:83]
	v_and_b32_e32 v82, 0x70, v25
	v_lshl_add_u64 v[20:21], v[20:21], 0, v[82:83]
	global_load_dwordx4 v[162:165], v[20:21], off
	v_lshrrev_b32_e32 v24, 3, v19
	v_mul_lo_u32 v24, v24, s56
	v_add3_u32 v178, 0, v24, v82
	v_add_u32_e32 v19, 0x200, v19
	v_add_u32_e32 v18, 0x1000, v18
	v_mov_b32_e32 v20, s53
	v_mov_b32_e32 v21, s49
	v_mov_b32_e32 v22, s52
	v_mov_b32_e32 v23, s48
	v_lshlrev_b32_e32 v24, 4, v19
	v_cmp_gt_u32_e32 vcc, s54, v19
	v_lshlrev_b32_e32 v25, 1, v18
	v_and_b32_e32 v82, 0x7f80, v24
	v_cndmask_b32_e32 v21, v20, v21, vcc
	v_cndmask_b32_e32 v20, v22, v23, vcc
	v_lshl_add_u64 v[20:21], v[20:21], 0, v[82:83]
	v_and_b32_e32 v82, 0x70, v25
	v_lshl_add_u64 v[20:21], v[20:21], 0, v[82:83]
	global_load_dwordx4 v[166:169], v[20:21], off
	v_lshrrev_b32_e32 v24, 3, v19
	v_mul_lo_u32 v24, v24, s56
	v_add3_u32 v179, 0, v24, v82
	v_add_u32_e32 v19, 0x200, v19
	v_add_u32_e32 v18, 0x1000, v18
	v_mov_b32_e32 v20, s53
	v_mov_b32_e32 v21, s49
	v_mov_b32_e32 v22, s52
	v_mov_b32_e32 v23, s48
	v_lshlrev_b32_e32 v24, 4, v19
	v_cmp_gt_u32_e32 vcc, s54, v19
	v_lshlrev_b32_e32 v25, 1, v18
	v_and_b32_e32 v82, 0x7f80, v24
	v_cndmask_b32_e32 v21, v20, v21, vcc
	v_cndmask_b32_e32 v20, v22, v23, vcc
	v_lshl_add_u64 v[20:21], v[20:21], 0, v[82:83]
	v_and_b32_e32 v82, 0x70, v25
	v_lshl_add_u64 v[20:21], v[20:21], 0, v[82:83]
	global_load_dwordx4 v[170:173], v[20:21], off
	v_lshrrev_b32_e32 v24, 3, v19
	v_mul_lo_u32 v24, v24, s56
	v_add3_u32 v180, 0, v24, v82
	v_add_u32_e32 v19, 0x200, v19
	v_add_u32_e32 v18, 0x1000, v18
	v_mov_b32_e32 v20, s53
	v_mov_b32_e32 v21, s49
	v_mov_b32_e32 v22, s52
	v_mov_b32_e32 v23, s48
	v_lshlrev_b32_e32 v24, 4, v19
	v_cmp_gt_u32_e32 vcc, s54, v19
	v_lshlrev_b32_e32 v25, 1, v18
	v_and_b32_e32 v82, 0x7f80, v24
	v_cndmask_b32_e32 v21, v20, v21, vcc
	v_cndmask_b32_e32 v20, v22, v23, vcc
	v_lshl_add_u64 v[20:21], v[20:21], 0, v[82:83]
	v_and_b32_e32 v82, 0x70, v25
	v_lshl_add_u64 v[20:21], v[20:21], 0, v[82:83]
	global_load_dwordx4 v[174:177], v[20:21], off
	v_lshrrev_b32_e32 v24, 3, v19
	v_mul_lo_u32 v24, v24, s56
	v_add3_u32 v181, 0, v24, v82
	v_add_u32_e32 v19, 0x200, v19
	v_add_u32_e32 v18, 0x1000, v18
	s_waitcnt vmcnt(0)
	ds_write_b128 v178, v[162:165]
	ds_write_b128 v179, v[166:169]
	ds_write_b128 v180, v[170:173]
	ds_write_b128 v181, v[174:177]
	s_nop 0
	s_nop 0
	s_nop 0
	s_nop 0
	s_nop 0
	s_nop 0
	s_nop 0
	s_nop 0
	s_nop 0
	s_nop 0
	s_nop 0
	s_nop 0
	s_nop 0
.LBB0_666:
	s_or_b64 exec, exec, s[10:11]
	s_lshl_b32 s10, s2, 4
	s_add_i32 s10, s10, s95
	s_lshl_b32 s10, s10, 12
	v_or_b32_e32 v82, s10, v88
	s_waitcnt lgkmcnt(0)
	s_barrier
	s_add_i32 s11, 0, 0x12000
	v_lshl_add_u64 v[70:71], v[82:83], 1, s[80:81]
	global_load_dwordx4 v[62:65], v[70:71], off
	global_load_dwordx4 v[54:57], v[70:71], off offset:32
	global_load_dwordx4 v[58:61], v[70:71], off offset:64
	global_load_dwordx4 v[50:53], v[70:71], off offset:96
	ds_read_b128 v[34:37], v94
	ds_read_b128 v[38:41], v94 offset:32
	s_add_i32 s10, s10, 0x8000
	s_mov_b32 s41, 0
	s_waitcnt vmcnt(3) lgkmcnt(1)
	v_mfma_f32_32x32x16_bf16 v[18:33], v[34:37], v[62:65], v[2:17]
	ds_read_b128 v[34:37], v94 offset:64
	ds_read_b128 v[66:69], v94 offset:96
	s_waitcnt vmcnt(2) lgkmcnt(2)
	v_mfma_f32_32x32x16_bf16 v[18:33], v[38:41], v[54:57], v[18:33]
	v_and_b32_e32 v38, 64, v112
	v_add_u32_e32 v122, 64, v38
	v_cmp_lt_i32_e32 vcc, v113, v122
	s_waitcnt vmcnt(1) lgkmcnt(1)
	v_mfma_f32_32x32x16_bf16 v[18:33], v[34:37], v[58:61], v[18:33]
	v_cndmask_b32_e32 v34, v112, v113, vcc
	v_lshlrev_b32_e32 v123, 2, v34
	global_load_dwordx4 v[46:49], v[70:71], off offset:128
	global_load_dwordx4 v[42:45], v[70:71], off offset:160
	global_load_dwordx4 v[38:41], v[70:71], off offset:192
	global_load_dwordx4 v[34:37], v[70:71], off offset:224
	s_waitcnt vmcnt(4) lgkmcnt(0)
	v_mfma_f32_32x32x16_bf16 v[18:33], v[66:69], v[50:53], v[18:33]
	s_nop 11
	s_movk_i32 s42, 0x7f
	s_movk_i32 s43, 0xff80
	v_bitop3_b32 v21, v21, s42, 3 bitop3:0x56
	v_bitop3_b32 v32, v32, s42, 26 bitop3:0x56
	v_bitop3_b32 v22, v22, s42, 8 bitop3:0x56
	v_bitop3_b32 v26, v26, s42, 16 bitop3:0x56
	v_bitop3_b32 v31, v31, s42, 25 bitop3:0x56
	v_bitop3_b32 v23, v23, s42, 9 bitop3:0x56
	v_bitop3_b32 v24, v24, s42, 10 bitop3:0x56
	v_bitop3_b32 v27, v27, s42, 17 bitop3:0x56
	v_bitop3_b32 v28, v28, s42, 18 bitop3:0x56
	v_bitop3_b32 v20, v20, s42, 2 bitop3:0x56
	v_bitop3_b32 v33, v33, s42, 27 bitop3:0x56
	v_bitop3_b32 v25, v25, s42, 11 bitop3:0x56
	v_bitop3_b32 v29, v29, s42, 19 bitop3:0x56
	v_bitop3_b32 v19, v19, s42, 1 bitop3:0x56
	v_bitop3_b32 v30, v30, s42, 24 bitop3:0x56
	v_or_b32_e32 v18, 0x7f, v18
	v_max_i32_e32 v66, v21, v32
	v_max_i32_e32 v67, v22, v26
	v_max_i32_e32 v68, v18, v31
	v_max_i32_e32 v69, v23, v24
	v_min_i32_e32 v70, v27, v28
	v_min_i32_e32 v71, v20, v33
	v_min_i32_e32 v72, v25, v29
	v_min_i32_e32 v73, v19, v30
	v_min_i32_e32 v23, v23, v24
	v_min_i32_e32 v18, v18, v31
	v_min_i32_e32 v22, v22, v26
	v_min_i32_e32 v21, v21, v32
	v_max_i32_e32 v19, v19, v30
	v_max_i32_e32 v24, v25, v29
	v_max_i32_e32 v20, v20, v33
	v_max_i32_e32 v25, v27, v28
	v_min_i32_e32 v26, v66, v67
	v_min_i32_e32 v27, v68, v69
	v_max_i32_e32 v28, v70, v71
	v_max_i32_e32 v29, v72, v73
	v_max_i32_e32 v30, v23, v18
	v_max_i32_e32 v31, v22, v21
	v_min_i32_e32 v32, v19, v24
	v_min_i32_e32 v33, v20, v25
	v_min_i32_e32 v18, v23, v18
; #define LAS __attribute__((address_space(3)))
; #define MFMA32(a, b, c) __builtin_amdgcn_mfma_f32_32x32x16_bf16((a), (b), (c), 0, 0, 0)
; #define CE_(a, b) ce_desc(v[a], v[b])
; __device__ __forceinline__ void sort16_desc(int (&v)[16]) {
;     ...
;     CE_(0,13); CE_(1,12); CE_(2,15); CE_(3,14); CE_(4,8); CE_(5,6); CE_(7,11); CE_(9,10);
;     CE_(0,5); CE_(1,7); CE_(2,9); CE_(3,4); CE_(6,13); CE_(8,14); CE_(10,15); CE_(11,12);
;     CE_(0,1); CE_(2,3); CE_(4,5); CE_(6,8); CE_(7,9); CE_(10,11); CE_(12,13); CE_(14,15);
;     CE_(0,2); CE_(1,3); CE_(4,10); CE_(5,11); CE_(6,7); CE_(8,9); CE_(12,14); CE_(13,15);
;     CE_(1,2); CE_(3,12); CE_(4,6); CE_(5,7); CE_(8,10); CE_(9,11); CE_(13,14);
;     CE_(1,4); CE_(2,6); CE_(5,8); CE_(7,10); CE_(9,13); CE_(11,14);
;     CE_(2,4); CE_(3,6); CE_(9,12); CE_(11,13);
;     CE_(3,5); CE_(6,8); CE_(7,9); CE_(10,12);
;     CE_(3,4); CE_(5,6); CE_(7,8); CE_(9,10); CE_(11,12);
;     CE_(6,7); CE_(8,9);
;     ...
; }
; __device__ __forceinline__ void route_task(int task, int tl0, const bf16* QP  , const LAS bf16* KHL, LAS unsigned short* EL, LAS float* GL, int lane) {
;     ...
;         for (int kt = 0; kt < 4; ++kt) {
;             f32x16 X;
; #pragma unroll
;             for (int i = 0; i < 16; ++i) X[i] = 8.f;
;             const LAS bf16* khp = KHL + (half * 128 + 32 * kt + r) * 72 + 8 * hi;
; #pragma unroll
;             for (int ks = 0; ks < 4; ++ks) {
;                 const bf16x8 kh = lds8(khp + 16 * ks);
;                 X = MFMA32(kh, qa[half][ks], X);
;             }
;             int grp[16];
; #pragma unroll
;             for (int i = 0; i < 16; ++i) grp[i] = (int)((__float_as_uint(X[i]) | 127u) - (unsigned)(32 * kt + (i & 3) + 8 * (i >> 2)));
;             sort16_desc(grp);
;             if (kt == 0) {
; #pragma unroll
;                 for (int i = 0; i < 16; ++i) cur[i] = grp[i];
;             } else merge16_desc(cur, grp);
	v_min_i32_e32 v21, v22, v21
	v_min_i32_e32 v22, v70, v71
	v_max_i32_e32 v23, v68, v69
	v_max_i32_e32 v19, v19, v24
	v_max_i32_e32 v20, v20, v25
	v_max_i32_e32 v24, v66, v67
	v_min_i32_e32 v25, v26, v27
	v_max_i32_e32 v67, v30, v31
	v_min_i32_e32 v30, v30, v31
	v_min_i32_e32 v31, v32, v33
	v_max_i32_e32 v26, v26, v27
	v_max_i32_e32 v27, v28, v29
	v_min_i32_e32 v66, v28, v29
	v_max_i32_e32 v68, v32, v33
	v_min_i32_e32 v75, v21, v22
	v_max_i32_e32 v21, v21, v22
	v_min_i32_e32 v22, v23, v19
	v_min_i32_e32 v28, v20, v24
	v_max_i32_e32 v33, v30, v31
	v_min_i32_e32 v69, v26, v27
	v_max_i32_e32 v29, v25, v66
	v_min_i32_e32 v32, v67, v68
	v_min_i32_e32 v77, v25, v66
	v_min_i32_e32 v25, v22, v28
	v_max_i32_e32 v80, v22, v28
	v_min_i32_e32 v22, v33, v69
	v_max_i32_e32 v125, v20, v24
	v_max_i32_e32 v129, v67, v68
	v_max_i32_e32 v24, v33, v69
	ds_read_b128 v[66:69], v95
	v_min_i32_e32 v72, v72, v73
	v_min_i32_e32 v74, v72, v18
	v_max_i32_e32 v18, v72, v18
	v_max_i32_e32 v124, v23, v19
	v_min_i32_e32 v76, v30, v31
	v_max_i32_e32 v78, v74, v75
	v_min_i32_e32 v79, v18, v21
	v_min_i32_e32 v126, v124, v125
	v_max_i32_e32 v128, v26, v27
	v_max_i32_e32 v18, v18, v21
	v_max_i32_e32 v81, v76, v77
	v_max_i32_e32 v82, v78, v79
	v_min_i32_e32 v127, v80, v126
	v_min_i32_e32 v130, v128, v129
	v_min_i32_e32 v21, v29, v32
	v_min_i32_e32 v28, v25, v18
	v_max_i32_e32 v18, v25, v18
	v_max_i32_e32 v30, v81, v82
	v_min_i32_e32 v19, v127, v130
	v_max_i32_e32 v23, v29, v32
	v_max_i32_e32 v25, v21, v22
	v_max_i32_e32 v31, v30, v28
	v_min_i32_e32 v20, v18, v19
	v_min_i32_e32 v26, v23, v24
	v_max_i32_e32 v70, v25, v31
	v_min_i32_e32 v27, v20, v26
	v_min_i32_e32 v131, v70, v27
	v_max_i32_e32 v143, v70, v27
	ds_read_b128 v[70:73], v95 offset:32
	v_min_i32_e32 v132, v25, v31
	v_min_i32_e32 v133, v21, v22
	v_min_i32_e32 v134, v30, v28
	v_max_i32_e32 v138, v18, v19
	v_max_i32_e32 v139, v23, v24
	v_max_i32_e32 v141, v20, v26
	s_waitcnt lgkmcnt(1)
	v_mfma_f32_32x32x16_bf16 v[18:33], v[66:69], v[62:65], v[2:17]
	ds_read_b128 v[66:69], v95 offset:64
	v_max_i32_e32 v135, v133, v134
	v_max_i32_e32 v136, v132, v135
	v_min_i32_e32 v76, v76, v77
	v_min_i32_e32 v77, v78, v79
	v_min_i32_e32 v132, v132, v135
	v_max_i32_e32 v127, v127, v130
	s_waitcnt lgkmcnt(1)
	v_mfma_f32_32x32x16_bf16 v[18:33], v[70:73], v[54:57], v[18:33]
	ds_read_b128 v[70:73], v95 offset:96
	v_max_i32_e32 v80, v80, v126
	v_min_i32_e32 v74, v74, v75
	v_min_i32_e32 v140, v138, v139
	v_max_i32_e32 v78, v76, v77
	v_min_i32_e32 v79, v81, v82
	v_min_i32_e32 v82, v133, v134
	s_waitcnt lgkmcnt(1)
	v_mfma_f32_32x32x16_bf16 v[18:33], v[66:69], v[58:61], v[18:33]
	v_max_i32_e32 v66, v128, v129
	v_max_i32_e32 v134, v138, v139
	v_min_i32_e32 v76, v76, v77
	v_max_i32_e32 v81, v78, v79
	v_min_i32_e32 v78, v78, v79
	v_min_i32_e32 v67, v80, v66
	v_min_i32_e32 v142, v140, v141
	s_waitcnt lgkmcnt(0)
	v_mfma_f32_32x32x16_bf16 v[18:33], v[70:73], v[50:53], v[18:33]
	v_min_i32_e32 v68, v127, v67
	v_min_i32_e32 v137, v131, v136
	v_min_i32_e32 v144, v142, v143
	v_min_i32_e32 v133, v81, v82
	v_min_i32_e32 v69, v134, v68
	s_nop 6
	v_bitop3_b32 v21, v21, s42, 35 bitop3:0x56
	v_bitop3_b32 v32, v32, s42, 58 bitop3:0x56
	v_bitop3_b32 v22, v22, s42, 40 bitop3:0x56
	v_bitop3_b32 v26, v26, s42, 48 bitop3:0x56
	v_bitop3_b32 v18, v18, s42, 32 bitop3:0x56
	v_bitop3_b32 v31, v31, s42, 57 bitop3:0x56
	v_bitop3_b32 v23, v23, s42, 41 bitop3:0x56
	v_bitop3_b32 v24, v24, s42, 42 bitop3:0x56
	v_bitop3_b32 v27, v27, s42, 49 bitop3:0x56
	v_bitop3_b32 v28, v28, s42, 50 bitop3:0x56
	v_bitop3_b32 v20, v20, s42, 34 bitop3:0x56
	v_bitop3_b32 v33, v33, s42, 59 bitop3:0x56
	v_bitop3_b32 v25, v25, s42, 43 bitop3:0x56
	v_bitop3_b32 v29, v29, s42, 51 bitop3:0x56
	v_bitop3_b32 v19, v19, s42, 33 bitop3:0x56
	v_bitop3_b32 v30, v30, s42, 56 bitop3:0x56
	v_max_i32_e32 v70, v21, v32
	v_max_i32_e32 v71, v22, v26
	v_max_i32_e32 v73, v18, v31
	v_max_i32_e32 v75, v23, v24
	v_min_i32_e32 v126, v27, v28
	v_min_i32_e32 v128, v20, v33
	v_min_i32_e32 v130, v25, v29
	v_min_i32_e32 v135, v19, v30
	v_min_i32_e32 v23, v23, v24
	v_min_i32_e32 v18, v18, v31
	v_min_i32_e32 v22, v22, v26
	v_min_i32_e32 v21, v21, v32
	v_max_i32_e32 v19, v19, v30
	v_max_i32_e32 v25, v25, v29
	v_max_i32_e32 v20, v20, v33
	v_max_i32_e32 v27, v27, v28
	v_min_i32_e32 v72, v70, v71
	v_min_i32_e32 v77, v73, v75
	v_max_i32_e32 v129, v126, v128
	v_max_i32_e32 v138, v130, v135
	v_max_i32_e32 v24, v23, v18
	v_max_i32_e32 v26, v22, v21
	v_min_i32_e32 v29, v19, v25
	v_min_i32_e32 v28, v20, v27
	v_min_i32_e32 v130, v130, v135
	v_min_i32_e32 v18, v23, v18
	v_min_i32_e32 v21, v22, v21
	v_min_i32_e32 v22, v126, v128
	v_max_i32_e32 v73, v73, v75
	v_max_i32_e32 v19, v19, v25
	v_max_i32_e32 v20, v20, v27
	v_max_i32_e32 v27, v70, v71
	v_min_i32_e32 v79, v72, v77
	v_min_i32_e32 v139, v129, v138
	v_max_i32_e32 v31, v24, v26
	v_max_i32_e32 v30, v29, v28
	v_min_i32_e32 v24, v24, v26
	v_min_i32_e32 v26, v29, v28
	v_max_i32_e32 v29, v72, v77
	v_max_i32_e32 v72, v129, v138
	v_min_i32_e32 v23, v130, v18
	v_min_i32_e32 v126, v21, v22
	v_max_i32_e32 v18, v130, v18
	v_max_i32_e32 v21, v21, v22
	v_min_i32_e32 v25, v73, v19
	v_min_i32_e32 v70, v20, v27
	v_max_i32_e32 v19, v73, v19
	v_max_i32_e32 v20, v20, v27
	v_min_i32_e32 v32, v31, v30
	v_max_i32_e32 v28, v24, v26
	v_min_i32_e32 v77, v29, v72
	v_min_i32_e32 v24, v24, v26
	v_min_i32_e32 v26, v79, v139
	v_max_i32_e32 v128, v23, v126
	v_min_i32_e32 v22, v18, v21
	v_min_i32_e32 v71, v25, v70
	v_max_i32_e32 v25, v25, v70
	v_min_i32_e32 v27, v19, v20
	v_max_i32_e32 v29, v29, v72
	v_max_i32_e32 v30, v31, v30
	v_max_i32_e32 v145, v79, v139
	v_max_i32_e32 v79, v24, v26
	v_max_i32_e32 v130, v128, v22
; #define LAS __attribute__((address_space(3)))
; #define MFMA32(a, b, c) __builtin_amdgcn_mfma_f32_32x32x16_bf16((a), (b), (c), 0, 0, 0)
; #define CE_(a, b) ce_desc(v[a], v[b])
; __device__ __forceinline__ void sort16_desc(int (&v)[16]) {
;     ...
;     CE_(0,13); CE_(1,12); CE_(2,15); CE_(3,14); CE_(4,8); CE_(5,6); CE_(7,11); CE_(9,10);
;     CE_(0,5); CE_(1,7); CE_(2,9); CE_(3,4); CE_(6,13); CE_(8,14); CE_(10,15); CE_(11,12);
;     CE_(0,1); CE_(2,3); CE_(4,5); CE_(6,8); CE_(7,9); CE_(10,11); CE_(12,13); CE_(14,15);
;     CE_(0,2); CE_(1,3); CE_(4,10); CE_(5,11); CE_(6,7); CE_(8,9); CE_(12,14); CE_(13,15);
;     CE_(1,2); CE_(3,12); CE_(4,6); CE_(5,7); CE_(8,10); CE_(9,11); CE_(13,14);
;     CE_(1,4); CE_(2,6); CE_(5,8); CE_(7,10); CE_(9,13); CE_(11,14);
;     CE_(2,4); CE_(3,6); CE_(9,12); CE_(11,13);
;     CE_(3,5); CE_(6,8); CE_(7,9); CE_(10,12);
;     CE_(3,4); CE_(5,6); CE_(7,8); CE_(9,10); CE_(11,12);
;     CE_(6,7); CE_(8,9);
;     ...
; }
; __device__ __forceinline__ void merge16_desc(int (&a)[16], const int (&b)[16]) {
; #pragma unroll
;     for (int i = 0; i < 16; ++i) a[i] = a[i] > b[15 - i] ? a[i] : b[15 - i];
; #pragma unroll
;     for (int j = 8; j > 0; j >>= 1)
; #pragma unroll
;         for (int i = 0; i < 16; ++i) { const int l = i ^ j; if (l > i) ce_desc(a[i], a[l]); }
; }
; __device__ __forceinline__ void route_task(int task, int tl0, const bf16* QP  , const LAS bf16* KHL, LAS unsigned short* EL, LAS float* GL, int lane) {
;     ...
;         for (int kt = 0; kt < 4; ++kt) {
;             f32x16 X;
; #pragma unroll
;             for (int i = 0; i < 16; ++i) X[i] = 8.f;
;             const LAS bf16* khp = KHL + (half * 128 + 32 * kt + r) * 72 + 8 * hi;
; #pragma unroll
;             for (int ks = 0; ks < 4; ++ks) {
;                 const bf16x8 kh = lds8(khp + 16 * ks);
;                 X = MFMA32(kh, qa[half][ks], X);
;             }
;             int grp[16];
; #pragma unroll
;             for (int i = 0; i < 16; ++i) grp[i] = (int)((__float_as_uint(X[i]) | 127u) - (unsigned)(32 * kt + (i & 3) + 8 * (i >> 2)));
;             sort16_desc(grp);
;             if (kt == 0) {
; #pragma unroll
;                 for (int i = 0; i < 16; ++i) cur[i] = grp[i];
;             } else merge16_desc(cur, grp);
	v_max_i32_e32 v18, v18, v21
	v_min_i32_e32 v70, v25, v27
	v_min_i32_e32 v31, v29, v30
	v_min_i32_e32 v33, v145, v32
	v_min_i32_e32 v129, v28, v77
	v_max_i32_e32 v135, v79, v130
	v_min_i32_e32 v21, v71, v18
	v_max_i32_e32 v18, v71, v18
	v_min_i32_e32 v71, v70, v31
	v_max_i32_e32 v32, v145, v32
	v_max_i32_e32 v28, v28, v77
	v_max_i32_e32 v138, v33, v129
	v_max_i32_e32 v75, v135, v21
	v_min_i32_e32 v72, v18, v71
	v_min_i32_e32 v73, v32, v28
	v_min_i32_e32 v33, v33, v129
	v_min_i32_e32 v21, v135, v21
	v_max_i32_e32 v18, v18, v71
	v_max_i32_e32 v28, v32, v28
	v_min_i32_e32 v24, v24, v26
	v_min_i32_e32 v22, v128, v22
	v_max_i32_e32 v25, v25, v27
	v_max_i32_e32 v27, v29, v30
	v_max_i32_e32 v139, v138, v75
	v_min_i32_e32 v77, v72, v73
	v_min_i32_e32 v75, v138, v75
	v_max_i32_e32 v129, v33, v21
	v_min_i32_e32 v32, v18, v28
	v_max_i32_e32 v71, v72, v73
	v_max_i32_e32 v26, v24, v22
	v_min_i32_e32 v79, v79, v130
	v_max_i32_e32 v18, v18, v28
	v_max_i32_e32 v28, v70, v31
	v_min_i32_e32 v29, v25, v27
	v_min_i32_e32 v145, v139, v77
	v_max_i32_e32 v135, v75, v129
	v_min_i32_e32 v72, v32, v71
	v_max_i32_e32 v73, v139, v77
	v_max_i32_e32 v128, v26, v79
	v_min_i32_e32 v21, v33, v21
	v_min_i32_e32 v30, v28, v29
	v_min_i32_e32 v138, v145, v135
	v_min_i32_e32 v77, v72, v73
	v_min_i32_e32 v33, v128, v21
	v_min_i32_e32 v75, v75, v129
	v_min_i32_e32 v31, v18, v30
	v_min_i32_e32 v26, v26, v79
	v_min_i32_e32 v22, v24, v22
	v_min_i32_e32 v23, v23, v126
	v_max3_i32 v23, v124, v125, v23
	v_max3_i32 v22, v80, v66, v22
	v_max3_i32 v24, v127, v67, v26
	v_max3_i32 v26, v134, v68, v33
	v_max3_i32 v21, v69, v128, v21
	v_max3_i32 v33, v140, v141, v75
	v_max3_i32 v66, v142, v143, v138
	v_max3_i32 v67, v144, v145, v135
	v_max3_i32 v68, v131, v136, v77
	v_max3_i32 v69, v137, v72, v73
	v_max3_i32 v32, v132, v32, v71
	v_max3_i32 v31, v81, v82, v31
	v_max3_i32 v18, v133, v18, v30
	v_max3_i32 v28, v78, v28, v29
	v_max3_i32 v25, v76, v25, v27
	v_max3_i32 v19, v74, v19, v20
	v_max_i32_e32 v20, v23, v68
	v_min_i32_e32 v23, v23, v68
	v_max_i32_e32 v27, v22, v69
	v_min_i32_e32 v22, v22, v69
	v_max_i32_e32 v29, v24, v32
	v_min_i32_e32 v24, v24, v32
	v_max_i32_e32 v30, v26, v31
	v_min_i32_e32 v26, v26, v31
	v_max_i32_e32 v31, v21, v18
	v_min_i32_e32 v18, v21, v18
	v_max_i32_e32 v21, v33, v28
	v_min_i32_e32 v28, v33, v28
	v_max_i32_e32 v32, v66, v25
	v_min_i32_e32 v25, v66, v25
	v_max_i32_e32 v33, v67, v19
	v_min_i32_e32 v19, v67, v19
	ds_read_b128 v[66:69], v94 offset:9216
	v_max_i32_e32 v70, v20, v31
	v_min_i32_e32 v74, v20, v31
	v_max_i32_e32 v20, v27, v21
	v_min_i32_e32 v75, v27, v21
	v_max_i32_e32 v21, v29, v32
	v_max_i32_e32 v27, v30, v33
	v_max_i32_e32 v127, v70, v21
	v_min_i32_e32 v128, v70, v21
	ds_read_b128 v[70:73], v94 offset:9248
	v_min_i32_e32 v76, v29, v32
	v_min_i32_e32 v77, v30, v33
	v_max_i32_e32 v78, v23, v18
	v_min_i32_e32 v79, v23, v18
	v_max_i32_e32 v80, v22, v28
	v_min_i32_e32 v81, v22, v28
	v_max_i32_e32 v82, v24, v25
	v_min_i32_e32 v124, v24, v25
	v_max_i32_e32 v125, v26, v19
	v_min_i32_e32 v126, v26, v19
	v_max_i32_e32 v129, v20, v27
	v_min_i32_e32 v130, v20, v27
	s_waitcnt lgkmcnt(1)
	v_mfma_f32_32x32x16_bf16 v[18:33], v[66:69], v[62:65], v[2:17]
	ds_read_b128 v[66:69], v94 offset:9280
	v_max_i32_e32 v131, v74, v76
	v_min_i32_e32 v74, v74, v76
	v_max_i32_e32 v76, v75, v77
	v_min_i32_e32 v75, v75, v77
	v_max_i32_e32 v77, v78, v82
	v_min_i32_e32 v78, v78, v82
	s_waitcnt lgkmcnt(1)
	v_mfma_f32_32x32x16_bf16 v[18:33], v[70:73], v[54:57], v[18:33]
	ds_read_b128 v[70:73], v94 offset:9312
	v_max_i32_e32 v82, v80, v125
	v_min_i32_e32 v80, v80, v125
	v_max_i32_e32 v125, v79, v124
	v_min_i32_e32 v79, v79, v124
	v_max_i32_e32 v124, v81, v126
	v_min_i32_e32 v81, v81, v126
	s_waitcnt lgkmcnt(1)
	v_mfma_f32_32x32x16_bf16 v[18:33], v[66:69], v[58:61], v[18:33]
	v_min_i32_e32 v126, v127, v129
	v_min_i32_e32 v66, v128, v130
	v_min_i32_e32 v67, v131, v76
	v_min_i32_e32 v69, v77, v82
	v_min_i32_e32 v132, v78, v80
	v_min_i32_e32 v133, v125, v124
	v_min_i32_e32 v68, v74, v75
	s_waitcnt lgkmcnt(0)
	v_mfma_f32_32x32x16_bf16 v[18:33], v[70:73], v[50:53], v[18:33]
	v_min_i32_e32 v134, v79, v81
	s_nop 10
	v_and_or_b32 v21, v21, s43, 60
	v_and_or_b32 v32, v32, s43, 37
	v_and_or_b32 v22, v22, s43, 55
	v_and_or_b32 v26, v26, s43, 47
	v_bitop3_b32 v18, v18, s42, 64 bitop3:0x56
	v_and_or_b32 v31, v31, s43, 38
	v_and_or_b32 v23, v23, s43, 54
	v_and_or_b32 v24, v24, s43, 53
	v_and_or_b32 v27, v27, s43, 46
	v_and_or_b32 v28, v28, s43, 45
	v_and_or_b32 v20, v20, s43, 61
	v_and_or_b32 v33, v33, s43, 36
	v_and_or_b32 v25, v25, s43, 52
	v_and_or_b32 v29, v29, s43, 44
	v_and_or_b32 v19, v19, s43, 62
	v_and_or_b32 v30, v30, s43, 39
	v_max_i32_e32 v70, v21, v32
	v_max_i32_e32 v71, v22, v26
	v_max_i32_e32 v73, v18, v31
	v_max_i32_e32 v135, v23, v24
	v_min_i32_e32 v138, v27, v28
	v_min_i32_e32 v139, v20, v33
	v_min_i32_e32 v141, v25, v29
	v_min_i32_e32 v142, v19, v30
	v_min_i32_e32 v23, v23, v24
	v_min_i32_e32 v18, v18, v31
	v_min_i32_e32 v22, v22, v26
	v_min_i32_e32 v21, v21, v32
	v_max_i32_e32 v19, v19, v30
	v_max_i32_e32 v25, v25, v29
	v_max_i32_e32 v20, v20, v33
	v_max_i32_e32 v27, v27, v28
	v_min_i32_e32 v72, v70, v71
	v_min_i32_e32 v136, v73, v135
	v_max_i32_e32 v140, v138, v139
	v_max_i32_e32 v143, v141, v142
	v_max_i32_e32 v24, v23, v18
	v_max_i32_e32 v26, v22, v21
	v_min_i32_e32 v29, v19, v25
	v_min_i32_e32 v28, v20, v27
	v_min_i32_e32 v141, v141, v142
	v_min_i32_e32 v18, v23, v18
	v_min_i32_e32 v21, v22, v21
	v_min_i32_e32 v22, v138, v139
	v_max_i32_e32 v73, v73, v135
	v_max_i32_e32 v19, v19, v25
	v_max_i32_e32 v20, v20, v27
	v_max_i32_e32 v27, v70, v71
	v_min_i32_e32 v137, v72, v136
; #define LAS __attribute__((address_space(3)))
; #define MFMA32(a, b, c) __builtin_amdgcn_mfma_f32_32x32x16_bf16((a), (b), (c), 0, 0, 0)
; __device__ __forceinline__ void merge16_desc(int (&a)[16], const int (&b)[16]) {
; #pragma unroll
;     for (int i = 0; i < 16; ++i) a[i] = a[i] > b[15 - i] ? a[i] : b[15 - i];
; #pragma unroll
;     for (int j = 8; j > 0; j >>= 1)
; #pragma unroll
;         for (int i = 0; i < 16; ++i) { const int l = i ^ j; if (l > i) ce_desc(a[i], a[l]); }
; }
; __device__ __forceinline__ void route_task(int task, int tl0, const bf16* QP  , const LAS bf16* KHL, LAS unsigned short* EL, LAS float* GL, int lane) {
;     ...
;         for (int kt = 0; kt < 4; ++kt) {
;             f32x16 X;
; #pragma unroll
;             for (int i = 0; i < 16; ++i) X[i] = 8.f;
;             const LAS bf16* khp = KHL + (half * 128 + 32 * kt + r) * 72 + 8 * hi;
; #pragma unroll
;             for (int ks = 0; ks < 4; ++ks) {
;                 const bf16x8 kh = lds8(khp + 16 * ks);
;                 X = MFMA32(kh, qa[half][ks], X);
;             }
;             int grp[16];
; #pragma unroll
;             for (int i = 0; i < 16; ++i) grp[i] = (int)((__float_as_uint(X[i]) | 127u) - (unsigned)(32 * kt + (i & 3) + 8 * (i >> 2)));
;             sort16_desc(grp);
;             if (kt == 0) {
; #pragma unroll
;                 for (int i = 0; i < 16; ++i) cur[i] = grp[i];
;             } else merge16_desc(cur, grp);
	v_min_i32_e32 v144, v140, v143
	v_max_i32_e32 v31, v24, v26
	v_max_i32_e32 v30, v29, v28
	v_min_i32_e32 v24, v24, v26
	v_min_i32_e32 v26, v29, v28
	v_max_i32_e32 v29, v72, v136
	v_max_i32_e32 v72, v140, v143
	v_min_i32_e32 v23, v141, v18
	v_min_i32_e32 v138, v21, v22
	v_max_i32_e32 v18, v141, v18
	v_max_i32_e32 v21, v21, v22
	v_min_i32_e32 v25, v73, v19
	v_min_i32_e32 v70, v20, v27
	v_max_i32_e32 v19, v73, v19
	v_max_i32_e32 v20, v20, v27
	v_min_i32_e32 v32, v31, v30
	v_max_i32_e32 v28, v24, v26
	v_min_i32_e32 v136, v29, v72
	v_min_i32_e32 v24, v24, v26
	v_min_i32_e32 v26, v137, v144
	v_max_i32_e32 v139, v23, v138
	v_min_i32_e32 v22, v18, v21
	v_min_i32_e32 v71, v25, v70
	v_max_i32_e32 v25, v25, v70
	v_min_i32_e32 v27, v19, v20
	v_max_i32_e32 v29, v29, v72
	v_max_i32_e32 v30, v31, v30
	v_max_i32_e32 v145, v137, v144
	v_max_i32_e32 v137, v24, v26
	v_max_i32_e32 v141, v139, v22
	v_max_i32_e32 v18, v18, v21
	v_min_i32_e32 v70, v25, v27
	v_min_i32_e32 v31, v29, v30
	v_min_i32_e32 v33, v145, v32
	v_min_i32_e32 v140, v28, v136
	v_max_i32_e32 v142, v137, v141
	v_min_i32_e32 v21, v71, v18
	v_max_i32_e32 v18, v71, v18
	v_min_i32_e32 v71, v70, v31
	v_max_i32_e32 v32, v145, v32
	v_max_i32_e32 v28, v28, v136
	v_max_i32_e32 v143, v33, v140
	v_max_i32_e32 v135, v142, v21
	v_min_i32_e32 v72, v18, v71
	v_min_i32_e32 v73, v32, v28
	v_min_i32_e32 v33, v33, v140
	v_min_i32_e32 v21, v142, v21
	v_max_i32_e32 v18, v18, v71
	v_max_i32_e32 v28, v32, v28
	v_min_i32_e32 v24, v24, v26
	v_min_i32_e32 v22, v139, v22
	v_max_i32_e32 v25, v25, v27
	v_max_i32_e32 v27, v29, v30
	v_max_i32_e32 v144, v143, v135
	v_min_i32_e32 v136, v72, v73
	v_min_i32_e32 v135, v143, v135
	v_max_i32_e32 v140, v33, v21
	v_min_i32_e32 v32, v18, v28
	v_max_i32_e32 v71, v72, v73
	v_max_i32_e32 v26, v24, v22
	v_min_i32_e32 v137, v137, v141
	v_max_i32_e32 v18, v18, v28
	v_max_i32_e32 v28, v70, v31
	v_min_i32_e32 v29, v25, v27
	v_min_i32_e32 v145, v144, v136
	v_max_i32_e32 v142, v135, v140
	v_min_i32_e32 v72, v32, v71
	v_max_i32_e32 v73, v144, v136
	v_max_i32_e32 v139, v26, v137
	v_min_i32_e32 v21, v33, v21
	v_min_i32_e32 v30, v28, v29
	v_min_i32_e32 v143, v145, v142
	v_min_i32_e32 v136, v72, v73
	v_min_i32_e32 v33, v139, v21
	v_max_i32_e32 v21, v139, v21
	v_min_i32_e32 v135, v135, v140
	v_max_i32_e32 v32, v32, v71
	v_min_i32_e32 v31, v18, v30
	v_max_i32_e32 v18, v18, v30
	v_min_i32_e32 v26, v26, v137
	v_min_i32_e32 v22, v24, v22
	v_max_i32_e32 v24, v25, v27
	v_min_i32_e32 v23, v23, v138
	v_max3_i32 v23, v127, v129, v23
	v_max_i32_e32 v22, v126, v22
	v_max3_i32 v25, v128, v130, v26
	v_max_i32_e32 v26, v66, v33
	v_max3_i32 v21, v131, v76, v21
	v_max_i32_e32 v27, v67, v135
	v_max3_i32 v30, v74, v75, v143
	v_max3_i32 v66, v77, v82, v136
	v_max3_i32 v67, v69, v72, v73
	v_max3_i32 v32, v78, v80, v32
	v_max_i32_e32 v31, v132, v31
	v_max3_i32 v18, v125, v124, v18
	v_max3_i32 v28, v133, v28, v29
	v_max3_i32 v24, v79, v81, v24
	v_max3_i32 v33, v68, v145, v142
	v_max3_i32 v19, v134, v19, v20
	v_max_i32_e32 v20, v23, v66
	v_min_i32_e32 v23, v23, v66
	v_max_i32_e32 v29, v22, v67
	v_max_i32_e32 v66, v25, v32
	v_min_i32_e32 v25, v25, v32
	v_max_i32_e32 v32, v26, v31
	v_min_i32_e32 v26, v26, v31
	v_max_i32_e32 v31, v21, v18
	v_min_i32_e32 v18, v21, v18
	v_max_i32_e32 v21, v27, v28
	v_min_i32_e32 v27, v27, v28
	v_max_i32_e32 v28, v30, v24
	v_min_i32_e32 v22, v22, v67
	v_min_i32_e32 v24, v30, v24
	v_max_i32_e32 v30, v33, v19
	v_min_i32_e32 v19, v33, v19
	v_max_i32_e32 v33, v20, v31
	v_min_i32_e32 v74, v20, v31
	v_max_i32_e32 v20, v29, v21
	v_min_i32_e32 v75, v29, v21
	v_max_i32_e32 v21, v66, v28
	v_min_i32_e32 v76, v66, v28
	ds_read_b128 v[66:69], v96
	ds_read_b128 v[70:73], v96 offset:32
	v_max_i32_e32 v28, v32, v30
	v_min_i32_e32 v77, v32, v30
	v_max_i32_e32 v78, v23, v18
	v_min_i32_e32 v79, v23, v18
	v_max_i32_e32 v80, v22, v27
	v_min_i32_e32 v81, v22, v27
	v_max_i32_e32 v82, v25, v24
	v_min_i32_e32 v124, v25, v24
	v_max_i32_e32 v125, v26, v19
	v_min_i32_e32 v126, v26, v19
	v_max_i32_e32 v127, v33, v21
	v_min_i32_e32 v128, v33, v21
	v_max_i32_e32 v129, v20, v28
	v_min_i32_e32 v130, v20, v28
	s_waitcnt lgkmcnt(1)
	v_mfma_f32_32x32x16_bf16 v[18:33], v[66:69], v[62:65], v[2:17]
	ds_read_b128 v[62:65], v96 offset:64
	v_max_i32_e32 v67, v75, v77
	v_min_i32_e32 v68, v75, v77
	v_max_i32_e32 v75, v80, v125
	v_max_i32_e32 v131, v74, v76
	v_min_i32_e32 v66, v74, v76
	v_max_i32_e32 v69, v78, v82
	s_waitcnt lgkmcnt(1)
	v_mfma_f32_32x32x16_bf16 v[18:33], v[70:73], v[54:57], v[18:33]
	ds_read_b128 v[54:57], v96 offset:96
	v_min_i32_e32 v70, v80, v125
	v_max_i32_e32 v71, v79, v124
	v_min_i32_e32 v72, v79, v124
	v_min_i32_e32 v74, v78, v82
	v_max_i32_e32 v73, v81, v126
	v_min_i32_e32 v76, v81, v126
	s_waitcnt lgkmcnt(1)
	v_mfma_f32_32x32x16_bf16 v[18:33], v[62:65], v[58:61], v[18:33]
	v_min_i32_e32 v77, v127, v129
	v_min_i32_e32 v58, v128, v130
	v_min_i32_e32 v59, v131, v67
	v_min_i32_e32 v60, v66, v68
	v_min_i32_e32 v61, v69, v75
	v_min_i32_e32 v62, v74, v70
	v_min_i32_e32 v63, v71, v73
	s_waitcnt lgkmcnt(0)
; #define LAS __attribute__((address_space(3)))
; #define MFMA32(a, b, c) __builtin_amdgcn_mfma_f32_32x32x16_bf16((a), (b), (c), 0, 0, 0)
; #define CE_(a, b) ce_desc(v[a], v[b])
; __device__ __forceinline__ void sort16_desc(int (&v)[16]) {
;     ...
;     CE_(0,13); CE_(1,12); CE_(2,15); CE_(3,14); CE_(4,8); CE_(5,6); CE_(7,11); CE_(9,10);
;     CE_(0,5); CE_(1,7); CE_(2,9); CE_(3,4); CE_(6,13); CE_(8,14); CE_(10,15); CE_(11,12);
;     CE_(0,1); CE_(2,3); CE_(4,5); CE_(6,8); CE_(7,9); CE_(10,11); CE_(12,13); CE_(14,15);
;     CE_(0,2); CE_(1,3); CE_(4,10); CE_(5,11); CE_(6,7); CE_(8,9); CE_(12,14); CE_(13,15);
;     CE_(1,2); CE_(3,12); CE_(4,6); CE_(5,7); CE_(8,10); CE_(9,11); CE_(13,14);
;     CE_(1,4); CE_(2,6); CE_(5,8); CE_(7,10); CE_(9,13); CE_(11,14);
;     CE_(2,4); CE_(3,6); CE_(9,12); CE_(11,13);
;     CE_(3,5); CE_(6,8); CE_(7,9); CE_(10,12);
;     CE_(3,4); CE_(5,6); CE_(7,8); CE_(9,10); CE_(11,12);
;     CE_(6,7); CE_(8,9);
;     ...
; }
; __device__ __forceinline__ void merge16_desc(int (&a)[16], const int (&b)[16]) {
; #pragma unroll
;     for (int i = 0; i < 16; ++i) a[i] = a[i] > b[15 - i] ? a[i] : b[15 - i];
; #pragma unroll
;     for (int j = 8; j > 0; j >>= 1)
; #pragma unroll
;         for (int i = 0; i < 16; ++i) { const int l = i ^ j; if (l > i) ce_desc(a[i], a[l]); }
; }
; __device__ __forceinline__ void route_task(int task, int tl0, const bf16* QP  , const LAS bf16* KHL, LAS unsigned short* EL, LAS float* GL, int lane) {
;     ...
;         for (int kt = 0; kt < 4; ++kt) {
;             f32x16 X;
; #pragma unroll
;             for (int i = 0; i < 16; ++i) X[i] = 8.f;
;             const LAS bf16* khp = KHL + (half * 128 + 32 * kt + r) * 72 + 8 * hi;
; #pragma unroll
;             for (int ks = 0; ks < 4; ++ks) {
;                 const bf16x8 kh = lds8(khp + 16 * ks);
;                 X = MFMA32(kh, qa[half][ks], X);
;             }
;             int grp[16];
; #pragma unroll
;             for (int i = 0; i < 16; ++i) grp[i] = (int)((__float_as_uint(X[i]) | 127u) - (unsigned)(32 * kt + (i & 3) + 8 * (i >> 2)));
;             sort16_desc(grp);
;             if (kt == 0) {
; #pragma unroll
;                 for (int i = 0; i < 16; ++i) cur[i] = grp[i];
;             } else merge16_desc(cur, grp);
	v_mfma_f32_32x32x16_bf16 v[18:33], v[54:57], v[50:53], v[18:33]
	v_min_i32_e32 v64, v72, v76
	s_nop 10
	v_and_or_b32 v25, v25, s43, 20
	v_and_or_b32 v29, v29, s43, 12
	v_and_or_b32 v19, v19, s43, 30
	v_and_or_b32 v30, v30, s43, 7
	v_and_or_b32 v23, v23, s43, 22
	v_and_or_b32 v24, v24, s43, 21
	v_and_or_b32 v18, v18, s43, 31
	v_and_or_b32 v31, v31, s43, 6
	v_and_or_b32 v22, v22, s43, 23
	v_and_or_b32 v26, v26, s43, 15
	v_and_or_b32 v21, v21, s43, 28
	v_and_or_b32 v32, v32, s43, 5
	v_and_or_b32 v27, v27, s43, 14
	v_and_or_b32 v28, v28, s43, 13
	v_and_or_b32 v20, v20, s43, 29
	v_and_or_b32 v33, v33, s43, 4
	v_min_i32_e32 v50, v25, v29
	v_min_i32_e32 v51, v19, v30
	v_min_i32_e32 v53, v23, v24
	v_min_i32_e32 v54, v18, v31
	v_min_i32_e32 v57, v22, v26
	v_min_i32_e32 v65, v21, v32
	v_min_i32_e32 v79, v27, v28
	v_min_i32_e32 v80, v20, v33
	v_max_i32_e32 v18, v18, v31
	v_max_i32_e32 v23, v23, v24
	v_max_i32_e32 v19, v19, v30
	v_max_i32_e32 v25, v25, v29
	v_max_i32_e32 v20, v20, v33
	v_max_i32_e32 v27, v27, v28
	v_max_i32_e32 v21, v21, v32
	v_max_i32_e32 v22, v22, v26
	v_max_i32_e32 v24, v18, v23
	v_max_i32_e32 v29, v19, v25
	v_max_i32_e32 v28, v20, v27
	v_max_i32_e32 v26, v21, v22
	v_min_i32_e32 v30, v24, v29
	v_min_i32_e32 v31, v28, v26
	v_min_i32_e32 v55, v53, v54
	v_min_i32_e32 v32, v30, v31
	v_max_i32_e32 v30, v30, v31
	v_min_i32_e32 v21, v21, v22
	v_min_i32_e32 v18, v18, v23
	v_max_i32_e32 v23, v79, v80
	v_max_i32_e32 v31, v50, v51
	v_max_i32_e32 v53, v53, v54
	v_max_i32_e32 v54, v57, v65
	v_min_i32_e32 v19, v19, v25
	v_min_i32_e32 v20, v20, v27
	v_min_i32_e32 v52, v50, v51
	v_min_i32_e32 v78, v57, v65
	v_min_i32_e32 v81, v79, v80
	v_max_i32_e32 v22, v21, v18
	v_max_i32_e32 v57, v53, v54
	v_max_i32_e32 v25, v19, v20
	v_min_i32_e32 v18, v21, v18
	v_min_i32_e32 v21, v23, v31
	v_min_i32_e32 v56, v52, v55
	v_min_i32_e32 v82, v78, v81
	v_max_i32_e32 v33, v52, v55
	v_max_i32_e32 v52, v78, v81
	v_max_i32_e32 v24, v24, v29
	v_max_i32_e32 v26, v28, v26
	v_max_i32_e32 v50, v23, v31
	v_max_i32_e32 v27, v57, v25
	v_max_i32_e32 v23, v18, v21
	v_min_i32_e32 v25, v57, v25
	v_min_i32_e32 v53, v53, v54
	v_min_i32_e32 v19, v19, v20
	v_max_i32_e32 v55, v33, v52
	v_min_i32_e32 v28, v24, v26
	v_max_i32_e32 v51, v22, v50
	v_max_i32_e32 v31, v23, v25
	v_max_i32_e32 v20, v53, v19
	v_min_i32_e32 v23, v23, v25
	v_min_i32_e32 v19, v53, v19
	v_min_i32_e32 v18, v18, v21
	v_max_i32_e32 v25, v56, v82
	v_min_i32_e32 v33, v33, v52
	v_min_i32_e32 v29, v30, v28
	v_min_i32_e32 v65, v51, v27
	v_min_i32_e32 v22, v22, v50
	v_max_i32_e32 v21, v19, v18
	v_max_i32_e32 v52, v25, v33
	v_max_i32_e32 v78, v32, v55
	v_min_i32_e32 v79, v29, v65
	v_max_i32_e32 v50, v20, v22
	v_min_i32_e32 v20, v20, v22
	v_max_i32_e32 v53, v21, v52
	v_min_i32_e32 v32, v32, v55
	v_max_i32_e32 v80, v78, v79
	v_max_i32_e32 v54, v31, v50
	v_min_i32_e32 v78, v78, v79
	v_min_i32_e32 v31, v31, v50
	v_max_i32_e32 v22, v23, v20
	v_max_i32_e32 v55, v53, v32
	v_min_i32_e32 v18, v19, v18
	v_min_i32_e32 v19, v25, v33
	v_min_i32_e32 v20, v23, v20
	v_min_i32_e32 v23, v53, v32
	v_max_i32_e32 v28, v30, v28
	v_max_i32_e32 v27, v51, v27
	v_min_i32_e32 v124, v56, v82
	v_min_i32_e32 v57, v80, v54
	v_max_i32_e32 v50, v78, v31
	v_max_i32_e32 v56, v22, v55
	v_min_i32_e32 v31, v78, v31
	v_max_i32_e32 v25, v18, v19
	v_min_i32_e32 v21, v21, v52
	v_min_i32_e32 v32, v20, v23
	v_max_i32_e32 v29, v29, v65
	v_min_i32_e32 v30, v28, v27
	v_min_i32_e32 v22, v22, v55
	v_max_i32_e32 v20, v20, v23
	v_min_i32_e32 v79, v57, v50
	v_max_i32_e32 v78, v56, v31
	v_max_i32_e32 v33, v25, v21
	v_max_i32_e32 v53, v80, v54
	v_min_i32_e32 v51, v29, v30
	v_min_i32_e32 v31, v56, v31
	v_max_i32_e32 v23, v22, v20
	v_min_i32_e32 v81, v79, v78
	v_max_i32_e32 v52, v33, v32
	v_max_i32_e32 v54, v53, v51
	v_min_i32_e32 v21, v25, v21
	v_max_i32_e32 v25, v57, v50
	v_min_i32_e32 v55, v31, v23
	v_max_i32_e32 v27, v28, v27
	v_min_i32_e32 v18, v18, v19
	v_min_i32_e32 v20, v22, v20
	v_min_i32_e32 v32, v33, v32
	v_min_i32_e32 v33, v53, v51
	v_max3_i32 v124, v127, v129, v124
	v_max3_i32 v69, v69, v75, v81
	v_max3_i32 v52, v131, v67, v52
	v_max3_i32 v54, v71, v73, v54
	v_max3_i32 v21, v128, v130, v21
	v_max3_i32 v25, v74, v70, v25
	v_max3_i32 v55, v66, v68, v55
	v_max3_i32 v27, v72, v76, v27
	v_max_i32_e32 v18, v77, v18
	v_max3_i32 v19, v61, v79, v78
	v_max_i32_e32 v20, v59, v20
	v_max3_i32 v22, v63, v29, v30
	v_max_i32_e32 v32, v58, v32
	v_max_i32_e32 v33, v62, v33
	v_max3_i32 v23, v60, v31, v23
	v_max3_i32 v24, v64, v24, v26
	v_min_i32_e32 v65, v52, v54
	v_min_i32_e32 v50, v21, v25
	v_min_i32_e32 v61, v18, v19
	v_min_i32_e32 v29, v20, v22
	v_min_i32_e32 v26, v23, v24
	v_max_i32_e32 v59, v124, v69
	v_max_i32_e32 v52, v52, v54
	v_max_i32_e32 v21, v21, v25
	v_max_i32_e32 v25, v55, v27
	v_max_i32_e32 v18, v18, v19
	v_max_i32_e32 v19, v20, v22
	v_max_i32_e32 v22, v32, v33
	v_max_i32_e32 v23, v23, v24
	v_min_i32_e32 v28, v55, v27
	v_max_i32_e32 v54, v59, v52
	v_max_i32_e32 v27, v21, v25
	v_max_i32_e32 v20, v18, v19
	v_max_i32_e32 v24, v22, v23
	v_min_i32_e32 v51, v32, v33
	v_max_i32_e32 v55, v54, v27
	v_max_i32_e32 v32, v20, v24
	v_min_i32_e32 v27, v54, v27
	v_min_i32_e32 v20, v20, v24
	v_max_i32_e32 v24, v27, v20
	v_min_i32_e32 v20, v27, v20
	v_min_i32_e32 v27, v59, v52
	v_min_i32_e32 v21, v21, v25
	v_min_i32_e32 v18, v18, v19
	v_min_i32_e32 v19, v22, v23
	v_min_i32_e32 v75, v124, v69
	v_max_i32_e32 v25, v27, v21
	v_max_i32_e32 v22, v18, v19
	v_min_i32_e32 v21, v27, v21
	v_min_i32_e32 v18, v18, v19
	v_min_i32_e32 v56, v50, v28
	v_min_i32_e32 v31, v51, v26
	v_max_i32_e32 v23, v25, v22
	v_min_i32_e32 v22, v25, v22
	v_max_i32_e32 v19, v21, v18
	v_min_i32_e32 v18, v21, v18
; #define LAS __attribute__((address_space(3)))
; #define MFMA32(a, b, c) __builtin_amdgcn_mfma_f32_32x32x16_bf16((a), (b), (c), 0, 0, 0)
; __device__ __forceinline__ void route_task(int task, int tl0, const bf16* QP  , const LAS bf16* KHL, LAS unsigned short* EL, LAS float* GL, int lane) {
;     ...
;         for (int kt = 0; kt < 4; ++kt) {
;             f32x16 X;
; #pragma unroll
;             for (int i = 0; i < 16; ++i) X[i] = 8.f;
;             const LAS bf16* khp = KHL + (half * 128 + 32 * kt + r) * 72 + 8 * hi;
; #pragma unroll
;             for (int ks = 0; ks < 4; ++ks) {
;                 const bf16x8 kh = lds8(khp + 16 * ks);
;                 X = MFMA32(kh, qa[half][ks], X);
;     ...
;         { const unsigned h4 = 4u * (unsigned)hi;
; #pragma unroll
;           for (int i = 0; i < 16; ++i) cur[i] -= (int)h4; }
;         int oth[16];
; #pragma unroll
;         for (int i = 0; i < 16; ++i) oth[i] = __shfl_xor(cur[i], 32);
;         merge16_desc(cur, oth);
; #pragma unroll
;         for (int i = 0; i < 16; ++i) top[half][i] = cur[i];
	v_max_i32_e32 v21, v75, v65
	v_max_i32_e32 v25, v50, v28
	v_max_i32_e32 v28, v61, v29
	v_max_i32_e32 v26, v51, v26
	v_min_i32_e32 v67, v75, v65
	v_min_i32_e32 v30, v61, v29
	v_max_i32_e32 v27, v21, v25
	v_min_i32_e32 v21, v21, v25
	v_min_i32_e32 v25, v28, v26
	v_min_i32_e32 v57, v67, v56
	v_min_i32_e32 v53, v30, v31
	v_max_i32_e32 v29, v28, v26
	v_max_i32_e32 v26, v21, v25
	v_min_i32_e32 v21, v21, v25
	v_max_i32_e32 v25, v67, v56
	v_max_i32_e32 v28, v30, v31
	v_min_i32_e32 v58, v57, v53
	v_max_i32_e32 v33, v55, v32
	v_min_i32_e32 v32, v55, v32
	v_max_i32_e32 v50, v27, v29
	v_min_i32_e32 v27, v27, v29
	v_max_i32_e32 v29, v25, v28
	v_min_i32_e32 v25, v25, v28
	v_max_i32_e32 v28, v57, v53
	v_sub_u32_e32 v30, v33, v87
	v_sub_u32_e32 v31, v32, v87
	v_sub_u32_e32 v24, v24, v87
	v_sub_u32_e32 v20, v20, v87
	v_sub_u32_e32 v23, v23, v87
	v_sub_u32_e32 v22, v22, v87
	v_sub_u32_e32 v19, v19, v87
	v_sub_u32_e32 v18, v18, v87
	v_sub_u32_e32 v32, v50, v87
	v_sub_u32_e32 v27, v27, v87
	v_sub_u32_e32 v26, v26, v87
	v_sub_u32_e32 v21, v21, v87
	v_sub_u32_e32 v29, v29, v87
	v_sub_u32_e32 v25, v25, v87
	v_sub_u32_e32 v28, v28, v87
	v_sub_u32_e32 v33, v58, v87
	ds_bpermute_b32 v50, v123, v30
	ds_bpermute_b32 v51, v123, v31
	ds_bpermute_b32 v52, v123, v24
	ds_bpermute_b32 v53, v123, v20
	ds_bpermute_b32 v54, v123, v23
	ds_bpermute_b32 v55, v123, v22
	ds_bpermute_b32 v56, v123, v19
	ds_bpermute_b32 v57, v123, v18
	ds_bpermute_b32 v58, v123, v32
	ds_bpermute_b32 v59, v123, v27
	ds_bpermute_b32 v60, v123, v26
	ds_bpermute_b32 v61, v123, v33
	ds_bpermute_b32 v62, v123, v28
	ds_bpermute_b32 v63, v123, v25
	ds_bpermute_b32 v64, v123, v29
	ds_bpermute_b32 v65, v123, v21
	s_waitcnt lgkmcnt(4)
	v_max_i32_e32 v30, v30, v61
	s_waitcnt lgkmcnt(3)
	v_max_i32_e32 v31, v31, v62
	s_waitcnt lgkmcnt(2)
	v_max_i32_e32 v24, v24, v63
	s_waitcnt lgkmcnt(1)
	v_max_i32_e32 v20, v20, v64
	s_waitcnt lgkmcnt(0)
	v_max_i32_e32 v23, v23, v65
	v_max_i32_e32 v22, v22, v60
	v_max_i32_e32 v19, v19, v59
	v_max_i32_e32 v18, v18, v58
	v_max_i32_e32 v32, v32, v57
	v_max_i32_e32 v27, v27, v56
	v_max_i32_e32 v26, v26, v55
	v_max_i32_e32 v21, v21, v54
	v_max_i32_e32 v29, v29, v53
	v_max_i32_e32 v25, v25, v52
	v_max_i32_e32 v28, v28, v51
	v_max_i32_e32 v33, v33, v50
	v_max_i32_e32 v50, v30, v32
	v_min_i32_e32 v30, v30, v32
	v_max_i32_e32 v32, v31, v27
	v_min_i32_e32 v27, v31, v27
	v_max_i32_e32 v31, v24, v26
	v_min_i32_e32 v24, v24, v26
	v_max_i32_e32 v26, v20, v21
	v_min_i32_e32 v20, v20, v21
	v_max_i32_e32 v21, v23, v29
	v_min_i32_e32 v23, v23, v29
	v_max_i32_e32 v29, v22, v25
	v_min_i32_e32 v22, v22, v25
	v_max_i32_e32 v25, v19, v28
	v_min_i32_e32 v19, v19, v28
	v_max_i32_e32 v28, v18, v33
	v_min_i32_e32 v18, v18, v33
	v_max_i32_e32 v33, v50, v21
	v_min_i32_e32 v21, v50, v21
	v_max_i32_e32 v50, v32, v29
	v_min_i32_e32 v29, v32, v29
	v_max_i32_e32 v32, v31, v25
	v_min_i32_e32 v25, v31, v25
	v_max_i32_e32 v31, v26, v28
	v_max_i32_e32 v64, v50, v31
	v_min_i32_e32 v67, v50, v31
	ds_read_b128 v[50:53], v94 offset:18432
	ds_read_b128 v[54:57], v94 offset:18464
	v_min_i32_e32 v26, v26, v28
	v_max_i32_e32 v28, v30, v23
	v_min_i32_e32 v58, v30, v23
	v_max_i32_e32 v23, v27, v22
	v_min_i32_e32 v59, v27, v22
	v_max_i32_e32 v22, v24, v19
	v_min_i32_e32 v60, v24, v19
	v_max_i32_e32 v19, v20, v18
	v_min_i32_e32 v61, v20, v18
	v_max_i32_e32 v62, v33, v32
	v_min_i32_e32 v66, v33, v32
	v_max_i32_e32 v68, v21, v25
	v_min_i32_e32 v69, v21, v25
	v_max_i32_e32 v70, v29, v26
	v_min_i32_e32 v71, v29, v26
	v_max_i32_e32 v72, v28, v22
	v_min_i32_e32 v73, v28, v22
	v_max_i32_e32 v74, v23, v19
	v_min_i32_e32 v75, v23, v19
	s_waitcnt vmcnt(3) lgkmcnt(1)
	v_mfma_f32_32x32x16_bf16 v[18:33], v[50:53], v[46:49], v[2:17]
	ds_read_b128 v[50:53], v94 offset:18496
	v_max_i32_e32 v76, v58, v60
	v_min_i32_e32 v77, v58, v60
	v_max_i32_e32 v78, v59, v61
	v_min_i32_e32 v79, v59, v61
	v_max_i32_e32 v63, v62, v64
	v_min_i32_e32 v65, v62, v64
	s_waitcnt vmcnt(2) lgkmcnt(1)
	v_mfma_f32_32x32x16_bf16 v[18:33], v[54:57], v[42:45], v[18:33]
	v_max_i32_e32 v64, v66, v67
	v_min_i32_e32 v62, v66, v67
	v_max_i32_e32 v61, v68, v70
	v_min_i32_e32 v60, v68, v70
	v_max_i32_e32 v59, v69, v71
	v_min_i32_e32 v57, v69, v71
	ds_read_b128 v[66:69], v94 offset:18528
	s_waitcnt vmcnt(1) lgkmcnt(1)
	v_mfma_f32_32x32x16_bf16 v[18:33], v[50:53], v[38:41], v[18:33]
	v_max_i32_e32 v55, v72, v74
	v_min_i32_e32 v58, v72, v74
	v_max_i32_e32 v56, v73, v75
	v_min_i32_e32 v54, v73, v75
	v_max_i32_e32 v53, v76, v78
	v_min_i32_e32 v52, v76, v78
	v_max_i32_e32 v51, v77, v79
	s_waitcnt vmcnt(0) lgkmcnt(0)
; #define LAS __attribute__((address_space(3)))
; #define MFMA32(a, b, c) __builtin_amdgcn_mfma_f32_32x32x16_bf16((a), (b), (c), 0, 0, 0)
; __device__ __forceinline__ void route_task(int task, int tl0, const bf16* QP  , const LAS bf16* KHL, LAS unsigned short* EL, LAS float* GL, int lane) {
;     ...
;     { unsigned qo = (unsigned)t * (unsigned)D + (unsigned)(head * 128 + 8 * hi); asm volatile("" : "+v"(qo)); const bf16* qp = QP + qo;
; #pragma unroll
;       for (int hf = 0; hf < 2; ++hf)
; #pragma unroll
;         for (int ks = 0; ks < 4; ++ks) qa[hf][ks] = ldg8(qp + 64 * hf + 16 * ks); }
;     ...
;         for (int kt = 0; kt < 4; ++kt) {
;             f32x16 X;
; #pragma unroll
;             for (int i = 0; i < 16; ++i) X[i] = 8.f;
;             const LAS bf16* khp = KHL + (half * 128 + 32 * kt + r) * 72 + 8 * hi;
; #pragma unroll
;             for (int ks = 0; ks < 4; ++ks) {
;                 const bf16x8 kh = lds8(khp + 16 * ks);
;                 X = MFMA32(kh, qa[half][ks], X);
;             }
;             int grp[16];
; #pragma unroll
;             for (int i = 0; i < 16; ++i) grp[i] = (int)((__float_as_uint(X[i]) | 127u) - (unsigned)(32 * kt + (i & 3) + 8 * (i >> 2)));
;             sort16_desc(grp);
;             if (kt == 0) {
; #pragma unroll
;                 for (int i = 0; i < 16; ++i) cur[i] = grp[i];
;             } else merge16_desc(cur, grp);
	v_or_b32_e32 v146, s10, v88
	v_mov_b32_e32 v147, v83
	v_lshl_add_u64 v[148:149], v[146:147], 1, s[80:81]
	global_load_dwordx4 v[150:153], v[148:149], off
	global_load_dwordx4 v[154:157], v[148:149], off offset:32
	global_load_dwordx4 v[158:161], v[148:149], off offset:64
	global_load_dwordx4 v[162:165], v[148:149], off offset:96
	global_load_dwordx4 v[166:169], v[148:149], off offset:128
	global_load_dwordx4 v[170:173], v[148:149], off offset:160
	global_load_dwordx4 v[174:177], v[148:149], off offset:192
	global_load_dwordx4 v[178:181], v[148:149], off offset:224
	v_mfma_f32_32x32x16_bf16 v[18:33], v[66:69], v[34:37], v[18:33]
	v_min_i32_e32 v50, v77, v79
	s_nop 10
	v_bitop3_b32 v21, v21, s42, 3 bitop3:0x56
	v_bitop3_b32 v32, v32, s42, 26 bitop3:0x56
	v_bitop3_b32 v22, v22, s42, 8 bitop3:0x56
	v_bitop3_b32 v26, v26, s42, 16 bitop3:0x56
	v_bitop3_b32 v31, v31, s42, 25 bitop3:0x56
	v_bitop3_b32 v23, v23, s42, 9 bitop3:0x56
	v_bitop3_b32 v24, v24, s42, 10 bitop3:0x56
	v_bitop3_b32 v27, v27, s42, 17 bitop3:0x56
	v_bitop3_b32 v28, v28, s42, 18 bitop3:0x56
	v_bitop3_b32 v20, v20, s42, 2 bitop3:0x56
	v_bitop3_b32 v33, v33, s42, 27 bitop3:0x56
	v_bitop3_b32 v25, v25, s42, 11 bitop3:0x56
	v_bitop3_b32 v29, v29, s42, 19 bitop3:0x56
	v_bitop3_b32 v19, v19, s42, 1 bitop3:0x56
	v_bitop3_b32 v30, v30, s42, 24 bitop3:0x56
	v_or_b32_e32 v18, 0x7f, v18
	v_max_i32_e32 v66, v21, v32
	v_max_i32_e32 v67, v22, v26
	v_max_i32_e32 v69, v18, v31
	v_max_i32_e32 v70, v23, v24
	v_min_i32_e32 v73, v27, v28
	v_min_i32_e32 v74, v20, v33
	v_min_i32_e32 v76, v25, v29
	v_min_i32_e32 v77, v19, v30
	v_min_i32_e32 v23, v23, v24
	v_min_i32_e32 v18, v18, v31
	v_min_i32_e32 v22, v22, v26
	v_min_i32_e32 v21, v21, v32
	v_max_i32_e32 v19, v19, v30
	v_max_i32_e32 v25, v25, v29
	v_max_i32_e32 v20, v20, v33
	v_max_i32_e32 v27, v27, v28
	v_max_i32_e32 v24, v23, v18
	v_max_i32_e32 v26, v22, v21
	v_min_i32_e32 v29, v19, v25
	v_min_i32_e32 v28, v20, v27
	v_max_i32_e32 v31, v24, v26
	v_min_i32_e32 v24, v24, v26
	v_min_i32_e32 v26, v29, v28
	v_min_i32_e32 v68, v66, v67
	v_min_i32_e32 v71, v69, v70
	v_max_i32_e32 v75, v73, v74
	v_max_i32_e32 v78, v76, v77
	v_max_i32_e32 v30, v29, v28
	v_max_i32_e32 v28, v24, v26
	v_min_i32_e32 v81, v24, v26
	v_min_i32_e32 v24, v76, v77
	v_min_i32_e32 v18, v23, v18
	v_min_i32_e32 v21, v22, v21
	v_min_i32_e32 v22, v73, v74
	v_min_i32_e32 v72, v68, v71
	v_min_i32_e32 v79, v75, v78
	v_min_i32_e32 v76, v24, v18
	v_min_i32_e32 v74, v21, v22
	v_max_i32_e32 v18, v24, v18
	v_max_i32_e32 v21, v21, v22
	v_max_i32_e32 v23, v69, v70
	v_max_i32_e32 v19, v19, v25
	v_max_i32_e32 v20, v20, v27
	v_max_i32_e32 v25, v66, v67
	v_max_i32_e32 v80, v72, v79
	v_max_i32_e32 v29, v68, v71
	v_max_i32_e32 v68, v75, v78
	v_min_i32_e32 v79, v72, v79
	v_max_i32_e32 v77, v76, v74
	v_min_i32_e32 v124, v18, v21
	v_min_i32_e32 v24, v23, v19
	v_min_i32_e32 v26, v20, v25
	v_min_i32_e32 v32, v31, v30
	v_min_i32_e32 v71, v29, v68
	v_max_i32_e32 v82, v81, v79
	v_max_i32_e32 v125, v77, v124
	v_min_i32_e32 v27, v24, v26
	v_max_i32_e32 v18, v18, v21
	v_min_i32_e32 v33, v80, v32
	v_min_i32_e32 v75, v28, v71
	v_max_i32_e32 v22, v82, v125
	v_min_i32_e32 v21, v27, v18
	v_max_i32_e32 v78, v33, v75
	v_max_i32_e32 v66, v22, v21
	v_max_i32_e32 v70, v78, v66
	v_max_i32_e32 v131, v29, v68
	v_min_i32_e32 v78, v78, v66
	ds_read_b128 v[66:69], v97
	v_max_i32_e32 v127, v23, v19
	v_max_i32_e32 v128, v20, v25
	v_max_i32_e32 v126, v24, v26
	v_min_i32_e32 v129, v127, v128
	v_max_i32_e32 v132, v31, v30
	v_min_i32_e32 v130, v126, v129
	v_min_i32_e32 v133, v131, v132
	v_max_i32_e32 v18, v27, v18
	v_min_i32_e32 v19, v130, v133
	v_max_i32_e32 v23, v80, v32
	v_max_i32_e32 v24, v28, v71
	v_min_i32_e32 v20, v18, v19
	v_min_i32_e32 v25, v23, v24
	v_min_i32_e32 v26, v20, v25
	v_min_i32_e32 v80, v70, v26
	v_max_i32_e32 v143, v70, v26
	ds_read_b128 v[70:73], v97 offset:32
	v_min_i32_e32 v75, v33, v75
	v_min_i32_e32 v134, v22, v21
	v_max_i32_e32 v138, v18, v19
	v_max_i32_e32 v139, v23, v24
	v_max_i32_e32 v141, v20, v25
	s_waitcnt lgkmcnt(1)
	v_mfma_f32_32x32x16_bf16 v[18:33], v[66:69], v[46:49], v[2:17]
	ds_read_b128 v[66:69], v97 offset:64
	v_max_i32_e32 v135, v75, v134
	v_max_i32_e32 v136, v78, v135
	v_min_i32_e32 v79, v81, v79
	v_min_i32_e32 v77, v77, v124
	v_min_i32_e32 v78, v78, v135
	v_max_i32_e32 v130, v130, v133
	s_waitcnt lgkmcnt(1)
	v_mfma_f32_32x32x16_bf16 v[18:33], v[70:73], v[42:45], v[18:33]
	ds_read_b128 v[70:73], v97 offset:96
	v_max_i32_e32 v126, v126, v129
	v_min_i32_e32 v74, v76, v74
	v_min_i32_e32 v140, v138, v139
	v_max_i32_e32 v81, v79, v77
	v_min_i32_e32 v82, v82, v125
	v_min_i32_e32 v75, v75, v134
	s_waitcnt lgkmcnt(1)
	v_mfma_f32_32x32x16_bf16 v[18:33], v[66:69], v[38:41], v[18:33]
	v_max_i32_e32 v66, v131, v132
	v_max_i32_e32 v134, v138, v139
	v_min_i32_e32 v77, v79, v77
	v_max_i32_e32 v124, v81, v82
	v_min_i32_e32 v81, v81, v82
	v_min_i32_e32 v67, v126, v66
	v_min_i32_e32 v142, v140, v141
	s_waitcnt lgkmcnt(0)
; #define LAS __attribute__((address_space(3)))
; #define MFMA32(a, b, c) __builtin_amdgcn_mfma_f32_32x32x16_bf16((a), (b), (c), 0, 0, 0)
; #define CE_(a, b) ce_desc(v[a], v[b])
; __device__ __forceinline__ void sort16_desc(int (&v)[16]) {
;     ...
;     CE_(0,13); CE_(1,12); CE_(2,15); CE_(3,14); CE_(4,8); CE_(5,6); CE_(7,11); CE_(9,10);
;     CE_(0,5); CE_(1,7); CE_(2,9); CE_(3,4); CE_(6,13); CE_(8,14); CE_(10,15); CE_(11,12);
;     CE_(0,1); CE_(2,3); CE_(4,5); CE_(6,8); CE_(7,9); CE_(10,11); CE_(12,13); CE_(14,15);
;     CE_(0,2); CE_(1,3); CE_(4,10); CE_(5,11); CE_(6,7); CE_(8,9); CE_(12,14); CE_(13,15);
;     CE_(1,2); CE_(3,12); CE_(4,6); CE_(5,7); CE_(8,10); CE_(9,11); CE_(13,14);
;     CE_(1,4); CE_(2,6); CE_(5,8); CE_(7,10); CE_(9,13); CE_(11,14);
;     CE_(2,4); CE_(3,6); CE_(9,12); CE_(11,13);
;     CE_(3,5); CE_(6,8); CE_(7,9); CE_(10,12);
;     CE_(3,4); CE_(5,6); CE_(7,8); CE_(9,10); CE_(11,12);
;     CE_(6,7); CE_(8,9);
;     ...
; }
; __device__ __forceinline__ void merge16_desc(int (&a)[16], const int (&b)[16]) {
; #pragma unroll
;     for (int i = 0; i < 16; ++i) a[i] = a[i] > b[15 - i] ? a[i] : b[15 - i];
; #pragma unroll
;     for (int j = 8; j > 0; j >>= 1)
; #pragma unroll
;         for (int i = 0; i < 16; ++i) { const int l = i ^ j; if (l > i) ce_desc(a[i], a[l]); }
; }
; __device__ __forceinline__ void route_task(int task, int tl0, const bf16* QP  , const LAS bf16* KHL, LAS unsigned short* EL, LAS float* GL, int lane) {
;     ...
;         for (int kt = 0; kt < 4; ++kt) {
;             f32x16 X;
; #pragma unroll
;             for (int i = 0; i < 16; ++i) X[i] = 8.f;
;             const LAS bf16* khp = KHL + (half * 128 + 32 * kt + r) * 72 + 8 * hi;
; #pragma unroll
;             for (int ks = 0; ks < 4; ++ks) {
;                 const bf16x8 kh = lds8(khp + 16 * ks);
;                 X = MFMA32(kh, qa[half][ks], X);
;             }
;             int grp[16];
; #pragma unroll
;             for (int i = 0; i < 16; ++i) grp[i] = (int)((__float_as_uint(X[i]) | 127u) - (unsigned)(32 * kt + (i & 3) + 8 * (i >> 2)));
;             sort16_desc(grp);
;             if (kt == 0) {
; #pragma unroll
;                 for (int i = 0; i < 16; ++i) cur[i] = grp[i];
;             } else merge16_desc(cur, grp);
	v_mfma_f32_32x32x16_bf16 v[18:33], v[70:73], v[34:37], v[18:33]
	v_min_i32_e32 v68, v130, v67
	v_min_i32_e32 v137, v80, v136
	v_min_i32_e32 v144, v142, v143
	v_min_i32_e32 v125, v124, v75
	v_min_i32_e32 v69, v134, v68
	s_nop 6
	v_bitop3_b32 v21, v21, s42, 35 bitop3:0x56
	v_bitop3_b32 v32, v32, s42, 58 bitop3:0x56
	v_bitop3_b32 v22, v22, s42, 40 bitop3:0x56
	v_bitop3_b32 v26, v26, s42, 48 bitop3:0x56
	v_bitop3_b32 v18, v18, s42, 32 bitop3:0x56
	v_bitop3_b32 v31, v31, s42, 57 bitop3:0x56
	v_bitop3_b32 v23, v23, s42, 41 bitop3:0x56
	v_bitop3_b32 v24, v24, s42, 42 bitop3:0x56
	v_bitop3_b32 v27, v27, s42, 49 bitop3:0x56
	v_bitop3_b32 v28, v28, s42, 50 bitop3:0x56
	v_bitop3_b32 v20, v20, s42, 34 bitop3:0x56
	v_bitop3_b32 v33, v33, s42, 59 bitop3:0x56
	v_bitop3_b32 v25, v25, s42, 43 bitop3:0x56
	v_bitop3_b32 v29, v29, s42, 51 bitop3:0x56
	v_bitop3_b32 v19, v19, s42, 33 bitop3:0x56
	v_bitop3_b32 v30, v30, s42, 56 bitop3:0x56
	v_max_i32_e32 v70, v21, v32
	v_max_i32_e32 v71, v22, v26
	v_max_i32_e32 v73, v18, v31
	v_max_i32_e32 v76, v23, v24
	v_min_i32_e32 v129, v27, v28
	v_min_i32_e32 v131, v20, v33
	v_min_i32_e32 v133, v25, v29
	v_min_i32_e32 v135, v19, v30
	v_min_i32_e32 v23, v23, v24
	v_min_i32_e32 v18, v18, v31
	v_min_i32_e32 v22, v22, v26
	v_min_i32_e32 v21, v21, v32
	v_max_i32_e32 v19, v19, v30
	v_max_i32_e32 v25, v25, v29
	v_max_i32_e32 v20, v20, v33
	v_max_i32_e32 v27, v27, v28
	v_min_i32_e32 v72, v70, v71
	v_min_i32_e32 v79, v73, v76
	v_max_i32_e32 v132, v129, v131
	v_max_i32_e32 v138, v133, v135
	v_max_i32_e32 v24, v23, v18
	v_max_i32_e32 v26, v22, v21
	v_min_i32_e32 v29, v19, v25
	v_min_i32_e32 v28, v20, v27
	v_min_i32_e32 v133, v133, v135
	v_min_i32_e32 v18, v23, v18
	v_min_i32_e32 v21, v22, v21
	v_min_i32_e32 v22, v129, v131
	v_max_i32_e32 v73, v73, v76
	v_max_i32_e32 v19, v19, v25
	v_max_i32_e32 v20, v20, v27
	v_max_i32_e32 v27, v70, v71
	v_min_i32_e32 v82, v72, v79
	v_min_i32_e32 v139, v132, v138
	v_max_i32_e32 v31, v24, v26
	v_max_i32_e32 v30, v29, v28
	v_min_i32_e32 v24, v24, v26
	v_min_i32_e32 v26, v29, v28
	v_max_i32_e32 v29, v72, v79
	v_max_i32_e32 v72, v132, v138
	v_min_i32_e32 v23, v133, v18
	v_min_i32_e32 v129, v21, v22
	v_max_i32_e32 v18, v133, v18
	v_max_i32_e32 v21, v21, v22
	v_min_i32_e32 v25, v73, v19
	v_min_i32_e32 v70, v20, v27
	v_max_i32_e32 v19, v73, v19
	v_max_i32_e32 v20, v20, v27
	v_min_i32_e32 v32, v31, v30
	v_max_i32_e32 v28, v24, v26
	v_min_i32_e32 v79, v29, v72
	v_min_i32_e32 v24, v24, v26
	v_min_i32_e32 v26, v82, v139
	v_max_i32_e32 v131, v23, v129
	v_min_i32_e32 v22, v18, v21
	v_min_i32_e32 v71, v25, v70
	v_max_i32_e32 v25, v25, v70
	v_min_i32_e32 v27, v19, v20
	v_max_i32_e32 v29, v29, v72
	v_max_i32_e32 v30, v31, v30
	v_max_i32_e32 v145, v82, v139
	v_max_i32_e32 v82, v24, v26
	v_max_i32_e32 v133, v131, v22
	v_max_i32_e32 v18, v18, v21
	v_min_i32_e32 v70, v25, v27
	v_min_i32_e32 v31, v29, v30
	v_min_i32_e32 v33, v145, v32
	v_min_i32_e32 v132, v28, v79
	v_max_i32_e32 v135, v82, v133
	v_min_i32_e32 v21, v71, v18
	v_max_i32_e32 v18, v71, v18
	v_min_i32_e32 v71, v70, v31
	v_max_i32_e32 v32, v145, v32
	v_max_i32_e32 v28, v28, v79
	v_max_i32_e32 v138, v33, v132
	v_max_i32_e32 v76, v135, v21
	v_min_i32_e32 v72, v18, v71
	v_min_i32_e32 v73, v32, v28
	v_min_i32_e32 v33, v33, v132
	v_min_i32_e32 v21, v135, v21
	v_max_i32_e32 v18, v18, v71
	v_max_i32_e32 v28, v32, v28
	v_min_i32_e32 v24, v24, v26
	v_min_i32_e32 v22, v131, v22
	v_max_i32_e32 v25, v25, v27
	v_max_i32_e32 v27, v29, v30
	v_max_i32_e32 v139, v138, v76
	v_min_i32_e32 v79, v72, v73
	v_min_i32_e32 v76, v138, v76
	v_max_i32_e32 v132, v33, v21
	v_min_i32_e32 v32, v18, v28
	v_max_i32_e32 v71, v72, v73
	v_max_i32_e32 v26, v24, v22
	v_min_i32_e32 v82, v82, v133
	v_max_i32_e32 v18, v18, v28
	v_max_i32_e32 v28, v70, v31
	v_min_i32_e32 v29, v25, v27
	v_min_i32_e32 v145, v139, v79
	v_max_i32_e32 v135, v76, v132
	v_min_i32_e32 v72, v32, v71
	v_max_i32_e32 v73, v139, v79
	v_max_i32_e32 v131, v26, v82
	v_min_i32_e32 v21, v33, v21
	v_min_i32_e32 v30, v28, v29
	v_min_i32_e32 v138, v145, v135
	v_min_i32_e32 v79, v72, v73
	v_min_i32_e32 v33, v131, v21
	v_min_i32_e32 v76, v76, v132
	v_min_i32_e32 v31, v18, v30
	v_min_i32_e32 v26, v26, v82
	v_min_i32_e32 v22, v24, v22
	v_min_i32_e32 v23, v23, v129
	v_max3_i32 v23, v127, v128, v23
	v_max3_i32 v22, v126, v66, v22
	v_max3_i32 v24, v130, v67, v26
	v_max3_i32 v26, v134, v68, v33
	v_max3_i32 v21, v69, v131, v21
	v_max3_i32 v33, v140, v141, v76
	v_max3_i32 v66, v142, v143, v138
	v_max3_i32 v67, v144, v145, v135
	v_max3_i32 v68, v80, v136, v79
	v_max3_i32 v69, v137, v72, v73
	v_max3_i32 v32, v78, v32, v71
	v_max3_i32 v31, v124, v75, v31
	v_max3_i32 v18, v125, v18, v30
	v_max3_i32 v28, v81, v28, v29
	v_max3_i32 v25, v77, v25, v27
	v_max3_i32 v19, v74, v19, v20
	v_max_i32_e32 v20, v23, v68
	v_min_i32_e32 v23, v23, v68
	v_max_i32_e32 v27, v22, v69
	v_min_i32_e32 v22, v22, v69
	v_max_i32_e32 v29, v24, v32
	v_min_i32_e32 v24, v24, v32
	v_max_i32_e32 v30, v26, v31
	v_min_i32_e32 v26, v26, v31
	v_max_i32_e32 v31, v21, v18
	v_min_i32_e32 v18, v21, v18
	v_max_i32_e32 v21, v33, v28
	v_min_i32_e32 v28, v33, v28
	v_max_i32_e32 v32, v66, v25
	v_min_i32_e32 v25, v66, v25
	v_max_i32_e32 v33, v67, v19
	v_min_i32_e32 v19, v67, v19
	ds_read_b128 v[66:69], v94 offset:27648
	v_max_i32_e32 v70, v20, v31
	v_min_i32_e32 v74, v20, v31
	v_max_i32_e32 v20, v27, v21
	v_min_i32_e32 v75, v27, v21
	v_max_i32_e32 v21, v29, v32
	v_max_i32_e32 v27, v30, v33
	v_max_i32_e32 v127, v70, v21
	v_min_i32_e32 v128, v70, v21
	ds_read_b128 v[70:73], v94 offset:27680
	v_min_i32_e32 v76, v29, v32
	v_min_i32_e32 v77, v30, v33
	v_max_i32_e32 v78, v23, v18
	v_min_i32_e32 v79, v23, v18
	v_max_i32_e32 v80, v22, v28
	v_min_i32_e32 v81, v22, v28
	v_max_i32_e32 v82, v24, v25
	v_min_i32_e32 v124, v24, v25
	v_max_i32_e32 v125, v26, v19
	v_min_i32_e32 v126, v26, v19
	v_max_i32_e32 v129, v20, v27
	v_min_i32_e32 v130, v20, v27
	s_waitcnt lgkmcnt(1)
; #define LAS __attribute__((address_space(3)))
; #define MFMA32(a, b, c) __builtin_amdgcn_mfma_f32_32x32x16_bf16((a), (b), (c), 0, 0, 0)
; #define CE_(a, b) ce_desc(v[a], v[b])
; __device__ __forceinline__ void sort16_desc(int (&v)[16]) {
;     ...
;     CE_(0,13); CE_(1,12); CE_(2,15); CE_(3,14); CE_(4,8); CE_(5,6); CE_(7,11); CE_(9,10);
;     CE_(0,5); CE_(1,7); CE_(2,9); CE_(3,4); CE_(6,13); CE_(8,14); CE_(10,15); CE_(11,12);
;     CE_(0,1); CE_(2,3); CE_(4,5); CE_(6,8); CE_(7,9); CE_(10,11); CE_(12,13); CE_(14,15);
;     CE_(0,2); CE_(1,3); CE_(4,10); CE_(5,11); CE_(6,7); CE_(8,9); CE_(12,14); CE_(13,15);
;     CE_(1,2); CE_(3,12); CE_(4,6); CE_(5,7); CE_(8,10); CE_(9,11); CE_(13,14);
;     CE_(1,4); CE_(2,6); CE_(5,8); CE_(7,10); CE_(9,13); CE_(11,14);
;     CE_(2,4); CE_(3,6); CE_(9,12); CE_(11,13);
;     CE_(3,5); CE_(6,8); CE_(7,9); CE_(10,12);
;     CE_(3,4); CE_(5,6); CE_(7,8); CE_(9,10); CE_(11,12);
;     CE_(6,7); CE_(8,9);
;     ...
; }
; __device__ __forceinline__ void merge16_desc(int (&a)[16], const int (&b)[16]) {
; #pragma unroll
;     for (int i = 0; i < 16; ++i) a[i] = a[i] > b[15 - i] ? a[i] : b[15 - i];
; #pragma unroll
;     for (int j = 8; j > 0; j >>= 1)
; #pragma unroll
;         for (int i = 0; i < 16; ++i) { const int l = i ^ j; if (l > i) ce_desc(a[i], a[l]); }
; }
; __device__ __forceinline__ void route_task(int task, int tl0, const bf16* QP  , const LAS bf16* KHL, LAS unsigned short* EL, LAS float* GL, int lane) {
;     ...
;         for (int kt = 0; kt < 4; ++kt) {
;             f32x16 X;
; #pragma unroll
;             for (int i = 0; i < 16; ++i) X[i] = 8.f;
;             const LAS bf16* khp = KHL + (half * 128 + 32 * kt + r) * 72 + 8 * hi;
; #pragma unroll
;             for (int ks = 0; ks < 4; ++ks) {
;                 const bf16x8 kh = lds8(khp + 16 * ks);
;                 X = MFMA32(kh, qa[half][ks], X);
;             }
;             int grp[16];
; #pragma unroll
;             for (int i = 0; i < 16; ++i) grp[i] = (int)((__float_as_uint(X[i]) | 127u) - (unsigned)(32 * kt + (i & 3) + 8 * (i >> 2)));
;             sort16_desc(grp);
;             if (kt == 0) {
; #pragma unroll
;                 for (int i = 0; i < 16; ++i) cur[i] = grp[i];
;             } else merge16_desc(cur, grp);
	v_mfma_f32_32x32x16_bf16 v[18:33], v[66:69], v[46:49], v[2:17]
	ds_read_b128 v[66:69], v94 offset:27712
	v_max_i32_e32 v131, v74, v76
	v_min_i32_e32 v74, v74, v76
	v_max_i32_e32 v76, v75, v77
	v_min_i32_e32 v75, v75, v77
	v_max_i32_e32 v77, v78, v82
	v_min_i32_e32 v78, v78, v82
	s_waitcnt lgkmcnt(1)
	v_mfma_f32_32x32x16_bf16 v[18:33], v[70:73], v[42:45], v[18:33]
	ds_read_b128 v[70:73], v94 offset:27744
	v_max_i32_e32 v82, v80, v125
	v_min_i32_e32 v80, v80, v125
	v_max_i32_e32 v125, v79, v124
	v_min_i32_e32 v79, v79, v124
	v_max_i32_e32 v124, v81, v126
	v_min_i32_e32 v81, v81, v126
	s_waitcnt lgkmcnt(1)
	v_mfma_f32_32x32x16_bf16 v[18:33], v[66:69], v[38:41], v[18:33]
	v_min_i32_e32 v126, v127, v129
	v_min_i32_e32 v66, v128, v130
	v_min_i32_e32 v67, v131, v76
	v_min_i32_e32 v69, v77, v82
	v_min_i32_e32 v132, v78, v80
	v_min_i32_e32 v133, v125, v124
	v_min_i32_e32 v68, v74, v75
	s_waitcnt lgkmcnt(0)
	v_mfma_f32_32x32x16_bf16 v[18:33], v[70:73], v[34:37], v[18:33]
	v_min_i32_e32 v134, v79, v81
	s_nop 10
	v_and_or_b32 v21, v21, s43, 60
	v_and_or_b32 v32, v32, s43, 37
	v_and_or_b32 v22, v22, s43, 55
	v_and_or_b32 v26, v26, s43, 47
	v_bitop3_b32 v18, v18, s42, 64 bitop3:0x56
	v_and_or_b32 v31, v31, s43, 38
	v_and_or_b32 v23, v23, s43, 54
	v_and_or_b32 v24, v24, s43, 53
	v_and_or_b32 v27, v27, s43, 46
	v_and_or_b32 v28, v28, s43, 45
	v_and_or_b32 v20, v20, s43, 61
	v_and_or_b32 v33, v33, s43, 36
	v_and_or_b32 v25, v25, s43, 52
	v_and_or_b32 v29, v29, s43, 44
	v_and_or_b32 v19, v19, s43, 62
	v_and_or_b32 v30, v30, s43, 39
	v_max_i32_e32 v70, v21, v32
	v_max_i32_e32 v71, v22, v26
	v_max_i32_e32 v73, v18, v31
	v_max_i32_e32 v135, v23, v24
	v_min_i32_e32 v138, v27, v28
	v_min_i32_e32 v139, v20, v33
	v_min_i32_e32 v141, v25, v29
	v_min_i32_e32 v142, v19, v30
	v_min_i32_e32 v23, v23, v24
	v_min_i32_e32 v18, v18, v31
	v_min_i32_e32 v22, v22, v26
	v_min_i32_e32 v21, v21, v32
	v_max_i32_e32 v19, v19, v30
	v_max_i32_e32 v25, v25, v29
	v_max_i32_e32 v20, v20, v33
	v_max_i32_e32 v27, v27, v28
	v_min_i32_e32 v72, v70, v71
	v_min_i32_e32 v136, v73, v135
	v_max_i32_e32 v140, v138, v139
	v_max_i32_e32 v143, v141, v142
	v_max_i32_e32 v24, v23, v18
	v_max_i32_e32 v26, v22, v21
	v_min_i32_e32 v29, v19, v25
	v_min_i32_e32 v28, v20, v27
	v_min_i32_e32 v141, v141, v142
	v_min_i32_e32 v18, v23, v18
	v_min_i32_e32 v21, v22, v21
	v_min_i32_e32 v22, v138, v139
	v_max_i32_e32 v73, v73, v135
	v_max_i32_e32 v19, v19, v25
	v_max_i32_e32 v20, v20, v27
	v_max_i32_e32 v27, v70, v71
	v_min_i32_e32 v137, v72, v136
	v_min_i32_e32 v144, v140, v143
	v_max_i32_e32 v31, v24, v26
	v_max_i32_e32 v30, v29, v28
	v_min_i32_e32 v24, v24, v26
	v_min_i32_e32 v26, v29, v28
	v_max_i32_e32 v29, v72, v136
	v_max_i32_e32 v72, v140, v143
	v_min_i32_e32 v23, v141, v18
	v_min_i32_e32 v138, v21, v22
	v_max_i32_e32 v18, v141, v18
	v_max_i32_e32 v21, v21, v22
	v_min_i32_e32 v25, v73, v19
	v_min_i32_e32 v70, v20, v27
	v_max_i32_e32 v19, v73, v19
	v_max_i32_e32 v20, v20, v27
	v_min_i32_e32 v32, v31, v30
	v_max_i32_e32 v28, v24, v26
	v_min_i32_e32 v136, v29, v72
	v_min_i32_e32 v24, v24, v26
	v_min_i32_e32 v26, v137, v144
	v_max_i32_e32 v139, v23, v138
	v_min_i32_e32 v22, v18, v21
	v_min_i32_e32 v71, v25, v70
	v_max_i32_e32 v25, v25, v70
	v_min_i32_e32 v27, v19, v20
	v_max_i32_e32 v29, v29, v72
	v_max_i32_e32 v30, v31, v30
	v_max_i32_e32 v145, v137, v144
	v_max_i32_e32 v137, v24, v26
	v_max_i32_e32 v141, v139, v22
	v_max_i32_e32 v18, v18, v21
	v_min_i32_e32 v70, v25, v27
	v_min_i32_e32 v31, v29, v30
	v_min_i32_e32 v33, v145, v32
	v_min_i32_e32 v140, v28, v136
	v_max_i32_e32 v142, v137, v141
	v_min_i32_e32 v21, v71, v18
	v_max_i32_e32 v18, v71, v18
	v_min_i32_e32 v71, v70, v31
	v_max_i32_e32 v32, v145, v32
	v_max_i32_e32 v28, v28, v136
	v_max_i32_e32 v143, v33, v140
	v_max_i32_e32 v135, v142, v21
	v_min_i32_e32 v72, v18, v71
	v_min_i32_e32 v73, v32, v28
	v_min_i32_e32 v33, v33, v140
	v_min_i32_e32 v21, v142, v21
	v_max_i32_e32 v18, v18, v71
	v_max_i32_e32 v28, v32, v28
	v_min_i32_e32 v24, v24, v26
	v_min_i32_e32 v22, v139, v22
	v_max_i32_e32 v25, v25, v27
	v_max_i32_e32 v27, v29, v30
	v_max_i32_e32 v144, v143, v135
	v_min_i32_e32 v136, v72, v73
	v_min_i32_e32 v135, v143, v135
	v_max_i32_e32 v140, v33, v21
	v_min_i32_e32 v32, v18, v28
	v_max_i32_e32 v71, v72, v73
	v_max_i32_e32 v26, v24, v22
	v_min_i32_e32 v137, v137, v141
	v_max_i32_e32 v18, v18, v28
	v_max_i32_e32 v28, v70, v31
	v_min_i32_e32 v29, v25, v27
	v_min_i32_e32 v145, v144, v136
	v_max_i32_e32 v142, v135, v140
	v_min_i32_e32 v72, v32, v71
	v_max_i32_e32 v73, v144, v136
	v_max_i32_e32 v139, v26, v137
	v_min_i32_e32 v21, v33, v21
	v_min_i32_e32 v30, v28, v29
	v_min_i32_e32 v143, v145, v142
	v_min_i32_e32 v136, v72, v73
	v_min_i32_e32 v33, v139, v21
	v_max_i32_e32 v21, v139, v21
	v_min_i32_e32 v135, v135, v140
	v_max_i32_e32 v32, v32, v71
	v_min_i32_e32 v31, v18, v30
	v_max_i32_e32 v18, v18, v30
	v_min_i32_e32 v26, v26, v137
	v_min_i32_e32 v22, v24, v22
	v_max_i32_e32 v24, v25, v27
	v_min_i32_e32 v23, v23, v138
	v_max3_i32 v23, v127, v129, v23
	v_max_i32_e32 v22, v126, v22
	v_max3_i32 v25, v128, v130, v26
	v_max_i32_e32 v26, v66, v33
	v_max3_i32 v21, v131, v76, v21
	v_max_i32_e32 v27, v67, v135
	v_max3_i32 v30, v74, v75, v143
	v_max3_i32 v66, v77, v82, v136
	v_max3_i32 v67, v69, v72, v73
	v_max3_i32 v32, v78, v80, v32
	v_max_i32_e32 v31, v132, v31
	v_max3_i32 v18, v125, v124, v18
	v_max3_i32 v28, v133, v28, v29
	v_max3_i32 v24, v79, v81, v24
	v_max3_i32 v33, v68, v145, v142
	v_max3_i32 v19, v134, v19, v20
	v_max_i32_e32 v20, v23, v66
	v_min_i32_e32 v23, v23, v66
	v_max_i32_e32 v29, v22, v67
	v_max_i32_e32 v66, v25, v32
	v_min_i32_e32 v25, v25, v32
	v_max_i32_e32 v32, v26, v31
	v_min_i32_e32 v26, v26, v31
	v_max_i32_e32 v31, v21, v18
	v_min_i32_e32 v18, v21, v18
	v_max_i32_e32 v21, v27, v28
	v_min_i32_e32 v27, v27, v28
	v_max_i32_e32 v28, v30, v24
	v_min_i32_e32 v22, v22, v67
	v_min_i32_e32 v24, v30, v24
	v_max_i32_e32 v30, v33, v19
	v_min_i32_e32 v19, v33, v19
	v_max_i32_e32 v33, v20, v31
	v_min_i32_e32 v74, v20, v31
	v_max_i32_e32 v20, v29, v21
	v_min_i32_e32 v75, v29, v21
	v_max_i32_e32 v21, v66, v28
	v_min_i32_e32 v76, v66, v28
	ds_read_b128 v[66:69], v98
	ds_read_b128 v[70:73], v98 offset:32
	v_max_i32_e32 v28, v32, v30
	v_min_i32_e32 v77, v32, v30
	v_max_i32_e32 v78, v23, v18
	v_min_i32_e32 v79, v23, v18
	v_max_i32_e32 v80, v22, v27
	v_min_i32_e32 v81, v22, v27
	v_max_i32_e32 v82, v25, v24
	v_min_i32_e32 v124, v25, v24
	v_max_i32_e32 v125, v26, v19
	v_min_i32_e32 v126, v26, v19
	v_max_i32_e32 v127, v33, v21
	v_min_i32_e32 v128, v33, v21
	v_max_i32_e32 v129, v20, v28
	v_min_i32_e32 v130, v20, v28
	s_waitcnt lgkmcnt(1)
; #define LAS __attribute__((address_space(3)))
; #define MFMA32(a, b, c) __builtin_amdgcn_mfma_f32_32x32x16_bf16((a), (b), (c), 0, 0, 0)
; #define CE_(a, b) ce_desc(v[a], v[b])
; __device__ __forceinline__ void sort16_desc(int (&v)[16]) {
;     ...
;     CE_(0,13); CE_(1,12); CE_(2,15); CE_(3,14); CE_(4,8); CE_(5,6); CE_(7,11); CE_(9,10);
;     CE_(0,5); CE_(1,7); CE_(2,9); CE_(3,4); CE_(6,13); CE_(8,14); CE_(10,15); CE_(11,12);
;     CE_(0,1); CE_(2,3); CE_(4,5); CE_(6,8); CE_(7,9); CE_(10,11); CE_(12,13); CE_(14,15);
;     CE_(0,2); CE_(1,3); CE_(4,10); CE_(5,11); CE_(6,7); CE_(8,9); CE_(12,14); CE_(13,15);
;     CE_(1,2); CE_(3,12); CE_(4,6); CE_(5,7); CE_(8,10); CE_(9,11); CE_(13,14);
;     CE_(1,4); CE_(2,6); CE_(5,8); CE_(7,10); CE_(9,13); CE_(11,14);
;     CE_(2,4); CE_(3,6); CE_(9,12); CE_(11,13);
;     CE_(3,5); CE_(6,8); CE_(7,9); CE_(10,12);
;     CE_(3,4); CE_(5,6); CE_(7,8); CE_(9,10); CE_(11,12);
;     CE_(6,7); CE_(8,9);
;     ...
; }
; __device__ __forceinline__ void merge16_desc(int (&a)[16], const int (&b)[16]) {
; #pragma unroll
;     for (int i = 0; i < 16; ++i) a[i] = a[i] > b[15 - i] ? a[i] : b[15 - i];
; #pragma unroll
;     for (int j = 8; j > 0; j >>= 1)
; #pragma unroll
;         for (int i = 0; i < 16; ++i) { const int l = i ^ j; if (l > i) ce_desc(a[i], a[l]); }
; }
; __device__ __forceinline__ void route_task(int task, int tl0, const bf16* QP  , const LAS bf16* KHL, LAS unsigned short* EL, LAS float* GL, int lane) {
;     ...
;         for (int kt = 0; kt < 4; ++kt) {
;             f32x16 X;
; #pragma unroll
;             for (int i = 0; i < 16; ++i) X[i] = 8.f;
;             const LAS bf16* khp = KHL + (half * 128 + 32 * kt + r) * 72 + 8 * hi;
; #pragma unroll
;             for (int ks = 0; ks < 4; ++ks) {
;                 const bf16x8 kh = lds8(khp + 16 * ks);
;                 X = MFMA32(kh, qa[half][ks], X);
;             }
;             int grp[16];
; #pragma unroll
;             for (int i = 0; i < 16; ++i) grp[i] = (int)((__float_as_uint(X[i]) | 127u) - (unsigned)(32 * kt + (i & 3) + 8 * (i >> 2)));
;             sort16_desc(grp);
;             if (kt == 0) {
; #pragma unroll
;                 for (int i = 0; i < 16; ++i) cur[i] = grp[i];
;             } else merge16_desc(cur, grp);
	v_mfma_f32_32x32x16_bf16 v[18:33], v[66:69], v[46:49], v[2:17]
	ds_read_b128 v[46:49], v98 offset:64
	v_max_i32_e32 v67, v75, v77
	v_min_i32_e32 v68, v75, v77
	v_max_i32_e32 v75, v80, v125
	v_max_i32_e32 v131, v74, v76
	v_min_i32_e32 v66, v74, v76
	v_max_i32_e32 v69, v78, v82
	s_waitcnt lgkmcnt(1)
	v_mfma_f32_32x32x16_bf16 v[18:33], v[70:73], v[42:45], v[18:33]
	ds_read_b128 v[42:45], v98 offset:96
	v_min_i32_e32 v70, v80, v125
	v_max_i32_e32 v71, v79, v124
	v_min_i32_e32 v72, v79, v124
	v_min_i32_e32 v74, v78, v82
	v_max_i32_e32 v73, v81, v126
	v_min_i32_e32 v76, v81, v126
	s_waitcnt lgkmcnt(1)
	v_mfma_f32_32x32x16_bf16 v[18:33], v[46:49], v[38:41], v[18:33]
	v_min_i32_e32 v77, v127, v129
	v_min_i32_e32 v38, v128, v130
	v_min_i32_e32 v39, v131, v67
	v_min_i32_e32 v40, v66, v68
	v_min_i32_e32 v41, v69, v75
	v_min_i32_e32 v46, v74, v70
	v_min_i32_e32 v47, v71, v73
	s_waitcnt lgkmcnt(0)
	v_mfma_f32_32x32x16_bf16 v[18:33], v[42:45], v[34:37], v[18:33]
	v_min_i32_e32 v48, v72, v76
	s_nop 10
	v_and_or_b32 v25, v25, s43, 20
	v_and_or_b32 v29, v29, s43, 12
	v_and_or_b32 v19, v19, s43, 30
	v_and_or_b32 v30, v30, s43, 7
	v_and_or_b32 v23, v23, s43, 22
	v_and_or_b32 v24, v24, s43, 21
	v_and_or_b32 v18, v18, s43, 31
	v_and_or_b32 v31, v31, s43, 6
	v_and_or_b32 v22, v22, s43, 23
	v_and_or_b32 v26, v26, s43, 15
	v_and_or_b32 v21, v21, s43, 28
	v_and_or_b32 v32, v32, s43, 5
	v_and_or_b32 v27, v27, s43, 14
	v_and_or_b32 v28, v28, s43, 13
	v_and_or_b32 v20, v20, s43, 29
	v_and_or_b32 v33, v33, s43, 4
	v_min_i32_e32 v34, v25, v29
	v_min_i32_e32 v35, v19, v30
	v_min_i32_e32 v37, v23, v24
	v_min_i32_e32 v42, v18, v31
	v_min_i32_e32 v45, v22, v26
	v_min_i32_e32 v49, v21, v32
	v_min_i32_e32 v79, v27, v28
	v_min_i32_e32 v80, v20, v33
	v_max_i32_e32 v18, v18, v31
	v_max_i32_e32 v23, v23, v24
	v_max_i32_e32 v19, v19, v30
	v_max_i32_e32 v25, v25, v29
	v_max_i32_e32 v20, v20, v33
	v_max_i32_e32 v27, v27, v28
	v_max_i32_e32 v21, v21, v32
	v_max_i32_e32 v22, v22, v26
	v_max_i32_e32 v24, v18, v23
	v_max_i32_e32 v29, v19, v25
	v_max_i32_e32 v28, v20, v27
	v_max_i32_e32 v26, v21, v22
	v_min_i32_e32 v30, v24, v29
	v_min_i32_e32 v31, v28, v26
	v_min_i32_e32 v43, v37, v42
	v_min_i32_e32 v32, v30, v31
	v_max_i32_e32 v30, v30, v31
	v_min_i32_e32 v21, v21, v22
	v_min_i32_e32 v18, v18, v23
	v_max_i32_e32 v23, v79, v80
	v_max_i32_e32 v31, v34, v35
	v_max_i32_e32 v37, v37, v42
	v_max_i32_e32 v42, v45, v49
	v_min_i32_e32 v19, v19, v25
	v_min_i32_e32 v20, v20, v27
	v_min_i32_e32 v36, v34, v35
	v_min_i32_e32 v78, v45, v49
	v_min_i32_e32 v81, v79, v80
	v_max_i32_e32 v22, v21, v18
	v_max_i32_e32 v45, v37, v42
	v_max_i32_e32 v25, v19, v20
	v_min_i32_e32 v18, v21, v18
	v_min_i32_e32 v21, v23, v31
	v_min_i32_e32 v44, v36, v43
	v_min_i32_e32 v82, v78, v81
	v_max_i32_e32 v33, v36, v43
	v_max_i32_e32 v36, v78, v81
	v_max_i32_e32 v24, v24, v29
	v_max_i32_e32 v26, v28, v26
	v_max_i32_e32 v34, v23, v31
	v_max_i32_e32 v27, v45, v25
	v_max_i32_e32 v23, v18, v21
	v_min_i32_e32 v25, v45, v25
	v_min_i32_e32 v37, v37, v42
	v_min_i32_e32 v19, v19, v20
	v_max_i32_e32 v43, v33, v36
	v_min_i32_e32 v28, v24, v26
	v_max_i32_e32 v35, v22, v34
	v_max_i32_e32 v31, v23, v25
	v_max_i32_e32 v20, v37, v19
	v_min_i32_e32 v23, v23, v25
	v_min_i32_e32 v19, v37, v19
	v_min_i32_e32 v18, v18, v21
	v_max_i32_e32 v25, v44, v82
	v_min_i32_e32 v33, v33, v36
	v_min_i32_e32 v29, v30, v28
	v_min_i32_e32 v49, v35, v27
	v_min_i32_e32 v22, v22, v34
	v_max_i32_e32 v21, v19, v18
	v_max_i32_e32 v36, v25, v33
	v_max_i32_e32 v78, v32, v43
	v_min_i32_e32 v79, v29, v49
	v_max_i32_e32 v34, v20, v22
	v_min_i32_e32 v20, v20, v22
	v_max_i32_e32 v37, v21, v36
	v_min_i32_e32 v32, v32, v43
	v_max_i32_e32 v80, v78, v79
	v_max_i32_e32 v42, v31, v34
	v_min_i32_e32 v78, v78, v79
	v_min_i32_e32 v31, v31, v34
	v_max_i32_e32 v22, v23, v20
	v_max_i32_e32 v43, v37, v32
	v_min_i32_e32 v18, v19, v18
	v_min_i32_e32 v19, v25, v33
	v_min_i32_e32 v20, v23, v20
	v_min_i32_e32 v23, v37, v32
	v_max_i32_e32 v28, v30, v28
	v_max_i32_e32 v27, v35, v27
	v_min_i32_e32 v124, v44, v82
	v_min_i32_e32 v45, v80, v42
	v_max_i32_e32 v34, v78, v31
	v_max_i32_e32 v44, v22, v43
	v_min_i32_e32 v31, v78, v31
	v_max_i32_e32 v25, v18, v19
	v_min_i32_e32 v21, v21, v36
	v_min_i32_e32 v32, v20, v23
	v_max_i32_e32 v29, v29, v49
	v_min_i32_e32 v30, v28, v27
	v_min_i32_e32 v22, v22, v43
	v_max_i32_e32 v20, v20, v23
	v_min_i32_e32 v79, v45, v34
	v_max_i32_e32 v78, v44, v31
	v_max_i32_e32 v33, v25, v21
	v_max_i32_e32 v37, v80, v42
	v_min_i32_e32 v35, v29, v30
	v_min_i32_e32 v31, v44, v31
	v_max_i32_e32 v23, v22, v20
	v_min_i32_e32 v81, v79, v78
	v_max_i32_e32 v36, v33, v32
	v_max_i32_e32 v42, v37, v35
	v_min_i32_e32 v21, v25, v21
	v_max_i32_e32 v25, v45, v34
	v_min_i32_e32 v43, v31, v23
	v_max_i32_e32 v27, v28, v27
	v_min_i32_e32 v18, v18, v19
	v_min_i32_e32 v20, v22, v20
	v_min_i32_e32 v32, v33, v32
	v_min_i32_e32 v33, v37, v35
	v_max3_i32 v124, v127, v129, v124
	v_max3_i32 v69, v69, v75, v81
	v_max3_i32 v36, v131, v67, v36
	v_max3_i32 v42, v71, v73, v42
	v_max3_i32 v21, v128, v130, v21
	v_max3_i32 v25, v74, v70, v25
	v_max3_i32 v43, v66, v68, v43
	v_max3_i32 v27, v72, v76, v27
	v_max_i32_e32 v18, v77, v18
	v_max3_i32 v19, v41, v79, v78
	v_max_i32_e32 v20, v39, v20
	v_max3_i32 v22, v47, v29, v30
	v_max_i32_e32 v32, v38, v32
	v_max_i32_e32 v33, v46, v33
	v_max3_i32 v23, v40, v31, v23
	v_max3_i32 v24, v48, v24, v26
	v_min_i32_e32 v49, v36, v42
	v_min_i32_e32 v34, v21, v25
	v_min_i32_e32 v41, v18, v19
	v_min_i32_e32 v29, v20, v22
	v_min_i32_e32 v26, v23, v24
	v_max_i32_e32 v39, v124, v69
	v_max_i32_e32 v36, v36, v42
	v_max_i32_e32 v21, v21, v25
	v_max_i32_e32 v25, v43, v27
; __device__ __forceinline__ void route_task(int task, int tl0, const bf16* QP  , const LAS bf16* KHL, LAS unsigned short* EL, LAS float* GL, int lane) {
;     ...
;         { const unsigned h4 = 4u * (unsigned)hi;
; #pragma unroll
;           for (int i = 0; i < 16; ++i) cur[i] -= (int)h4; }
;         int oth[16];
; #pragma unroll
;         for (int i = 0; i < 16; ++i) oth[i] = __shfl_xor(cur[i], 32);
;         merge16_desc(cur, oth);
; #pragma unroll
;         for (int i = 0; i < 16; ++i) top[half][i] = cur[i];
;     }
;     unsigned P1[4], P2[4];
; #pragma unroll
;     for (int q = 0; q < 4; ++q) { P1[q] = 0u; P2[q] = 0u;
; #pragma unroll
;         for (int s = 0; s < 4; ++s) { P1[q] |= (127u - ((unsigned)top[0][4 * q + s] & 127u)) << (8 * s); P2[q] |= (127u - ((unsigned)top[1][4 * q + s] & 127u)) << (8 * s); } }
	v_max_i32_e32 v18, v18, v19
	v_max_i32_e32 v19, v20, v22
	v_max_i32_e32 v22, v32, v33
	v_max_i32_e32 v23, v23, v24
	v_min_i32_e32 v28, v43, v27
	v_max_i32_e32 v40, v39, v36
	v_max_i32_e32 v27, v21, v25
	v_max_i32_e32 v20, v18, v19
	v_max_i32_e32 v24, v22, v23
	v_min_i32_e32 v35, v32, v33
	v_max_i32_e32 v42, v40, v27
	v_max_i32_e32 v32, v20, v24
	v_min_i32_e32 v27, v40, v27
	v_min_i32_e32 v20, v20, v24
	v_max_i32_e32 v24, v27, v20
	v_min_i32_e32 v20, v27, v20
	v_min_i32_e32 v27, v39, v36
	v_min_i32_e32 v21, v21, v25
	v_min_i32_e32 v18, v18, v19
	v_min_i32_e32 v19, v22, v23
	v_min_i32_e32 v75, v124, v69
	v_max_i32_e32 v25, v27, v21
	v_max_i32_e32 v22, v18, v19
	v_min_i32_e32 v21, v27, v21
	v_min_i32_e32 v18, v18, v19
	v_min_i32_e32 v44, v34, v28
	v_min_i32_e32 v31, v35, v26
	v_max_i32_e32 v23, v25, v22
	v_min_i32_e32 v22, v25, v22
	v_max_i32_e32 v19, v21, v18
	v_min_i32_e32 v18, v21, v18
	v_max_i32_e32 v21, v75, v49
	v_max_i32_e32 v25, v34, v28
	v_max_i32_e32 v28, v41, v29
	v_max_i32_e32 v26, v35, v26
	v_min_i32_e32 v67, v75, v49
	v_min_i32_e32 v30, v41, v29
	v_max_i32_e32 v27, v21, v25
	v_min_i32_e32 v21, v21, v25
	v_min_i32_e32 v25, v28, v26
	v_min_i32_e32 v45, v67, v44
	v_min_i32_e32 v37, v30, v31
	v_max_i32_e32 v29, v28, v26
	v_max_i32_e32 v26, v21, v25
	v_min_i32_e32 v21, v21, v25
	v_max_i32_e32 v25, v67, v44
	v_max_i32_e32 v28, v30, v31
	v_min_i32_e32 v38, v45, v37
	v_max_i32_e32 v33, v42, v32
	v_min_i32_e32 v32, v42, v32
	v_max_i32_e32 v34, v27, v29
	v_min_i32_e32 v27, v27, v29
	v_max_i32_e32 v29, v25, v28
	v_min_i32_e32 v25, v25, v28
	v_max_i32_e32 v28, v45, v37
	v_sub_u32_e32 v30, v33, v87
	v_sub_u32_e32 v31, v32, v87
	v_sub_u32_e32 v24, v24, v87
	v_sub_u32_e32 v20, v20, v87
	v_sub_u32_e32 v23, v23, v87
	v_sub_u32_e32 v22, v22, v87
	v_sub_u32_e32 v19, v19, v87
	v_sub_u32_e32 v18, v18, v87
	v_sub_u32_e32 v32, v34, v87
	v_sub_u32_e32 v27, v27, v87
	v_sub_u32_e32 v26, v26, v87
	v_sub_u32_e32 v21, v21, v87
	v_sub_u32_e32 v29, v29, v87
	v_sub_u32_e32 v25, v25, v87
	v_sub_u32_e32 v28, v28, v87
	v_sub_u32_e32 v33, v38, v87
	ds_bpermute_b32 v34, v123, v30
	ds_bpermute_b32 v35, v123, v31
	ds_bpermute_b32 v36, v123, v24
	ds_bpermute_b32 v37, v123, v20
	ds_bpermute_b32 v38, v123, v23
	ds_bpermute_b32 v39, v123, v22
	ds_bpermute_b32 v40, v123, v19
	ds_bpermute_b32 v41, v123, v18
	ds_bpermute_b32 v42, v123, v32
	ds_bpermute_b32 v43, v123, v27
	ds_bpermute_b32 v44, v123, v26
	ds_bpermute_b32 v45, v123, v33
	ds_bpermute_b32 v46, v123, v28
	ds_bpermute_b32 v47, v123, v25
	ds_bpermute_b32 v48, v123, v29
	ds_bpermute_b32 v49, v123, v21
	s_waitcnt lgkmcnt(4)
	v_max_i32_e32 v30, v30, v45
	s_waitcnt lgkmcnt(3)
	v_max_i32_e32 v31, v31, v46
	s_waitcnt lgkmcnt(2)
	v_max_i32_e32 v24, v24, v47
	s_waitcnt lgkmcnt(1)
	v_max_i32_e32 v20, v20, v48
	s_waitcnt lgkmcnt(0)
	v_max_i32_e32 v23, v23, v49
	v_max_i32_e32 v22, v22, v44
	v_max_i32_e32 v19, v19, v43
	v_max_i32_e32 v18, v18, v42
	v_max_i32_e32 v32, v32, v41
	v_max_i32_e32 v27, v27, v40
	v_max_i32_e32 v26, v26, v39
	v_max_i32_e32 v21, v21, v38
	v_max_i32_e32 v29, v29, v37
	v_max_i32_e32 v25, v25, v36
	v_max_i32_e32 v28, v28, v35
	v_max_i32_e32 v33, v33, v34
	v_max_i32_e32 v34, v30, v32
	v_min_i32_e32 v30, v30, v32
	v_max_i32_e32 v32, v31, v27
	v_min_i32_e32 v27, v31, v27
	v_max_i32_e32 v31, v24, v26
	v_min_i32_e32 v24, v24, v26
	v_max_i32_e32 v26, v20, v21
	v_min_i32_e32 v20, v20, v21
	v_max_i32_e32 v21, v23, v29
	v_min_i32_e32 v23, v23, v29
	v_max_i32_e32 v29, v22, v25
	v_min_i32_e32 v22, v22, v25
	v_max_i32_e32 v25, v19, v28
	v_min_i32_e32 v19, v19, v28
	v_max_i32_e32 v28, v18, v33
	v_min_i32_e32 v18, v18, v33
	v_max_i32_e32 v33, v34, v21
	v_min_i32_e32 v21, v34, v21
	v_max_i32_e32 v34, v32, v29
	v_min_i32_e32 v29, v32, v29
	v_max_i32_e32 v32, v31, v25
	v_min_i32_e32 v25, v31, v25
	v_max_i32_e32 v31, v26, v28
	v_min_i32_e32 v26, v26, v28
	v_max_i32_e32 v28, v30, v23
	v_min_i32_e32 v23, v30, v23
	v_max_i32_e32 v30, v27, v22
	v_min_i32_e32 v22, v27, v22
	v_max_i32_e32 v27, v24, v19
	v_min_i32_e32 v19, v24, v19
	v_max_i32_e32 v24, v20, v18
	v_min_i32_e32 v18, v20, v18
	v_max_i32_e32 v20, v33, v32
	v_min_i32_e32 v32, v33, v32
	v_max_i32_e32 v33, v34, v31
	v_min_i32_e32 v31, v34, v31
	v_max_i32_e32 v34, v21, v25
	v_min_i32_e32 v21, v21, v25
	v_max_i32_e32 v25, v29, v26
	v_min_i32_e32 v29, v29, v26
	v_max_i32_e32 v35, v28, v27
	v_min_i32_e32 v27, v28, v27
	v_max_i32_e32 v28, v30, v24
	v_min_i32_e32 v24, v30, v24
	v_max_i32_e32 v30, v23, v19
	v_min_i32_e32 v19, v23, v19
	v_max_i32_e32 v23, v22, v18
	v_min_i32_e32 v18, v22, v18
	v_max_i32_e32 v26, v20, v33
	v_min_i32_e32 v33, v20, v33
	v_lshlrev_b32_e32 v20, 8, v65
	v_lshlrev_b32_e32 v22, 16, v64
	v_max_i32_e32 v36, v32, v31
	v_max_i32_e32 v40, v19, v18
	v_min_i32_e32 v41, v19, v18
	v_and_b32_e32 v18, 0x7f, v63
	v_and_b32_e32 v20, 0x7f00, v20
	v_and_b32_e32 v22, 0x7f0000, v22
	v_max_i32_e32 v37, v21, v29
	v_min_i32_e32 v29, v21, v29
	v_lshlrev_b32_e32 v21, 8, v33
	v_or3_b32 v18, v20, v18, v22
	v_lshlrev_b32_e32 v20, 16, v36
	v_and_b32_e32 v19, 0x7f, v26
	v_and_b32_e32 v21, 0x7f00, v21
	v_and_b32_e32 v20, 0x7f0000, v20
	v_or3_b32 v20, v21, v19, v20
	v_lshlrev_b32_e32 v19, 24, v62
	v_min_i32_e32 v31, v32, v31
	v_and_b32_e32 v19, 0x7f000000, v19
	v_bitop3_b32 v19, v18, s68, v19 bitop3:0x36
	v_lshlrev_b32_e32 v18, 24, v31
	v_max_i32_e32 v38, v35, v28
	v_min_i32_e32 v28, v35, v28
	v_max_i32_e32 v35, v27, v24
	v_min_i32_e32 v27, v27, v24
	v_and_b32_e32 v18, 0x7f000000, v18
	v_lshlrev_b32_e32 v22, 8, v60
	v_lshlrev_b32_e32 v24, 16, v59
	v_max_i32_e32 v32, v34, v25
	v_min_i32_e32 v34, v34, v25
	v_bitop3_b32 v18, v20, s68, v18 bitop3:0x36
	v_and_b32_e32 v20, 0x7f, v61
; __device__ __forceinline__ void route_task(int task, int tl0, const bf16* QP  , const LAS bf16* KHL, LAS unsigned short* EL, LAS float* GL, int lane) {
;     ...
;     unsigned P1[4], P2[4];
; #pragma unroll
;     for (int q = 0; q < 4; ++q) { P1[q] = 0u; P2[q] = 0u;
; #pragma unroll
;         for (int s = 0; s < 4; ++s) { P1[q] |= (127u - ((unsigned)top[0][4 * q + s] & 127u)) << (8 * s); P2[q] |= (127u - ((unsigned)top[1][4 * q + s] & 127u)) << (8 * s); } }
;     int bk[16];
;     {
;         int hi2 = hi; asm volatile("" : "+v"(hi2));
;         const bool h1 = hi2 != 0;
;         constexpr int A1[16] = {1, 1, 1, 1, 1, 1, 1, 1, 2, 2, 2, 2, 2, 3, 3, 3}, B1[16] = {0, 1, 2, 3, 4, 5, 6, 7, 0, 1, 2, 3, 4, 0, 1, 2};
; #pragma unroll
;         for (int i = 0; i < 16; ++i) { const float ta = __int_as_float(h1 ? top[0][A1[i]] : top[0][0]), tb = __int_as_float(h1 ? top[1][B1[i]] : top[1][i]); const unsigned code = h1 ? (unsigned)(A1[i] * 16 + B1[i]) : (unsigned)i;
;             bk[i] = (int)((__float_as_uint(ta + tb) | 255u) - code); }
;         sort16_desc(bk);
	v_and_b32_e32 v22, 0x7f00, v22
	v_and_b32_e32 v24, 0x7f0000, v24
	v_max_i32_e32 v39, v30, v23
	v_min_i32_e32 v30, v30, v23
	v_lshlrev_b32_e32 v23, 8, v34
	v_or3_b32 v20, v22, v20, v24
	v_lshlrev_b32_e32 v22, 16, v37
	v_and_b32_e32 v21, 0x7f, v32
	v_and_b32_e32 v23, 0x7f00, v23
	v_and_b32_e32 v22, 0x7f0000, v22
	v_or3_b32 v22, v23, v21, v22
	v_lshlrev_b32_e32 v21, 24, v57
	v_and_b32_e32 v21, 0x7f000000, v21
	v_bitop3_b32 v21, v20, s68, v21 bitop3:0x36
	v_lshlrev_b32_e32 v20, 24, v29
	v_and_b32_e32 v20, 0x7f000000, v20
	v_lshlrev_b32_e32 v24, 8, v58
	v_lshlrev_b32_e32 v42, 16, v56
	v_bitop3_b32 v20, v22, s68, v20 bitop3:0x36
	v_and_b32_e32 v22, 0x7f, v55
	v_and_b32_e32 v24, 0x7f00, v24
	v_and_b32_e32 v42, 0x7f0000, v42
	v_lshlrev_b32_e32 v25, 8, v28
	v_or3_b32 v22, v24, v22, v42
	v_lshlrev_b32_e32 v24, 16, v35
	v_and_b32_e32 v23, 0x7f, v38
	v_and_b32_e32 v25, 0x7f00, v25
	v_and_b32_e32 v24, 0x7f0000, v24
	v_or3_b32 v24, v25, v23, v24
	v_lshlrev_b32_e32 v23, 24, v54
	v_and_b32_e32 v23, 0x7f000000, v23
	v_bitop3_b32 v23, v22, s68, v23 bitop3:0x36
	v_lshlrev_b32_e32 v22, 24, v27
	v_and_b32_e32 v22, 0x7f000000, v22
	v_lshlrev_b32_e32 v42, 8, v52
	v_lshlrev_b32_e32 v44, 16, v51
	v_bitop3_b32 v22, v24, s68, v22 bitop3:0x36
	v_and_b32_e32 v24, 0x7f, v53
	v_and_b32_e32 v42, 0x7f00, v42
	v_and_b32_e32 v44, 0x7f0000, v44
	v_lshlrev_b32_e32 v43, 8, v30
	v_or3_b32 v24, v42, v24, v44
	v_lshlrev_b32_e32 v42, 16, v40
	v_and_b32_e32 v25, 0x7f, v39
	v_and_b32_e32 v43, 0x7f00, v43
	v_and_b32_e32 v42, 0x7f0000, v42
	v_or3_b32 v42, v43, v25, v42
	v_lshlrev_b32_e32 v25, 24, v50
	v_and_b32_e32 v25, 0x7f000000, v25
	v_bitop3_b32 v25, v24, s68, v25 bitop3:0x36
	v_lshlrev_b32_e32 v24, 24, v41
	v_and_b32_e32 v24, 0x7f000000, v24
	v_bitop3_b32 v24, v42, s68, v24 bitop3:0x36
	v_mov_b32_e32 v42, v86
	v_add_f32_e32 v55, v55, v26
	v_cmp_eq_u32_e32 vcc, 0, v42
	v_add_f32_e32 v56, v56, v26
	v_add_f32_e32 v54, v54, v26
	v_cndmask_b32_e32 v42, v65, v63, vcc
	v_add_f32_e32 v44, v42, v26
	v_cndmask_b32_e64 v43, -16, 0, vcc
	v_or_b32_e32 v44, 0xff, v44
	v_add_f32_e32 v45, v42, v33
	v_add_u32_e32 v43, v44, v43
	v_cndmask_b32_e64 v44, v99, -1, vcc
	v_or_b32_e32 v45, 0xff, v45
	v_add_f32_e32 v46, v42, v36
	v_add_u32_e32 v44, v45, v44
	v_cndmask_b32_e64 v45, v100, -2, vcc
	v_or_b32_e32 v46, 0xff, v46
	v_add_f32_e32 v47, v42, v31
	v_add_u32_e32 v45, v46, v45
	v_cndmask_b32_e64 v46, v101, -3, vcc
	v_or_b32_e32 v47, 0xff, v47
	v_add_f32_e32 v48, v42, v32
	v_add_u32_e32 v46, v47, v46
	v_cndmask_b32_e64 v47, v102, -4, vcc
	v_or_b32_e32 v48, 0xff, v48
	v_add_f32_e32 v34, v42, v34
	v_add_f32_e32 v37, v42, v37
	v_add_f32_e32 v29, v42, v29
	v_cndmask_b32_e32 v42, v64, v63, vcc
	v_cndmask_b32_e32 v32, v32, v39, vcc
	v_add_u32_e32 v47, v48, v47
	v_cndmask_b32_e64 v48, v103, -5, vcc
	v_or_b32_e32 v34, 0xff, v34
	v_add_f32_e32 v32, v42, v32
	v_add_u32_e32 v34, v34, v48
	v_cndmask_b32_e64 v48, v104, -6, vcc
	v_or_b32_e32 v37, 0xff, v37
	v_cndmask_b32_e32 v38, v26, v38, vcc
	v_cndmask_b32_e64 v39, v116, -12, vcc
	v_or_b32_e32 v32, 0xff, v32
	v_add_u32_e32 v37, v37, v48
	v_cndmask_b32_e64 v48, v105, -7, vcc
	v_or_b32_e32 v29, 0xff, v29
	v_add_f32_e32 v38, v42, v38
	v_cndmask_b32_e32 v28, v33, v28, vcc
	v_add_u32_e32 v32, v32, v39
	v_cndmask_b32_e32 v39, v62, v63, vcc
	v_cndmask_b32_e32 v30, v26, v30, vcc
	v_add_u32_e32 v29, v29, v48
	v_cndmask_b32_e64 v48, v106, -8, vcc
	v_or_b32_e32 v38, 0xff, v38
	v_add_f32_e32 v28, v42, v28
	v_cndmask_b32_e32 v35, v36, v35, vcc
	v_cndmask_b32_e32 v27, v31, v27, vcc
	v_add_f32_e32 v30, v39, v30
	v_cndmask_b32_e32 v40, v33, v40, vcc
	v_add_u32_e32 v38, v38, v48
	v_cndmask_b32_e64 v48, v107, -9, vcc
	v_or_b32_e32 v28, 0xff, v28
	v_add_f32_e32 v35, v42, v35
	v_add_f32_e32 v27, v42, v27
	v_cndmask_b32_e64 v42, v117, -13, vcc
	v_or_b32_e32 v30, 0xff, v30
	v_add_f32_e32 v40, v39, v40
	v_cndmask_b32_e32 v41, v36, v41, vcc
	v_add_u32_e32 v28, v28, v48
	v_cndmask_b32_e64 v48, v114, -10, vcc
	v_or_b32_e32 v35, 0xff, v35
	v_add_u32_e32 v30, v30, v42
	v_cndmask_b32_e64 v42, v118, -14, vcc
	v_or_b32_e32 v40, 0xff, v40
	v_add_f32_e32 v39, v39, v41
	v_add_u32_e32 v35, v35, v48
	v_cndmask_b32_e64 v48, v115, -11, vcc
	v_or_b32_e32 v27, 0xff, v27
	v_add_u32_e32 v40, v40, v42
	v_cndmask_b32_e64 v42, v119, -15, vcc
	v_or_b32_e32 v39, 0xff, v39
	v_add_u32_e32 v27, v27, v48
	v_add_u32_e32 v39, v39, v42
	v_max_i32_e32 v41, v43, v30
	v_min_i32_e32 v30, v43, v30
	v_max_i32_e32 v42, v44, v32
	v_min_i32_e32 v32, v44, v32
	v_max_i32_e32 v43, v45, v39
	v_min_i32_e32 v39, v45, v39
	v_max_i32_e32 v44, v46, v40
	v_min_i32_e32 v40, v46, v40
	v_max_i32_e32 v45, v47, v38
	v_min_i32_e32 v38, v47, v38
	v_max_i32_e32 v46, v34, v37
	v_min_i32_e32 v34, v34, v37
	v_max_i32_e32 v37, v29, v27
	v_min_i32_e32 v27, v29, v27
	v_max_i32_e32 v29, v28, v35
	v_min_i32_e32 v28, v28, v35
	v_max_i32_e32 v35, v41, v46
	v_min_i32_e32 v41, v41, v46
	v_max_i32_e32 v46, v42, v37
	v_min_i32_e32 v37, v42, v37
	v_max_i32_e32 v42, v43, v29
	v_min_i32_e32 v29, v43, v29
	v_max_i32_e32 v43, v44, v45
	v_min_i32_e32 v44, v44, v45
	v_max_i32_e32 v45, v34, v30
	v_min_i32_e32 v30, v34, v30
	v_max_i32_e32 v34, v38, v40
	v_min_i32_e32 v38, v38, v40
	v_max_i32_e32 v40, v28, v39
	v_min_i32_e32 v28, v28, v39
	v_max_i32_e32 v39, v27, v32
	v_min_i32_e32 v27, v27, v32
	v_max_i32_e32 v32, v35, v46
	v_min_i32_e32 v35, v35, v46
	v_max_i32_e32 v46, v42, v43
	v_min_i32_e32 v42, v42, v43
	v_max_i32_e32 v43, v44, v41
	v_min_i32_e32 v41, v44, v41
	v_max_i32_e32 v44, v45, v34
	v_min_i32_e32 v34, v45, v34
	v_max_i32_e32 v45, v37, v29
	v_min_i32_e32 v29, v37, v29
	v_max_i32_e32 v37, v40, v39
	v_min_i32_e32 v39, v40, v39
	v_max_i32_e32 v40, v27, v30
; #define CE_(a, b) ce_desc(v[a], v[b])
; #define CAND(a, b) (int)((__float_as_uint(__int_as_float(top[0][a]) + __int_as_float(top[1][b])) | 255u) - (unsigned)((a) * 16 + (b)))
; __device__ __forceinline__ void sort16_desc(int (&v)[16]) {
;     ...
;     CE_(0,13); CE_(1,12); CE_(2,15); CE_(3,14); CE_(4,8); CE_(5,6); CE_(7,11); CE_(9,10);
;     CE_(0,5); CE_(1,7); CE_(2,9); CE_(3,4); CE_(6,13); CE_(8,14); CE_(10,15); CE_(11,12);
;     CE_(0,1); CE_(2,3); CE_(4,5); CE_(6,8); CE_(7,9); CE_(10,11); CE_(12,13); CE_(14,15);
;     CE_(0,2); CE_(1,3); CE_(4,10); CE_(5,11); CE_(6,7); CE_(8,9); CE_(12,14); CE_(13,15);
;     CE_(1,2); CE_(3,12); CE_(4,6); CE_(5,7); CE_(8,10); CE_(9,11); CE_(13,14);
;     CE_(1,4); CE_(2,6); CE_(5,8); CE_(7,10); CE_(9,13); CE_(11,14);
;     CE_(2,4); CE_(3,6); CE_(9,12); CE_(11,13);
;     CE_(3,5); CE_(6,8); CE_(7,9); CE_(10,12);
;     CE_(3,4); CE_(5,6); CE_(7,8); CE_(9,10); CE_(11,12);
;     CE_(6,7); CE_(8,9);
;     ...
; }
; __device__ __forceinline__ void route_task(int task, int tl0, const bf16* QP  , const LAS bf16* KHL, LAS unsigned short* EL, LAS float* GL, int lane) {
;     ...
;         sort16_desc(bk);
;         int oth[16];
; #pragma unroll
;         for (int i = 0; i < 16; ++i) oth[i] = __shfl_xor(bk[i], 32);
;         merge16_desc(bk, oth);
;     }
;     ...
;     {
;         int gk[16];
;         gk[0] = CAND(3, 3); gk[1] = CAND(4, 0); gk[2] = CAND(4, 1); gk[3] = CAND(4, 2); gk[4] = CAND(5, 0); gk[5] = CAND(5, 1); gk[6] = CAND(6, 0); gk[7] = CAND(6, 1);
;         gk[8] = CAND(7, 0); gk[9] = CAND(7, 1); gk[10] = CAND(8, 0); gk[11] = CAND(9, 0); gk[12] = CAND(10, 0); gk[13] = CAND(11, 0); gk[14] = CAND(12, 0); gk[15] = CAND(13, 0);
;         sort16_desc(gk);
	v_min_i32_e32 v27, v27, v30
	v_max_i32_e32 v30, v38, v28
	v_min_i32_e32 v28, v38, v28
	v_max_i32_e32 v38, v32, v46
	v_min_i32_e32 v32, v32, v46
	v_max_i32_e32 v46, v35, v42
	v_min_i32_e32 v35, v35, v42
	v_max_i32_e32 v42, v43, v37
	v_min_i32_e32 v37, v43, v37
	v_max_i32_e32 v43, v41, v39
	v_min_i32_e32 v39, v41, v39
	v_max_i32_e32 v41, v44, v45
	v_min_i32_e32 v44, v44, v45
	v_max_i32_e32 v45, v34, v29
	v_min_i32_e32 v29, v34, v29
	v_max_i32_e32 v34, v40, v30
	v_min_i32_e32 v30, v40, v30
	v_max_i32_e32 v40, v27, v28
	v_min_i32_e32 v27, v27, v28
	v_max_i32_e32 v28, v46, v32
	v_min_i32_e32 v32, v46, v32
	v_max_i32_e32 v46, v35, v34
	v_min_i32_e32 v34, v35, v34
	v_max_i32_e32 v35, v42, v41
	v_min_i32_e32 v41, v42, v41
	v_max_i32_e32 v42, v43, v44
	v_min_i32_e32 v43, v43, v44
	v_max_i32_e32 v44, v45, v37
	v_min_i32_e32 v37, v45, v37
	v_max_i32_e32 v45, v29, v39
	v_min_i32_e32 v29, v29, v39
	v_max_i32_e32 v39, v40, v30
	v_min_i32_e32 v30, v40, v30
	v_max_i32_e32 v40, v28, v35
	v_min_i32_e32 v28, v28, v35
	v_max_i32_e32 v35, v32, v41
	v_min_i32_e32 v32, v32, v41
	v_max_i32_e32 v41, v42, v44
	v_min_i32_e32 v42, v42, v44
	v_max_i32_e32 v44, v43, v37
	v_min_i32_e32 v37, v43, v37
	v_max_i32_e32 v43, v45, v39
	v_min_i32_e32 v39, v45, v39
	v_max_i32_e32 v45, v29, v30
	v_min_i32_e32 v29, v29, v30
	v_max_i32_e32 v30, v35, v28
	v_min_i32_e32 v28, v35, v28
	v_max_i32_e32 v35, v46, v32
	v_min_i32_e32 v32, v46, v32
	v_max_i32_e32 v46, v43, v34
	v_min_i32_e32 v34, v43, v34
	v_max_i32_e32 v43, v45, v39
	v_min_i32_e32 v39, v45, v39
	v_max_i32_e32 v45, v35, v41
	v_min_i32_e32 v35, v35, v41
	v_max_i32_e32 v41, v32, v42
	v_min_i32_e32 v32, v32, v42
	v_max_i32_e32 v42, v44, v46
	v_min_i32_e32 v44, v44, v46
	v_max_i32_e32 v46, v37, v34
	v_min_i32_e32 v34, v37, v34
	v_max_i32_e32 v37, v45, v28
	v_min_i32_e32 v28, v45, v28
	v_max_i32_e32 v45, v35, v41
	v_min_i32_e32 v35, v35, v41
	v_max_i32_e32 v41, v42, v32
	v_min_i32_e32 v32, v42, v32
	v_max_i32_e32 v42, v44, v46
	v_min_i32_e32 v44, v44, v46
	v_max_i32_e32 v46, v43, v34
	v_min_i32_e32 v34, v43, v34
	v_max_i32_e32 v43, v35, v41
	v_min_i32_e32 v35, v35, v41
	v_max_i32_e32 v41, v32, v42
	v_min_i32_e32 v32, v32, v42
	ds_bpermute_b32 v67, v123, v41
	ds_bpermute_b32 v68, v123, v32
	ds_bpermute_b32 v69, v123, v44
	ds_bpermute_b32 v64, v123, v45
	ds_bpermute_b32 v65, v123, v43
	ds_bpermute_b32 v66, v123, v35
	s_waitcnt lgkmcnt(4)
	v_max_i32_e32 v43, v43, v68
	s_waitcnt lgkmcnt(3)
	v_max_i32_e32 v45, v45, v69
	v_max_i32_e32 v35, v35, v67
	v_add_f32_e32 v31, v62, v31
	v_add_f32_e32 v62, v61, v26
	v_add_f32_e32 v67, v61, v33
	v_add_f32_e32 v36, v61, v36
	v_add_f32_e32 v61, v60, v26
	v_add_f32_e32 v60, v60, v33
	v_add_f32_e32 v68, v59, v26
	v_add_f32_e32 v59, v59, v33
	v_add_f32_e32 v69, v57, v26
	v_add_f32_e32 v33, v57, v33
	v_add_f32_e32 v57, v58, v26
	v_add_f32_e32 v53, v53, v26
	v_add_f32_e32 v52, v52, v26
	ds_bpermute_b32 v70, v123, v27
	v_or_b32_e32 v31, 0xff, v31
	v_or_b32_e32 v62, 0xff, v62
	v_or_b32_e32 v67, 0xff, v67
	v_or_b32_e32 v36, 0xff, v36
	v_or_b32_e32 v61, 0xff, v61
	v_or_b32_e32 v60, 0xff, v60
	v_or_b32_e32 v68, 0xff, v68
	v_or_b32_e32 v59, 0xff, v59
	v_or_b32_e32 v69, 0xff, v69
	v_or_b32_e32 v33, 0xff, v33
	v_or_b32_e32 v55, 0xff, v55
	v_or_b32_e32 v57, 0xff, v57
	v_or_b32_e32 v56, 0xff, v56
	v_or_b32_e32 v54, 0xff, v54
	v_or_b32_e32 v53, 0xff, v53
	v_or_b32_e32 v52, 0xff, v52
	v_subrev_u32_e32 v31, 51, v31
	v_subrev_u32_e32 v62, 64, v62
	v_add_u32_e32 v67, 0xffffffbf, v67
	v_add_u32_e32 v36, 0xffffffbe, v36
	v_add_u32_e32 v61, 0xffffffb0, v61
	v_add_u32_e32 v60, 0xffffffaf, v60
	v_add_u32_e32 v68, 0xffffffa0, v68
	v_add_u32_e32 v59, 0xffffff9f, v59
	v_add_u32_e32 v69, 0xffffff90, v69
	v_add_u32_e32 v33, 0xffffff8f, v33
	v_add_u32_e32 v55, 0xffffff80, v55
	v_add_u32_e32 v57, 0xffffff70, v57
	v_add_u32_e32 v56, 0xffffff60, v56
	v_add_u32_e32 v54, 0xffffff50, v54
	v_add_u32_e32 v53, 0xffffff40, v53
	v_add_u32_e32 v52, 0xffffff30, v52
	ds_bpermute_b32 v42, v123, v38
	ds_bpermute_b32 v47, v123, v40
	ds_bpermute_b32 v48, v123, v30
	ds_bpermute_b32 v49, v123, v37
	ds_bpermute_b32 v63, v123, v28
	ds_bpermute_b32 v71, v123, v29
	ds_bpermute_b32 v72, v123, v39
	ds_bpermute_b32 v73, v123, v34
	ds_bpermute_b32 v74, v123, v46
	v_max_i32_e32 v58, v31, v54
	v_min_i32_e32 v31, v31, v54
	v_max_i32_e32 v54, v62, v56
	v_min_i32_e32 v56, v62, v56
	v_max_i32_e32 v62, v67, v52
	v_min_i32_e32 v52, v67, v52
	v_max_i32_e32 v67, v36, v53
	v_min_i32_e32 v36, v36, v53
	v_max_i32_e32 v53, v61, v69
	v_min_i32_e32 v61, v61, v69
	v_max_i32_e32 v69, v60, v68
	v_min_i32_e32 v60, v60, v68
	v_max_i32_e32 v68, v59, v57
	v_min_i32_e32 v57, v59, v57
	v_max_i32_e32 v59, v33, v55
	v_min_i32_e32 v33, v33, v55
	v_max_i32_e32 v55, v58, v69
	v_min_i32_e32 v58, v58, v69
	v_max_i32_e32 v69, v54, v68
	v_min_i32_e32 v54, v54, v68
	v_max_i32_e32 v68, v62, v59
	v_min_i32_e32 v59, v62, v59
	v_max_i32_e32 v62, v67, v53
	v_min_i32_e32 v53, v67, v53
	v_max_i32_e32 v67, v60, v31
	v_min_i32_e32 v31, v60, v31
	v_max_i32_e32 v60, v61, v36
	v_min_i32_e32 v36, v61, v36
	v_max_i32_e32 v61, v33, v52
	v_min_i32_e32 v33, v33, v52
	v_max_i32_e32 v52, v57, v56
	v_min_i32_e32 v56, v57, v56
	v_max_i32_e32 v57, v55, v69
	v_min_i32_e32 v55, v55, v69
	v_max_i32_e32 v69, v68, v62
	v_min_i32_e32 v62, v68, v62
	v_max_i32_e32 v68, v53, v58
	v_min_i32_e32 v53, v53, v58
	v_max_i32_e32 v58, v67, v60
	v_min_i32_e32 v60, v67, v60
	v_max_i32_e32 v67, v54, v59
	v_min_i32_e32 v54, v54, v59
	v_max_i32_e32 v59, v61, v52
	v_min_i32_e32 v52, v61, v52
	v_max_i32_e32 v61, v56, v31
	v_min_i32_e32 v31, v56, v31
	v_max_i32_e32 v56, v36, v33
	v_min_i32_e32 v33, v36, v33
	s_waitcnt lgkmcnt(9)
; #define CAND(a, b) (int)((__float_as_uint(__int_as_float(top[0][a]) + __int_as_float(top[1][b])) | 255u) - (unsigned)((a) * 16 + (b)))
; __device__ __forceinline__ void merge16_desc(int (&a)[16], const int (&b)[16]) {
; #pragma unroll
;     for (int i = 0; i < 16; ++i) a[i] = a[i] > b[15 - i] ? a[i] : b[15 - i];
; #pragma unroll
;     for (int j = 8; j > 0; j >>= 1)
; #pragma unroll
;         for (int i = 0; i < 16; ++i) { const int l = i ^ j; if (l > i) ce_desc(a[i], a[l]); }
; }
; __device__ __forceinline__ void route_task(int task, int tl0, const bf16* QP  , const LAS bf16* KHL, LAS unsigned short* EL, LAS float* GL, int lane) {
;     ...
;         sort16_desc(bk);
;         int oth[16];
; #pragma unroll
;         for (int i = 0; i < 16; ++i) oth[i] = __shfl_xor(bk[i], 32);
;         merge16_desc(bk, oth);
;     }
;     ...
;     {
;         int gk[16];
;         gk[0] = CAND(3, 3); gk[1] = CAND(4, 0); gk[2] = CAND(4, 1); gk[3] = CAND(4, 2); gk[4] = CAND(5, 0); gk[5] = CAND(5, 1); gk[6] = CAND(6, 0); gk[7] = CAND(6, 1);
;         gk[8] = CAND(7, 0); gk[9] = CAND(7, 1); gk[10] = CAND(8, 0); gk[11] = CAND(9, 0); gk[12] = CAND(10, 0); gk[13] = CAND(11, 0); gk[14] = CAND(12, 0); gk[15] = CAND(13, 0);
;         sort16_desc(gk);
;         merge16_desc(bk, gk);
;     }
	v_max_i32_e32 v38, v38, v70
	v_min_i32_e32 v36, v57, v69
	v_max_i32_e32 v70, v55, v62
	v_min_i32_e32 v55, v55, v62
	v_max_i32_e32 v62, v68, v59
	v_min_i32_e32 v59, v68, v59
	v_max_i32_e32 v68, v53, v52
	v_min_i32_e32 v52, v53, v52
	v_max_i32_e32 v53, v58, v67
	v_min_i32_e32 v58, v58, v67
	v_max_i32_e32 v67, v60, v54
	v_min_i32_e32 v54, v60, v54
	v_max_i32_e32 v60, v61, v56
	v_min_i32_e32 v56, v61, v56
	v_max_i32_e32 v61, v31, v33
	v_min_i32_e32 v31, v31, v33
	v_max_i32_e32 v33, v70, v36
	v_min_i32_e32 v36, v70, v36
	v_max_i32_e32 v70, v55, v60
	v_min_i32_e32 v55, v55, v60
	v_max_i32_e32 v60, v62, v53
	v_min_i32_e32 v53, v62, v53
	v_max_i32_e32 v62, v68, v58
	v_min_i32_e32 v58, v68, v58
	v_max_i32_e32 v68, v67, v59
	v_min_i32_e32 v59, v67, v59
	v_max_i32_e32 v67, v54, v52
	v_min_i32_e32 v52, v54, v52
	v_max_i32_e32 v54, v61, v56
	s_waitcnt lgkmcnt(3)
	v_max_i32_e32 v40, v40, v71
	s_waitcnt lgkmcnt(2)
	v_max_i32_e32 v30, v30, v72
	s_waitcnt lgkmcnt(1)
	v_max_i32_e32 v37, v37, v73
	s_waitcnt lgkmcnt(0)
	v_max_i32_e32 v28, v28, v74
	v_max_i32_e32 v41, v41, v66
	v_max_i32_e32 v32, v32, v65
	v_max_i32_e32 v44, v44, v64
	v_max_i32_e32 v46, v46, v63
	v_max_i32_e32 v34, v34, v49
	v_max_i32_e32 v39, v39, v48
	v_max_i32_e32 v29, v29, v47
	v_max_i32_e32 v27, v27, v42
	v_min_i32_e32 v56, v61, v56
	v_max_i32_e32 v61, v33, v60
	v_min_i32_e32 v33, v33, v60
	v_max_i32_e32 v60, v36, v53
	v_min_i32_e32 v36, v36, v53
	v_max_i32_e32 v53, v62, v68
	v_min_i32_e32 v62, v62, v68
	v_max_i32_e32 v68, v58, v59
	v_min_i32_e32 v58, v58, v59
	v_max_i32_e32 v59, v67, v54
	v_max_i32_e32 v42, v38, v41
	v_min_i32_e32 v38, v38, v41
	v_max_i32_e32 v41, v40, v32
	v_min_i32_e32 v32, v40, v32
	v_max_i32_e32 v40, v30, v44
	v_min_i32_e32 v30, v30, v44
	v_max_i32_e32 v44, v37, v46
	v_min_i32_e32 v37, v37, v46
	v_max_i32_e32 v46, v28, v34
	v_min_i32_e32 v28, v28, v34
	v_max_i32_e32 v34, v45, v39
	v_min_i32_e32 v39, v45, v39
	v_max_i32_e32 v45, v43, v29
	v_min_i32_e32 v29, v43, v29
	v_max_i32_e32 v43, v35, v27
	v_min_i32_e32 v27, v35, v27
	v_min_i32_e32 v54, v67, v54
	v_max_i32_e32 v67, v52, v56
	v_max_i32_e32 v71, v70, v36
	v_min_i32_e32 v36, v70, v36
	v_max_i32_e32 v70, v59, v55
	v_min_i32_e32 v55, v59, v55
	v_max_i32_e32 v35, v42, v46
	v_min_i32_e32 v42, v42, v46
	v_max_i32_e32 v46, v41, v34
	v_min_i32_e32 v34, v41, v34
	v_max_i32_e32 v41, v40, v45
	v_min_i32_e32 v40, v40, v45
	v_max_i32_e32 v45, v44, v43
	v_min_i32_e32 v43, v44, v43
	v_max_i32_e32 v44, v38, v28
	v_min_i32_e32 v28, v38, v28
	v_max_i32_e32 v38, v32, v39
	v_min_i32_e32 v32, v32, v39
	v_max_i32_e32 v39, v30, v29
	v_min_i32_e32 v29, v30, v29
	v_max_i32_e32 v30, v37, v27
	v_min_i32_e32 v27, v37, v27
	v_min_i32_e32 v52, v52, v56
	v_min_i32_e32 v56, v60, v33
	v_max_i32_e32 v59, v67, v54
	v_min_i32_e32 v54, v67, v54
	v_max_i32_e32 v67, v71, v53
	v_min_i32_e32 v53, v71, v53
	v_max_i32_e32 v71, v36, v62
	v_min_i32_e32 v36, v36, v62
	v_max_i32_e32 v62, v68, v70
	v_min_i32_e32 v68, v68, v70
	v_max_i32_e32 v70, v58, v55
	v_max_i32_e32 v37, v35, v41
	v_min_i32_e32 v35, v35, v41
	v_max_i32_e32 v41, v46, v45
	v_min_i32_e32 v45, v46, v45
	v_max_i32_e32 v46, v42, v40
	v_min_i32_e32 v40, v42, v40
	v_max_i32_e32 v42, v34, v43
	v_min_i32_e32 v34, v34, v43
	v_max_i32_e32 v43, v44, v39
	v_min_i32_e32 v39, v44, v39
	v_max_i32_e32 v44, v38, v30
	v_min_i32_e32 v30, v38, v30
	v_max_i32_e32 v38, v28, v29
	v_min_i32_e32 v28, v28, v29
	v_max_i32_e32 v29, v32, v27
	v_min_i32_e32 v27, v32, v27
	v_min_i32_e32 v55, v58, v55
	v_max_i32_e32 v58, v67, v56
	v_min_i32_e32 v56, v67, v56
	v_max_i32_e32 v67, v53, v71
	v_min_i32_e32 v53, v53, v71
	v_max_i32_e32 v71, v62, v36
	v_min_i32_e32 v36, v62, v36
	v_max_i32_e32 v62, v68, v70
	v_min_i32_e32 v32, v37, v41
	v_min_i32_e32 v47, v35, v45
	v_min_i32_e32 v48, v46, v42
	v_min_i32_e32 v49, v40, v34
	v_min_i32_e32 v63, v43, v44
	v_min_i32_e32 v64, v39, v30
	v_min_i32_e32 v65, v38, v29
	v_min_i32_e32 v66, v28, v27
	v_min_i32_e32 v68, v68, v70
	v_max_i32_e32 v70, v59, v55
	v_min_i32_e32 v55, v59, v55
	v_min_i32_e32 v59, v53, v71
	v_min_i32_e32 v72, v36, v62
	v_max3_i32 v31, v37, v41, v31
	v_max_i32_e32 v32, v32, v52
	v_max3_i32 v35, v35, v45, v54
	v_max_i32_e32 v37, v47, v55
	v_max3_i32 v41, v46, v42, v70
	v_max_i32_e32 v42, v48, v68
	v_max3_i32 v34, v40, v34, v72
	v_max3_i32 v36, v49, v36, v62
	v_max3_i32 v40, v43, v44, v59
	v_max3_i32 v43, v63, v53, v71
	v_max3_i32 v30, v39, v30, v67
	v_max_i32_e32 v39, v64, v56
	v_max3_i32 v29, v38, v29, v58
	v_max3_i32 v33, v65, v60, v33
	v_max3_i32 v27, v28, v27, v61
	v_max3_i32 v28, v66, v57, v69
	v_max_i32_e32 v38, v31, v40
	v_min_i32_e32 v31, v31, v40
	v_max_i32_e32 v40, v32, v43
	v_min_i32_e32 v32, v32, v43
	v_max_i32_e32 v43, v35, v30
	v_min_i32_e32 v30, v35, v30
	v_max_i32_e32 v35, v37, v39
	v_min_i32_e32 v37, v37, v39
	v_max_i32_e32 v39, v41, v29
	v_min_i32_e32 v29, v41, v29
	v_max_i32_e32 v41, v42, v33
	v_min_i32_e32 v33, v42, v33
	v_max_i32_e32 v42, v34, v27
	v_min_i32_e32 v27, v34, v27
	v_max_i32_e32 v34, v36, v28
	v_min_i32_e32 v28, v36, v28
	v_max_i32_e32 v36, v38, v39
	v_min_i32_e32 v38, v38, v39
	v_max_i32_e32 v39, v40, v41
	v_min_i32_e32 v40, v40, v41
	v_max_i32_e32 v41, v43, v42
	v_min_i32_e32 v42, v43, v42
	v_max_i32_e32 v43, v35, v34
	v_min_i32_e32 v34, v35, v34
	v_max_i32_e32 v35, v31, v29
	v_min_i32_e32 v29, v31, v29
	v_max_i32_e32 v31, v32, v33
	v_min_i32_e32 v32, v32, v33
	v_max_i32_e32 v33, v30, v27
	v_min_i32_e32 v27, v30, v27
	v_max_i32_e32 v30, v37, v28
	v_min_i32_e32 v28, v37, v28
	v_max_i32_e32 v37, v36, v41
	v_min_i32_e32 v36, v36, v41
	v_max_i32_e32 v41, v39, v43
	v_min_i32_e32 v39, v39, v43
	v_max_i32_e32 v43, v38, v42
	v_min_i32_e32 v38, v38, v42
; #define CAND(a, b) (int)((__float_as_uint(__int_as_float(top[0][a]) + __int_as_float(top[1][b])) | 255u) - (unsigned)((a) * 16 + (b)))
; __device__ __forceinline__ void route_task(int task, int tl0, const bf16* QP  , const LAS bf16* KHL, LAS unsigned short* EL, LAS float* GL, int lane) {
;     ...
;     {
;         const int c14 = CAND(14, 0), c15 = CAND(15, 0);
;         const int n14 = max(bk[14], c14), n15 = max(min(bk[14], c14), max(bk[15], c15));
;         bk[14] = n14; bk[15] = n15;
;     }
;     ...
;     int my[8];
; #pragma unroll
;     for (int i = 0; i < 8; ++i) { int lo_ = bk[i], hi_ = bk[8 + i]; asm volatile("" : "+v"(lo_), "+v"(hi_)); my[i] = hi ? hi_ : lo_; }
;     int bv[8];
; #pragma unroll
;     for (int i = 0; i < 8; ++i) {
;         const unsigned cd = 255u - ((unsigned)my[i] & 255u), ca = cd >> 4, cb = cd & 15u;
;         const unsigned wa = (ca >> 2) == 0u ? P1[0] : (ca >> 2) == 1u ? P1[1] : (ca >> 2) == 2u ? P1[2] : P1[3];
;         const unsigned wb = (cb >> 2) == 0u ? P2[0] : (cb >> 2) == 1u ? P2[1] : (cb >> 2) == 2u ? P2[2] : P2[3];
;         bv[i] = (int)((((wa >> (8u * (ca & 3u))) & 255u) << 7) | ((wb >> (8u * (cb & 3u))) & 255u));
;     }
	v_max_i32_e32 v42, v40, v34
	v_min_i32_e32 v34, v40, v34
	v_max_i32_e32 v40, v35, v33
	v_min_i32_e32 v33, v35, v33
	v_max_i32_e32 v35, v31, v30
	v_min_i32_e32 v30, v31, v30
	v_max_i32_e32 v31, v29, v27
	v_min_i32_e32 v27, v29, v27
	v_max_i32_e32 v29, v32, v28
	v_min_i32_e32 v28, v32, v28
	v_max_i32_e32 v32, v37, v41
	v_min_i32_e32 v37, v37, v41
	v_max_i32_e32 v41, v36, v39
	v_min_i32_e32 v36, v36, v39
	v_max_i32_e32 v39, v43, v42
	v_min_i32_e32 v42, v43, v42
	v_max_i32_e32 v43, v38, v34
	v_min_i32_e32 v34, v38, v34
	v_max_i32_e32 v38, v40, v35
	v_min_i32_e32 v35, v40, v35
	v_max_i32_e32 v40, v33, v30
	v_min_i32_e32 v30, v33, v30
	v_max_i32_e32 v33, v31, v29
	v_min_i32_e32 v29, v31, v29
	v_max_i32_e32 v31, v27, v28
	v_min_i32_e32 v27, v27, v28
	v_add_f32_e32 v28, v51, v26
	v_or_b32_e32 v28, 0xff, v28
	v_add_f32_e32 v26, v50, v26
	v_add_u32_e32 v28, 0xffffff20, v28
	v_or_b32_e32 v26, 0xff, v26
	v_add_u32_e32 v26, 0xffffff10, v26
	v_max_i32_e32 v44, v31, v28
	v_min_i32_e32 v28, v31, v28
	v_max3_i32 v26, v28, v27, v26
	v_mov_b32_e32 v27, v32
	s_nop 0
	v_cndmask_b32_e64 v27, v38, v27, s[6:7]
	v_not_b32_e32 v28, v27
	v_bfe_u32 v45, v28, 6, 2
	v_cmp_eq_u32_e32 vcc, 2, v45
	v_cndmask_b32_e64 v34, v26, v34, s[6:7]
	v_bitop3_b32 v26, v27, s3, v27 bitop3:0xc
	v_cndmask_b32_e32 v46, v25, v23, vcc
	v_cmp_eq_u32_e32 vcc, 1, v45
	v_cndmask_b32_e64 v31, v35, v37, s[6:7]
	v_not_b32_e32 v35, v31
	v_cndmask_b32_e32 v45, v46, v21, vcc
	v_cmp_gt_u32_e32 vcc, 64, v26
	v_cndmask_b32_e64 v37, v40, v41, s[6:7]
	v_cndmask_b32_e64 v41, v44, v43, s[6:7]
	v_cndmask_b32_e32 v26, v45, v19, vcc
	v_bfe_u32 v45, v28, 2, 2
	v_cmp_eq_u32_e32 vcc, 2, v45
	v_bitop3_b32 v44, v27, 15, v27 bitop3:0xc
	v_bfe_u32 v47, v35, 6, 2
	v_cndmask_b32_e32 v46, v24, v22, vcc
	v_cmp_eq_u32_e32 vcc, 1, v45
	v_not_b32_e32 v38, v37
	v_bfe_u32 v49, v38, 6, 2
	v_cndmask_b32_e32 v45, v46, v20, vcc
	v_cmp_gt_u32_e32 vcc, 4, v44
	v_bitop3_b32 v46, v31, 15, v31 bitop3:0xc
	v_cndmask_b32_e64 v30, v30, v36, s[6:7]
	v_cndmask_b32_e32 v44, v45, v18, vcc
	v_cmp_eq_u32_e32 vcc, 2, v47
	v_bitop3_b32 v45, v31, s3, v31 bitop3:0xc
	v_not_b32_e32 v36, v30
	v_cndmask_b32_e32 v48, v25, v23, vcc
	v_cmp_eq_u32_e32 vcc, 1, v47
	v_bfe_u32 v51, v36, 6, 2
	v_cndmask_b32_e64 v33, v33, v39, s[6:7]
	v_cndmask_b32_e32 v47, v48, v21, vcc
	v_cmp_gt_u32_e32 vcc, 64, v45
	v_not_b32_e32 v39, v33
	v_bfe_u32 v53, v39, 6, 2
	v_cndmask_b32_e32 v45, v47, v19, vcc
	v_bfe_u32 v47, v35, 2, 2
	v_cmp_eq_u32_e32 vcc, 2, v47
	v_cndmask_b32_e64 v29, v29, v42, s[6:7]
	v_not_b32_e32 v40, v29
	v_cndmask_b32_e32 v48, v24, v22, vcc
	v_cmp_eq_u32_e32 vcc, 1, v47
	v_bfe_u32 v55, v40, 6, 2
	v_not_b32_e32 v42, v41
	v_cndmask_b32_e32 v47, v48, v20, vcc
	v_cmp_gt_u32_e32 vcc, 4, v46
	v_bitop3_b32 v48, v37, 15, v37 bitop3:0xc
	v_bfe_u32 v57, v42, 6, 2
	v_cndmask_b32_e32 v46, v47, v18, vcc
	v_cmp_eq_u32_e32 vcc, 2, v49
	v_bitop3_b32 v47, v37, s3, v37 bitop3:0xc
	v_not_b32_e32 v43, v34
	v_cndmask_b32_e32 v50, v25, v23, vcc
	v_cmp_eq_u32_e32 vcc, 1, v49
	v_bfe_u32 v59, v43, 6, 2
	v_or_b32_e32 v82, s10, v88
	v_cndmask_b32_e32 v49, v50, v21, vcc
	v_cmp_gt_u32_e32 vcc, 64, v47
	s_nop 1
	v_cndmask_b32_e32 v47, v49, v19, vcc
	v_bfe_u32 v49, v38, 2, 2
	v_cmp_eq_u32_e32 vcc, 2, v49
	s_nop 1
	v_cndmask_b32_e32 v50, v24, v22, vcc
	v_cmp_eq_u32_e32 vcc, 1, v49
	s_nop 1
	v_cndmask_b32_e32 v49, v50, v20, vcc
	v_cmp_gt_u32_e32 vcc, 4, v48
	v_bitop3_b32 v50, v30, 15, v30 bitop3:0xc
	s_nop 0
	v_cndmask_b32_e32 v48, v49, v18, vcc
	v_cmp_eq_u32_e32 vcc, 2, v51
	v_bitop3_b32 v49, v30, s3, v30 bitop3:0xc
	s_nop 0
	v_cndmask_b32_e32 v52, v25, v23, vcc
	v_cmp_eq_u32_e32 vcc, 1, v51
	s_nop 1
	v_cndmask_b32_e32 v51, v52, v21, vcc
	v_cmp_gt_u32_e32 vcc, 64, v49
	s_nop 1
	v_cndmask_b32_e32 v49, v51, v19, vcc
	v_bfe_u32 v51, v36, 2, 2
	v_cmp_eq_u32_e32 vcc, 2, v51
	s_nop 1
	v_cndmask_b32_e32 v52, v24, v22, vcc
	v_cmp_eq_u32_e32 vcc, 1, v51
	s_nop 1
	v_cndmask_b32_e32 v51, v52, v20, vcc
	v_cmp_gt_u32_e32 vcc, 4, v50
	v_bitop3_b32 v52, v33, 15, v33 bitop3:0xc
	s_nop 0
	v_cndmask_b32_e32 v50, v51, v18, vcc
	v_cmp_eq_u32_e32 vcc, 2, v53
	v_bitop3_b32 v51, v33, s3, v33 bitop3:0xc
	s_nop 0
	v_cndmask_b32_e32 v54, v25, v23, vcc
	v_cmp_eq_u32_e32 vcc, 1, v53
	s_nop 1
	v_cndmask_b32_e32 v53, v54, v21, vcc
	v_cmp_gt_u32_e32 vcc, 64, v51
	s_nop 1
	v_cndmask_b32_e32 v51, v53, v19, vcc
	v_bfe_u32 v53, v39, 2, 2
	v_cmp_eq_u32_e32 vcc, 2, v53
	s_nop 1
	v_cndmask_b32_e32 v54, v24, v22, vcc
	v_cmp_eq_u32_e32 vcc, 1, v53
	s_nop 1
	v_cndmask_b32_e32 v53, v54, v20, vcc
	v_cmp_gt_u32_e32 vcc, 4, v52
	v_bitop3_b32 v54, v29, 15, v29 bitop3:0xc
	s_nop 0
	v_cndmask_b32_e32 v52, v53, v18, vcc
	v_cmp_eq_u32_e32 vcc, 2, v55
	v_bitop3_b32 v53, v29, s3, v29 bitop3:0xc
	s_nop 0
	v_cndmask_b32_e32 v56, v25, v23, vcc
	v_cmp_eq_u32_e32 vcc, 1, v55
	s_nop 1
	v_cndmask_b32_e32 v55, v56, v21, vcc
	v_cmp_gt_u32_e32 vcc, 64, v53
	s_nop 1
	v_cndmask_b32_e32 v53, v55, v19, vcc
	v_bfe_u32 v55, v40, 2, 2
	v_cmp_eq_u32_e32 vcc, 2, v55
	s_nop 1
	v_cndmask_b32_e32 v56, v24, v22, vcc
	v_cmp_eq_u32_e32 vcc, 1, v55
	s_nop 1
	v_cndmask_b32_e32 v55, v56, v20, vcc
	v_cmp_gt_u32_e32 vcc, 4, v54
	v_bitop3_b32 v56, v41, 15, v41 bitop3:0xc
	s_nop 0
	v_cndmask_b32_e32 v54, v55, v18, vcc
	v_cmp_eq_u32_e32 vcc, 2, v57
	v_bitop3_b32 v55, v41, s3, v41 bitop3:0xc
	s_nop 0
	v_cndmask_b32_e32 v58, v25, v23, vcc
	v_cmp_eq_u32_e32 vcc, 1, v57
	s_nop 1
	v_cndmask_b32_e32 v57, v58, v21, vcc
	v_cmp_gt_u32_e32 vcc, 64, v55
	s_nop 1
	v_cndmask_b32_e32 v55, v57, v19, vcc
	v_bfe_u32 v57, v42, 2, 2
	v_cmp_eq_u32_e32 vcc, 2, v57
	s_nop 1
	v_cndmask_b32_e32 v58, v24, v22, vcc
	v_cmp_eq_u32_e32 vcc, 1, v57
	s_nop 1
	v_cndmask_b32_e32 v57, v58, v20, vcc
; #define LAS __attribute__((address_space(3)))
; #define MFMA32(a, b, c) __builtin_amdgcn_mfma_f32_32x32x16_bf16((a), (b), (c), 0, 0, 0)
; __device__ __forceinline__ void route_task(int task, int tl0, const bf16* QP  , const LAS bf16* KHL, LAS unsigned short* EL, LAS float* GL, int lane) {
;     ...
;         for (int kt = 0; kt < 4; ++kt) {
;             f32x16 X;
; #pragma unroll
;             for (int i = 0; i < 16; ++i) X[i] = 8.f;
;             const LAS bf16* khp = KHL + (half * 128 + 32 * kt + r) * 72 + 8 * hi;
; #pragma unroll
;             for (int ks = 0; ks < 4; ++ks) {
;                 const bf16x8 kh = lds8(khp + 16 * ks);
;                 X = MFMA32(kh, qa[half][ks], X);
;     ...
;     for (int i = 0; i < 8; ++i) {
;         const unsigned cd = 255u - ((unsigned)my[i] & 255u), ca = cd >> 4, cb = cd & 15u;
;         const unsigned wa = (ca >> 2) == 0u ? P1[0] : (ca >> 2) == 1u ? P1[1] : (ca >> 2) == 2u ? P1[2] : P1[3];
;         const unsigned wb = (cb >> 2) == 0u ? P2[0] : (cb >> 2) == 1u ? P2[1] : (cb >> 2) == 2u ? P2[2] : P2[3];
;         bv[i] = (int)((((wa >> (8u * (ca & 3u))) & 255u) << 7) | ((wb >> (8u * (cb & 3u))) & 255u));
;     }
;     float e[8], se = 0.f;
; #pragma unroll
;     for (int i = 0; i < 8; ++i) { e[i] = __expf(__int_as_float(my[i]) - __int_as_float(bk[0])); se += e[i]; }
;     se += __shfl_xor(se, 32);
;     const float inv = 1.f / se;
;     {
;         int l2 = lane; asm volatile("" : "+v"(l2));
;         const int o2 = (tl0 + ((l2 & 31) >> 3)) * 128 + (l2 & 7) * 16 + 8 * (l2 >> 5);
;         LAS v4u* ip = (LAS v4u*)(EL + o2); typedef float f4v __attribute__((ext_vector_type(4))); LAS f4v* gp = (LAS f4v*)(GL + o2);
;         ip[0] = (v4u){(unsigned)bv[0] | ((unsigned)bv[1] << 16), (unsigned)bv[2] | ((unsigned)bv[3] << 16), (unsigned)bv[4] | ((unsigned)bv[5] << 16), (unsigned)bv[6] | ((unsigned)bv[7] << 16)};
;         gp[0] = (f4v){e[0] * inv, e[1] * inv, e[2] * inv, e[3] * inv}; gp[1] = (f4v){e[4] * inv, e[5] * inv, e[6] * inv, e[7] * inv};
;     }
	v_cmp_gt_u32_e32 vcc, 4, v56
	v_bitop3_b32 v58, v34, 15, v34 bitop3:0xc
	s_nop 0
	v_cndmask_b32_e32 v56, v57, v18, vcc
	v_cmp_eq_u32_e32 vcc, 2, v59
	v_bitop3_b32 v57, v34, s3, v34 bitop3:0xc
	s_nop 0
	v_cndmask_b32_e32 v23, v25, v23, vcc
	v_cmp_eq_u32_e32 vcc, 1, v59
	v_sub_f32_e32 v25, v30, v32
	v_mul_f32_e32 v25, 0x3fb8aa3b, v25
	v_cndmask_b32_e32 v21, v23, v21, vcc
	v_cmp_gt_u32_e32 vcc, 64, v57
	v_lshrrev_b32_e32 v23, 1, v39
	v_and_b32_e32 v23, 24, v23
	v_cndmask_b32_e32 v19, v21, v19, vcc
	v_bfe_u32 v21, v43, 2, 2
	v_cmp_eq_u32_e32 vcc, 2, v21
	v_lshrrev_b32_e32 v23, v23, v51
	v_lshlrev_b32_e32 v23, 7, v23
	v_cndmask_b32_e32 v22, v24, v22, vcc
	v_cmp_eq_u32_e32 vcc, 1, v21
	v_lshrrev_b32_e32 v21, 1, v42
	v_and_b32_e32 v21, 24, v21
	v_cndmask_b32_e32 v20, v22, v20, vcc
	v_cmp_gt_u32_e32 vcc, 4, v58
	v_lshrrev_b32_e32 v21, v21, v55
	v_lshrrev_b32_e32 v22, 1, v40
	v_cndmask_b32_e32 v18, v20, v18, vcc
	v_lshlrev_b32_e32 v20, 3, v42
	v_lshlrev_b32_e32 v21, 7, v21
	v_and_b32_e32 v22, 24, v22
	v_lshrrev_b32_e32 v20, v20, v56
	v_and_b32_e32 v21, 0x7f80, v21
	v_lshrrev_b32_e32 v22, v22, v53
	v_and_or_b32 v21, v20, s3, v21
	v_lshlrev_b32_e32 v20, 3, v40
	v_lshlrev_b32_e32 v22, 7, v22
	v_lshrrev_b32_e32 v20, v20, v54
	v_and_b32_e32 v22, 0x7f80, v22
	v_and_or_b32 v20, v20, s3, v22
	v_lshlrev_b32_e32 v22, 3, v39
	v_lshrrev_b32_e32 v22, v22, v52
	v_and_b32_e32 v23, 0x7f80, v23
	v_and_or_b32 v39, v22, s3, v23
	v_lshrrev_b32_e32 v23, 1, v36
	v_and_b32_e32 v23, 24, v23
	v_lshrrev_b32_e32 v23, v23, v49
	v_lshlrev_b32_e32 v22, 3, v36
	v_lshlrev_b32_e32 v23, 7, v23
	v_lshrrev_b32_e32 v22, v22, v50
	v_and_b32_e32 v23, 0x7f80, v23
	v_and_or_b32 v36, v22, s3, v23
	v_lshrrev_b32_e32 v23, 1, v38
	v_and_b32_e32 v23, 24, v23
	v_lshrrev_b32_e32 v23, v23, v47
	v_lshlrev_b32_e32 v22, 3, v38
	v_lshlrev_b32_e32 v23, 7, v23
	v_lshrrev_b32_e32 v22, v22, v48
	v_and_b32_e32 v23, 0x7f80, v23
	v_and_or_b32 v38, v22, s3, v23
	v_lshrrev_b32_e32 v23, 1, v35
	v_and_b32_e32 v23, 24, v23
	v_lshrrev_b32_e32 v23, v23, v45
	v_lshlrev_b32_e32 v22, 3, v35
	v_lshlrev_b32_e32 v23, 7, v23
	v_lshrrev_b32_e32 v22, v22, v46
	v_and_b32_e32 v23, 0x7f80, v23
	v_and_or_b32 v35, v22, s3, v23
	v_lshrrev_b32_e32 v23, 1, v28
	v_and_b32_e32 v23, 24, v23
	v_lshrrev_b32_e32 v23, v23, v26
	v_lshlrev_b32_e32 v22, 3, v28
	v_lshlrev_b32_e32 v23, 7, v23
	v_lshrrev_b32_e32 v22, v22, v44
	v_and_b32_e32 v23, 0x7f80, v23
	v_and_or_b32 v40, v22, s3, v23
	v_sub_f32_e32 v22, v27, v32
	v_mul_f32_e32 v22, 0x3fb8aa3b, v22
	v_sub_f32_e32 v23, v31, v32
	v_exp_f32_e32 v22, v22
	v_mul_f32_e32 v23, 0x3fb8aa3b, v23
	v_sub_f32_e32 v24, v37, v32
	v_exp_f32_e32 v23, v23
	v_mul_f32_e32 v24, 0x3fb8aa3b, v24
	v_exp_f32_e32 v24, v24
	v_exp_f32_e32 v25, v25
	v_add_f32_e32 v26, 0, v22
	v_add_f32_e32 v26, v23, v26
	v_add_f32_e32 v26, v24, v26
	v_add_f32_e32 v30, v25, v26
	v_sub_f32_e32 v26, v33, v32
	v_mul_f32_e32 v26, 0x3fb8aa3b, v26
	v_sub_f32_e32 v27, v29, v32
	v_exp_f32_e32 v26, v26
	v_mul_f32_e32 v27, 0x3fb8aa3b, v27
	v_sub_f32_e32 v28, v41, v32
	v_exp_f32_e32 v27, v27
	v_mul_f32_e32 v28, 0x3fb8aa3b, v28
	v_sub_f32_e32 v29, v34, v32
	v_exp_f32_e32 v28, v28
	v_mul_f32_e32 v29, 0x3fb8aa3b, v29
	v_exp_f32_e32 v29, v29
	v_add_f32_e32 v30, v26, v30
	v_add_f32_e32 v30, v27, v30
	v_add_f32_e32 v30, v28, v30
	v_add_f32_e32 v30, v29, v30
	ds_bpermute_b32 v31, v123, v30
	v_lshrrev_b32_e32 v42, 1, v43
	v_and_b32_e32 v32, 24, v42
	v_lshrrev_b32_e32 v19, v32, v19
	v_lshlrev_b32_e32 v19, 7, v19
	s_waitcnt lgkmcnt(0)
	v_add_f32_e32 v30, v30, v31
	v_div_scale_f32 v31, s[12:13], v30, v30, 1.0
	v_rcp_f32_e32 v32, v31
	v_lshlrev_b32_e32 v33, 3, v43
	v_and_b32_e32 v19, 0x7f80, v19
	v_lshrrev_b32_e32 v18, v33, v18
	v_and_or_b32 v33, v18, s3, v19
	v_fma_f32 v18, -v31, v32, 1.0
	v_fmac_f32_e32 v32, v18, v32
	v_div_scale_f32 v18, vcc, 1.0, v30, 1.0
	v_mul_f32_e32 v19, v18, v32
	v_fma_f32 v34, -v31, v19, v18
	v_fmac_f32_e32 v19, v34, v32
	v_fma_f32 v18, -v31, v19, v18
	v_div_fmas_f32 v18, v18, v32, v19
	v_div_fixup_f32 v30, v18, v30, 1.0
	v_mov_b32_e32 v18, v1
	v_lshl_or_b32 v20, v20, 16, v39
	v_lshrrev_b32_e32 v19, 3, v18
	v_and_or_b32 v19, v19, 3, s55
	v_lshlrev_b32_e32 v31, 4, v18
	v_ashrrev_i32_e32 v18, 2, v18
	v_lshlrev_b32_e32 v19, 7, v19
	v_and_b32_e32 v31, 0x70, v31
	v_and_b32_e32 v18, -8, v18
	v_add3_u32 v18, v18, v31, v19
	v_lshl_add_u32 v31, v18, 1, s11
	v_lshl_add_u32 v32, v18, 2, s69
	v_lshl_or_b32 v18, v35, 16, v40
	v_lshl_or_b32 v19, v36, 16, v38
	v_lshl_or_b32 v21, v33, 16, v21
	ds_write_b128 v31, v[18:21]
	v_pk_mul_f32 v[20:21], v[24:25], v[30:31] op_sel_hi:[1,0]
	v_pk_mul_f32 v[18:19], v[22:23], v[30:31] op_sel_hi:[1,0]
	ds_write_b128 v32, v[18:21]
	v_pk_mul_f32 v[20:21], v[28:29], v[30:31] op_sel_hi:[1,0]
	v_pk_mul_f32 v[18:19], v[26:27], v[30:31] op_sel_hi:[1,0]
	ds_write_b128 v32, v[18:21] offset:16
	v_mov_b64_e32 v[32:33], s[30:31]
	v_lshl_add_u64 v[128:129], v[82:83], 1, s[80:81]
	s_waitcnt vmcnt(4)
	v_mov_b32_e32 v78, v150
	v_mov_b32_e32 v79, v151
	v_mov_b32_e32 v80, v152
	v_mov_b32_e32 v81, v153
	v_mov_b32_e32 v74, v154
	v_mov_b32_e32 v75, v155
	v_mov_b32_e32 v76, v156
	v_mov_b32_e32 v77, v157
	v_mov_b32_e32 v70, v158
	v_mov_b32_e32 v71, v159
	v_mov_b32_e32 v72, v160
	v_mov_b32_e32 v73, v161
	v_mov_b32_e32 v66, v162
	v_mov_b32_e32 v67, v163
	v_mov_b32_e32 v68, v164
	v_mov_b32_e32 v69, v165
	ds_read_b128 v[50:53], v94
	ds_read_b128 v[54:57], v94 offset:32
	v_mov_b64_e32 v[30:31], s[28:29]
	v_mov_b64_e32 v[28:29], s[26:27]
	v_mov_b64_e32 v[26:27], s[24:25]
	v_mov_b64_e32 v[24:25], s[22:23]
	v_mov_b64_e32 v[22:23], s[20:21]
	v_mov_b64_e32 v[20:21], s[18:19]
	v_mov_b64_e32 v[18:19], s[16:17]
	s_waitcnt vmcnt(3) lgkmcnt(1)
; #define LAS __attribute__((address_space(3)))
; #define MFMA32(a, b, c) __builtin_amdgcn_mfma_f32_32x32x16_bf16((a), (b), (c), 0, 0, 0)
; __device__ __forceinline__ void route_task(int task, int tl0, const bf16* QP  , const LAS bf16* KHL, LAS unsigned short* EL, LAS float* GL, int lane) {
;     ...
;         for (int kt = 0; kt < 4; ++kt) {
;             f32x16 X;
; #pragma unroll
;             for (int i = 0; i < 16; ++i) X[i] = 8.f;
;             const LAS bf16* khp = KHL + (half * 128 + 32 * kt + r) * 72 + 8 * hi;
; #pragma unroll
;             for (int ks = 0; ks < 4; ++ks) {
;                 const bf16x8 kh = lds8(khp + 16 * ks);
;                 X = MFMA32(kh, qa[half][ks], X);
;             }
;             int grp[16];
; #pragma unroll
;             for (int i = 0; i < 16; ++i) grp[i] = (int)((__float_as_uint(X[i]) | 127u) - (unsigned)(32 * kt + (i & 3) + 8 * (i >> 2)));
;             sort16_desc(grp);
;             if (kt == 0) {
; #pragma unroll
;                 for (int i = 0; i < 16; ++i) cur[i] = grp[i];
;             } else merge16_desc(cur, grp);
	s_nop 0
	v_mfma_f32_32x32x16_bf16 v[34:49], v[50:53], v[78:81], v[18:33]
	ds_read_b128 v[50:53], v94 offset:64
	ds_read_b128 v[124:127], v94 offset:96
	s_waitcnt vmcnt(2) lgkmcnt(2)
	v_mfma_f32_32x32x16_bf16 v[34:49], v[54:57], v[74:77], v[34:49]
	s_waitcnt vmcnt(1) lgkmcnt(1)
	v_mfma_f32_32x32x16_bf16 v[34:49], v[50:53], v[70:73], v[34:49]
	s_waitcnt vmcnt(0)
	v_mov_b32_e32 v62, v166
	v_mov_b32_e32 v63, v167
	v_mov_b32_e32 v64, v168
	v_mov_b32_e32 v65, v169
	v_mov_b32_e32 v58, v170
	v_mov_b32_e32 v59, v171
	v_mov_b32_e32 v60, v172
	v_mov_b32_e32 v61, v173
	v_mov_b32_e32 v54, v174
	v_mov_b32_e32 v55, v175
	v_mov_b32_e32 v56, v176
	v_mov_b32_e32 v57, v177
	v_mov_b32_e32 v50, v178
	v_mov_b32_e32 v51, v179
	v_mov_b32_e32 v52, v180
	v_mov_b32_e32 v53, v181
	s_waitcnt vmcnt(4) lgkmcnt(0)
	v_mfma_f32_32x32x16_bf16 v[34:49], v[124:127], v[66:69], v[34:49]
	s_nop 11
	v_bitop3_b32 v37, v37, s42, 3 bitop3:0x56
	v_bitop3_b32 v48, v48, s42, 26 bitop3:0x56
	v_bitop3_b32 v38, v38, s42, 8 bitop3:0x56
	v_bitop3_b32 v42, v42, s42, 16 bitop3:0x56
	v_bitop3_b32 v47, v47, s42, 25 bitop3:0x56
	v_bitop3_b32 v39, v39, s42, 9 bitop3:0x56
	v_bitop3_b32 v40, v40, s42, 10 bitop3:0x56
	v_bitop3_b32 v43, v43, s42, 17 bitop3:0x56
	v_bitop3_b32 v44, v44, s42, 18 bitop3:0x56
	v_bitop3_b32 v36, v36, s42, 2 bitop3:0x56
	v_bitop3_b32 v49, v49, s42, 27 bitop3:0x56
	v_bitop3_b32 v41, v41, s42, 11 bitop3:0x56
	v_bitop3_b32 v45, v45, s42, 19 bitop3:0x56
	v_bitop3_b32 v35, v35, s42, 1 bitop3:0x56
	v_bitop3_b32 v46, v46, s42, 24 bitop3:0x56
	v_or_b32_e32 v34, 0x7f, v34
	v_max_i32_e32 v82, v37, v48
	v_max_i32_e32 v124, v38, v42
	v_max_i32_e32 v126, v34, v47
	v_max_i32_e32 v127, v39, v40
	v_min_i32_e32 v130, v43, v44
	v_min_i32_e32 v131, v36, v49
	v_min_i32_e32 v133, v41, v45
	v_min_i32_e32 v134, v35, v46
	v_min_i32_e32 v39, v39, v40
	v_min_i32_e32 v34, v34, v47
	v_min_i32_e32 v38, v38, v42
	v_min_i32_e32 v37, v37, v48
	v_max_i32_e32 v35, v35, v46
	v_max_i32_e32 v41, v41, v45
	v_max_i32_e32 v36, v36, v49
	v_max_i32_e32 v43, v43, v44
	v_min_i32_e32 v125, v82, v124
	v_min_i32_e32 v128, v126, v127
	v_max_i32_e32 v132, v130, v131
	v_max_i32_e32 v135, v133, v134
	v_max_i32_e32 v40, v39, v34
	v_max_i32_e32 v42, v38, v37
	v_min_i32_e32 v45, v35, v41
	v_min_i32_e32 v44, v36, v43
	v_min_i32_e32 v129, v125, v128
	v_max_i32_e32 v47, v40, v42
	v_max_i32_e32 v46, v45, v44
	v_min_i32_e32 v40, v40, v42
	v_min_i32_e32 v42, v45, v44
	v_max_i32_e32 v45, v125, v128
	v_max_i32_e32 v125, v132, v135
	v_min_i32_e32 v128, v45, v125
	v_min_i32_e32 v34, v39, v34
	v_max_i32_e32 v39, v126, v127
	v_max_i32_e32 v35, v35, v41
	v_max_i32_e32 v41, v82, v124
	v_max_i32_e32 v148, v45, v125
	ds_read_b128 v[124:127], v95
	v_max_i32_e32 v44, v40, v42
	v_min_i32_e32 v138, v40, v42
	v_min_i32_e32 v40, v133, v134
	v_min_i32_e32 v37, v38, v37
	v_min_i32_e32 v38, v130, v131
	v_max_i32_e32 v36, v36, v43
	v_min_i32_e32 v136, v132, v135
	v_min_i32_e32 v133, v40, v34
	v_min_i32_e32 v134, v37, v38
	v_max_i32_e32 v34, v40, v34
	v_max_i32_e32 v37, v37, v38
	v_min_i32_e32 v40, v39, v35
	v_min_i32_e32 v42, v36, v41
	v_max_i32_e32 v144, v39, v35
	v_max_i32_e32 v145, v36, v41
	v_max_i32_e32 v137, v129, v136
	v_min_i32_e32 v136, v129, v136
	v_max_i32_e32 v140, v133, v134
	v_min_i32_e32 v141, v34, v37
	v_max_i32_e32 v143, v40, v42
	v_min_i32_e32 v146, v144, v145
	v_max_i32_e32 v149, v47, v46
	v_min_i32_e32 v48, v47, v46
	v_max_i32_e32 v139, v138, v136
	v_max_i32_e32 v142, v140, v141
	v_min_i32_e32 v43, v40, v42
	v_max_i32_e32 v34, v34, v37
	v_min_i32_e32 v147, v143, v146
	v_min_i32_e32 v150, v148, v149
	v_min_i32_e32 v49, v137, v48
	v_min_i32_e32 v132, v44, v128
	v_max_i32_e32 v38, v139, v142
	v_min_i32_e32 v37, v43, v34
	v_max_i32_e32 v34, v43, v34
	v_min_i32_e32 v35, v147, v150
	v_max_i32_e32 v39, v137, v48
	v_max_i32_e32 v40, v44, v128
	v_max_i32_e32 v135, v49, v132
	v_max_i32_e32 v82, v38, v37
	v_min_i32_e32 v36, v34, v35
	v_min_i32_e32 v41, v39, v40
	v_max_i32_e32 v129, v135, v82
	v_min_i32_e32 v42, v36, v41
	v_min_i32_e32 v137, v129, v42
	v_max_i32_e32 v159, v129, v42
	ds_read_b128 v[128:131], v95 offset:32
	v_min_i32_e32 v82, v135, v82
	v_min_i32_e32 v132, v49, v132
	v_min_i32_e32 v135, v38, v37
	v_max_i32_e32 v154, v34, v35
	v_max_i32_e32 v155, v39, v40
	v_max_i32_e32 v157, v36, v41
	s_waitcnt lgkmcnt(1)
	v_mfma_f32_32x32x16_bf16 v[34:49], v[124:127], v[78:81], v[18:33]
	ds_read_b128 v[124:127], v95 offset:64
	v_max_i32_e32 v151, v132, v135
	v_max_i32_e32 v152, v82, v151
	v_min_i32_e32 v136, v138, v136
	v_min_i32_e32 v138, v140, v141
	v_min_i32_e32 v82, v82, v151
	v_max_i32_e32 v147, v147, v150
	s_waitcnt lgkmcnt(1)
	v_mfma_f32_32x32x16_bf16 v[34:49], v[128:131], v[74:77], v[34:49]
	ds_read_b128 v[128:131], v95 offset:96
	v_max_i32_e32 v143, v143, v146
	v_min_i32_e32 v133, v133, v134
	v_min_i32_e32 v156, v154, v155
	v_max_i32_e32 v140, v136, v138
	v_min_i32_e32 v139, v139, v142
	v_max_i32_e32 v142, v154, v155
	s_waitcnt lgkmcnt(1)
	v_mfma_f32_32x32x16_bf16 v[34:49], v[124:127], v[70:73], v[34:49]
	v_max_i32_e32 v124, v148, v149
	v_min_i32_e32 v136, v136, v138
	v_max_i32_e32 v141, v140, v139
	v_min_i32_e32 v139, v140, v139
	v_min_i32_e32 v125, v143, v124
	v_min_i32_e32 v158, v156, v157
	v_min_i32_e32 v132, v132, v135
	s_waitcnt lgkmcnt(0)
; #define LAS __attribute__((address_space(3)))
; #define MFMA32(a, b, c) __builtin_amdgcn_mfma_f32_32x32x16_bf16((a), (b), (c), 0, 0, 0)
; __device__ __forceinline__ void merge16_desc(int (&a)[16], const int (&b)[16]) {
; #pragma unroll
;     for (int i = 0; i < 16; ++i) a[i] = a[i] > b[15 - i] ? a[i] : b[15 - i];
; #pragma unroll
;     for (int j = 8; j > 0; j >>= 1)
; #pragma unroll
;         for (int i = 0; i < 16; ++i) { const int l = i ^ j; if (l > i) ce_desc(a[i], a[l]); }
; }
; __device__ __forceinline__ void route_task(int task, int tl0, const bf16* QP  , const LAS bf16* KHL, LAS unsigned short* EL, LAS float* GL, int lane) {
;     ...
;         for (int kt = 0; kt < 4; ++kt) {
;             f32x16 X;
; #pragma unroll
;             for (int i = 0; i < 16; ++i) X[i] = 8.f;
;             const LAS bf16* khp = KHL + (half * 128 + 32 * kt + r) * 72 + 8 * hi;
; #pragma unroll
;             for (int ks = 0; ks < 4; ++ks) {
;                 const bf16x8 kh = lds8(khp + 16 * ks);
;                 X = MFMA32(kh, qa[half][ks], X);
;             }
;             int grp[16];
; #pragma unroll
;             for (int i = 0; i < 16; ++i) grp[i] = (int)((__float_as_uint(X[i]) | 127u) - (unsigned)(32 * kt + (i & 3) + 8 * (i >> 2)));
;             sort16_desc(grp);
;             if (kt == 0) {
; #pragma unroll
;                 for (int i = 0; i < 16; ++i) cur[i] = grp[i];
;             } else merge16_desc(cur, grp);
	v_mfma_f32_32x32x16_bf16 v[34:49], v[128:131], v[66:69], v[34:49]
	v_min_i32_e32 v126, v147, v125
	v_min_i32_e32 v153, v137, v152
	v_min_i32_e32 v160, v158, v159
	v_min_i32_e32 v135, v141, v132
	v_min_i32_e32 v127, v142, v126
	s_nop 6
	v_bitop3_b32 v37, v37, s42, 35 bitop3:0x56
	v_bitop3_b32 v48, v48, s42, 58 bitop3:0x56
	v_bitop3_b32 v38, v38, s42, 40 bitop3:0x56
	v_bitop3_b32 v42, v42, s42, 48 bitop3:0x56
	v_bitop3_b32 v34, v34, s42, 32 bitop3:0x56
	v_bitop3_b32 v47, v47, s42, 57 bitop3:0x56
	v_bitop3_b32 v39, v39, s42, 41 bitop3:0x56
	v_bitop3_b32 v40, v40, s42, 42 bitop3:0x56
	v_bitop3_b32 v43, v43, s42, 49 bitop3:0x56
	v_bitop3_b32 v44, v44, s42, 50 bitop3:0x56
	v_bitop3_b32 v36, v36, s42, 34 bitop3:0x56
	v_bitop3_b32 v49, v49, s42, 59 bitop3:0x56
	v_bitop3_b32 v41, v41, s42, 43 bitop3:0x56
	v_bitop3_b32 v45, v45, s42, 51 bitop3:0x56
	v_bitop3_b32 v35, v35, s42, 33 bitop3:0x56
	v_bitop3_b32 v46, v46, s42, 56 bitop3:0x56
	v_max_i32_e32 v128, v37, v48
	v_max_i32_e32 v129, v38, v42
	v_max_i32_e32 v131, v34, v47
	v_max_i32_e32 v134, v39, v40
	v_min_i32_e32 v146, v43, v44
	v_min_i32_e32 v148, v36, v49
	v_min_i32_e32 v150, v41, v45
	v_min_i32_e32 v151, v35, v46
	v_min_i32_e32 v39, v39, v40
	v_min_i32_e32 v34, v34, v47
	v_min_i32_e32 v38, v38, v42
	v_min_i32_e32 v37, v37, v48
	v_max_i32_e32 v35, v35, v46
	v_max_i32_e32 v41, v41, v45
	v_max_i32_e32 v36, v36, v49
	v_max_i32_e32 v43, v43, v44
	v_min_i32_e32 v130, v128, v129
	v_min_i32_e32 v138, v131, v134
	v_max_i32_e32 v149, v146, v148
	v_max_i32_e32 v154, v150, v151
	v_max_i32_e32 v40, v39, v34
	v_max_i32_e32 v42, v38, v37
	v_min_i32_e32 v45, v35, v41
	v_min_i32_e32 v44, v36, v43
	v_min_i32_e32 v150, v150, v151
	v_min_i32_e32 v34, v39, v34
	v_min_i32_e32 v37, v38, v37
	v_min_i32_e32 v38, v146, v148
	v_max_i32_e32 v131, v131, v134
	v_max_i32_e32 v35, v35, v41
	v_max_i32_e32 v36, v36, v43
	v_max_i32_e32 v43, v128, v129
	v_min_i32_e32 v140, v130, v138
	v_min_i32_e32 v155, v149, v154
	v_max_i32_e32 v47, v40, v42
	v_max_i32_e32 v46, v45, v44
	v_min_i32_e32 v40, v40, v42
	v_min_i32_e32 v42, v45, v44
	v_max_i32_e32 v45, v130, v138
	v_max_i32_e32 v130, v149, v154
	v_min_i32_e32 v39, v150, v34
	v_min_i32_e32 v146, v37, v38
	v_max_i32_e32 v34, v150, v34
	v_max_i32_e32 v37, v37, v38
	v_min_i32_e32 v41, v131, v35
	v_min_i32_e32 v128, v36, v43
	v_max_i32_e32 v35, v131, v35
	v_max_i32_e32 v36, v36, v43
	v_min_i32_e32 v48, v47, v46
	v_max_i32_e32 v44, v40, v42
	v_min_i32_e32 v138, v45, v130
	v_min_i32_e32 v40, v40, v42
	v_min_i32_e32 v42, v140, v155
	v_max_i32_e32 v148, v39, v146
	v_min_i32_e32 v38, v34, v37
	v_min_i32_e32 v129, v41, v128
	v_max_i32_e32 v41, v41, v128
	v_min_i32_e32 v43, v35, v36
	v_max_i32_e32 v45, v45, v130
	v_max_i32_e32 v46, v47, v46
	v_max_i32_e32 v161, v140, v155
	v_max_i32_e32 v140, v40, v42
	v_max_i32_e32 v150, v148, v38
	v_max_i32_e32 v34, v34, v37
	v_min_i32_e32 v128, v41, v43
	v_min_i32_e32 v47, v45, v46
	v_min_i32_e32 v49, v161, v48
	v_min_i32_e32 v149, v44, v138
	v_max_i32_e32 v151, v140, v150
	v_min_i32_e32 v37, v129, v34
	v_max_i32_e32 v34, v129, v34
	v_min_i32_e32 v129, v128, v47
	v_max_i32_e32 v48, v161, v48
	v_max_i32_e32 v44, v44, v138
	v_max_i32_e32 v154, v49, v149
	v_max_i32_e32 v134, v151, v37
	v_min_i32_e32 v130, v34, v129
	v_min_i32_e32 v131, v48, v44
	v_min_i32_e32 v49, v49, v149
	v_min_i32_e32 v37, v151, v37
	v_max_i32_e32 v34, v34, v129
	v_max_i32_e32 v44, v48, v44
	v_min_i32_e32 v40, v40, v42
	v_min_i32_e32 v38, v148, v38
	v_max_i32_e32 v41, v41, v43
	v_max_i32_e32 v43, v45, v46
	v_max_i32_e32 v155, v154, v134
	v_min_i32_e32 v138, v130, v131
	v_min_i32_e32 v134, v154, v134
	v_max_i32_e32 v149, v49, v37
	v_min_i32_e32 v48, v34, v44
	v_max_i32_e32 v129, v130, v131
	v_max_i32_e32 v42, v40, v38
	v_min_i32_e32 v140, v140, v150
	v_max_i32_e32 v34, v34, v44
	v_max_i32_e32 v44, v128, v47
	v_min_i32_e32 v45, v41, v43
	v_min_i32_e32 v161, v155, v138
	v_max_i32_e32 v151, v134, v149
	v_min_i32_e32 v130, v48, v129
	v_max_i32_e32 v131, v155, v138
	v_max_i32_e32 v148, v42, v140
	v_min_i32_e32 v37, v49, v37
	v_min_i32_e32 v46, v44, v45
	v_min_i32_e32 v154, v161, v151
	v_min_i32_e32 v138, v130, v131
	v_min_i32_e32 v49, v148, v37
	v_min_i32_e32 v134, v134, v149
	v_min_i32_e32 v47, v34, v46
	v_min_i32_e32 v42, v42, v140
	v_min_i32_e32 v38, v40, v38
	v_min_i32_e32 v39, v39, v146
	v_max3_i32 v39, v144, v145, v39
	v_max3_i32 v38, v143, v124, v38
	v_max3_i32 v40, v147, v125, v42
	v_max3_i32 v42, v142, v126, v49
	v_max3_i32 v37, v127, v148, v37
	v_max3_i32 v49, v156, v157, v134
	v_max3_i32 v124, v158, v159, v154
	v_max3_i32 v125, v160, v161, v151
	v_max3_i32 v126, v137, v152, v138
	v_max3_i32 v127, v153, v130, v131
	v_max3_i32 v48, v82, v48, v129
	v_max3_i32 v47, v141, v132, v47
	v_max3_i32 v34, v135, v34, v46
	v_max3_i32 v44, v139, v44, v45
	v_max3_i32 v41, v136, v41, v43
	v_max3_i32 v35, v133, v35, v36
	v_max_i32_e32 v36, v39, v126
	v_min_i32_e32 v39, v39, v126
	v_max_i32_e32 v43, v38, v127
	v_min_i32_e32 v38, v38, v127
	v_max_i32_e32 v45, v40, v48
	v_min_i32_e32 v40, v40, v48
	v_max_i32_e32 v46, v42, v47
	v_min_i32_e32 v42, v42, v47
	v_max_i32_e32 v47, v37, v34
	v_min_i32_e32 v34, v37, v34
	v_max_i32_e32 v37, v49, v44
	v_min_i32_e32 v44, v49, v44
	v_max_i32_e32 v48, v124, v41
	v_min_i32_e32 v41, v124, v41
	v_max_i32_e32 v49, v125, v35
	v_min_i32_e32 v35, v125, v35
	ds_read_b128 v[124:127], v94 offset:9216
	ds_read_b128 v[128:131], v94 offset:9248
	v_max_i32_e32 v82, v36, v47
	v_min_i32_e32 v132, v36, v47
	v_max_i32_e32 v36, v43, v37
	v_min_i32_e32 v133, v43, v37
	v_max_i32_e32 v37, v45, v48
	v_max_i32_e32 v43, v46, v49
	v_min_i32_e32 v134, v45, v48
	v_min_i32_e32 v135, v46, v49
	v_max_i32_e32 v136, v39, v34
	v_min_i32_e32 v137, v39, v34
	v_max_i32_e32 v138, v38, v44
	v_min_i32_e32 v139, v38, v44
	v_max_i32_e32 v140, v40, v41
	v_min_i32_e32 v141, v40, v41
	v_max_i32_e32 v142, v42, v35
	v_min_i32_e32 v143, v42, v35
	v_max_i32_e32 v144, v82, v37
	v_min_i32_e32 v82, v82, v37
	v_max_i32_e32 v145, v36, v43
	v_min_i32_e32 v146, v36, v43
	s_waitcnt lgkmcnt(1)
; #define LAS __attribute__((address_space(3)))
; #define MFMA32(a, b, c) __builtin_amdgcn_mfma_f32_32x32x16_bf16((a), (b), (c), 0, 0, 0)
; __device__ __forceinline__ void merge16_desc(int (&a)[16], const int (&b)[16]) {
; #pragma unroll
;     for (int i = 0; i < 16; ++i) a[i] = a[i] > b[15 - i] ? a[i] : b[15 - i];
; #pragma unroll
;     for (int j = 8; j > 0; j >>= 1)
; #pragma unroll
;         for (int i = 0; i < 16; ++i) { const int l = i ^ j; if (l > i) ce_desc(a[i], a[l]); }
; }
; __device__ __forceinline__ void route_task(int task, int tl0, const bf16* QP  , const LAS bf16* KHL, LAS unsigned short* EL, LAS float* GL, int lane) {
;     ...
;         for (int kt = 0; kt < 4; ++kt) {
;             f32x16 X;
; #pragma unroll
;             for (int i = 0; i < 16; ++i) X[i] = 8.f;
;             const LAS bf16* khp = KHL + (half * 128 + 32 * kt + r) * 72 + 8 * hi;
; #pragma unroll
;             for (int ks = 0; ks < 4; ++ks) {
;                 const bf16x8 kh = lds8(khp + 16 * ks);
;                 X = MFMA32(kh, qa[half][ks], X);
;             }
;             int grp[16];
; #pragma unroll
;             for (int i = 0; i < 16; ++i) grp[i] = (int)((__float_as_uint(X[i]) | 127u) - (unsigned)(32 * kt + (i & 3) + 8 * (i >> 2)));
;             sort16_desc(grp);
;             if (kt == 0) {
; #pragma unroll
;                 for (int i = 0; i < 16; ++i) cur[i] = grp[i];
;             } else merge16_desc(cur, grp);
	v_mfma_f32_32x32x16_bf16 v[34:49], v[124:127], v[78:81], v[18:33]
	ds_read_b128 v[124:127], v94 offset:9280
	v_max_i32_e32 v147, v132, v134
	v_min_i32_e32 v132, v132, v134
	v_max_i32_e32 v134, v133, v135
	v_min_i32_e32 v133, v133, v135
	v_max_i32_e32 v135, v136, v140
	v_min_i32_e32 v136, v136, v140
	s_waitcnt lgkmcnt(1)
	v_mfma_f32_32x32x16_bf16 v[34:49], v[128:131], v[74:77], v[34:49]
	ds_read_b128 v[128:131], v94 offset:9312
	v_max_i32_e32 v140, v138, v142
	v_min_i32_e32 v138, v138, v142
	v_max_i32_e32 v142, v137, v141
	v_min_i32_e32 v137, v137, v141
	v_max_i32_e32 v141, v139, v143
	v_min_i32_e32 v139, v139, v143
	s_waitcnt lgkmcnt(1)
	v_mfma_f32_32x32x16_bf16 v[34:49], v[124:127], v[70:73], v[34:49]
	v_min_i32_e32 v143, v144, v145
	v_min_i32_e32 v124, v82, v146
	v_min_i32_e32 v127, v135, v140
	v_min_i32_e32 v125, v147, v134
	v_min_i32_e32 v126, v132, v133
	v_min_i32_e32 v149, v142, v141
	v_min_i32_e32 v148, v136, v138
	s_waitcnt lgkmcnt(0)
	v_mfma_f32_32x32x16_bf16 v[34:49], v[128:131], v[66:69], v[34:49]
	v_min_i32_e32 v150, v137, v139
	s_nop 10
	v_and_or_b32 v37, v37, s43, 60
	v_and_or_b32 v48, v48, s43, 37
	v_and_or_b32 v38, v38, s43, 55
	v_and_or_b32 v42, v42, s43, 47
	v_bitop3_b32 v34, v34, s42, 64 bitop3:0x56
	v_and_or_b32 v47, v47, s43, 38
	v_and_or_b32 v39, v39, s43, 54
	v_and_or_b32 v40, v40, s43, 53
	v_and_or_b32 v43, v43, s43, 46
	v_and_or_b32 v44, v44, s43, 45
	v_and_or_b32 v36, v36, s43, 61
	v_and_or_b32 v49, v49, s43, 36
	v_and_or_b32 v41, v41, s43, 52
	v_and_or_b32 v45, v45, s43, 44
	v_and_or_b32 v35, v35, s43, 62
	v_and_or_b32 v46, v46, s43, 39
	v_max_i32_e32 v128, v37, v48
	v_max_i32_e32 v129, v38, v42
	v_max_i32_e32 v131, v34, v47
	v_max_i32_e32 v151, v39, v40
	v_min_i32_e32 v154, v43, v44
	v_min_i32_e32 v155, v36, v49
	v_min_i32_e32 v157, v41, v45
	v_min_i32_e32 v158, v35, v46
	v_min_i32_e32 v39, v39, v40
	v_min_i32_e32 v34, v34, v47
	v_min_i32_e32 v38, v38, v42
	v_min_i32_e32 v37, v37, v48
	v_max_i32_e32 v35, v35, v46
	v_max_i32_e32 v41, v41, v45
	v_max_i32_e32 v36, v36, v49
	v_max_i32_e32 v43, v43, v44
	v_min_i32_e32 v130, v128, v129
	v_min_i32_e32 v152, v131, v151
	v_max_i32_e32 v156, v154, v155
	v_max_i32_e32 v159, v157, v158
	v_max_i32_e32 v40, v39, v34
	v_max_i32_e32 v42, v38, v37
	v_min_i32_e32 v45, v35, v41
	v_min_i32_e32 v44, v36, v43
	v_min_i32_e32 v157, v157, v158
	v_min_i32_e32 v34, v39, v34
	v_min_i32_e32 v37, v38, v37
	v_min_i32_e32 v38, v154, v155
	v_max_i32_e32 v131, v131, v151
	v_max_i32_e32 v35, v35, v41
	v_max_i32_e32 v36, v36, v43
	v_max_i32_e32 v43, v128, v129
	v_min_i32_e32 v153, v130, v152
	v_min_i32_e32 v160, v156, v159
	v_max_i32_e32 v47, v40, v42
	v_max_i32_e32 v46, v45, v44
	v_min_i32_e32 v40, v40, v42
	v_min_i32_e32 v42, v45, v44
	v_max_i32_e32 v45, v130, v152
	v_max_i32_e32 v130, v156, v159
	v_min_i32_e32 v39, v157, v34
	v_min_i32_e32 v154, v37, v38
	v_max_i32_e32 v34, v157, v34
	v_max_i32_e32 v37, v37, v38
	v_min_i32_e32 v41, v131, v35
	v_min_i32_e32 v128, v36, v43
	v_max_i32_e32 v35, v131, v35
	v_max_i32_e32 v36, v36, v43
	v_min_i32_e32 v48, v47, v46
	v_max_i32_e32 v44, v40, v42
	v_min_i32_e32 v152, v45, v130
	v_min_i32_e32 v40, v40, v42
	v_min_i32_e32 v42, v153, v160
	v_max_i32_e32 v155, v39, v154
	v_min_i32_e32 v38, v34, v37
	v_min_i32_e32 v129, v41, v128
	v_max_i32_e32 v41, v41, v128
	v_min_i32_e32 v43, v35, v36
	v_max_i32_e32 v45, v45, v130
	v_max_i32_e32 v46, v47, v46
	v_max_i32_e32 v161, v153, v160
	v_max_i32_e32 v153, v40, v42
	v_max_i32_e32 v157, v155, v38
	v_max_i32_e32 v34, v34, v37
	v_min_i32_e32 v128, v41, v43
	v_min_i32_e32 v47, v45, v46
	v_min_i32_e32 v49, v161, v48
	v_min_i32_e32 v156, v44, v152
	v_max_i32_e32 v158, v153, v157
	v_min_i32_e32 v37, v129, v34
	v_max_i32_e32 v34, v129, v34
	v_min_i32_e32 v129, v128, v47
	v_max_i32_e32 v48, v161, v48
	v_max_i32_e32 v44, v44, v152
	v_min_i32_e32 v40, v40, v42
	v_min_i32_e32 v38, v155, v38
	v_max_i32_e32 v159, v49, v156
	v_max_i32_e32 v151, v158, v37
	v_min_i32_e32 v130, v34, v129
	v_min_i32_e32 v131, v48, v44
	v_min_i32_e32 v49, v49, v156
	v_min_i32_e32 v37, v158, v37
	v_max_i32_e32 v34, v34, v129
	v_max_i32_e32 v44, v48, v44
	v_max_i32_e32 v42, v40, v38
	v_min_i32_e32 v153, v153, v157
	v_max_i32_e32 v160, v159, v151
	v_min_i32_e32 v152, v130, v131
	v_max_i32_e32 v156, v49, v37
	v_min_i32_e32 v48, v34, v44
	v_max_i32_e32 v129, v130, v131
	v_max_i32_e32 v155, v42, v153
	v_min_i32_e32 v37, v49, v37
	v_min_i32_e32 v151, v159, v151
	v_min_i32_e32 v130, v48, v129
	v_max_i32_e32 v131, v160, v152
	v_min_i32_e32 v49, v155, v37
	v_max_i32_e32 v41, v41, v43
	v_max_i32_e32 v43, v45, v46
	v_min_i32_e32 v42, v42, v153
	v_min_i32_e32 v38, v40, v38
	v_min_i32_e32 v161, v160, v152
	v_max_i32_e32 v158, v151, v156
	v_min_i32_e32 v151, v151, v156
	v_max_i32_e32 v34, v34, v44
	v_max_i32_e32 v44, v128, v47
	v_min_i32_e32 v45, v41, v43
	v_max_i32_e32 v40, v41, v43
	v_max_i32_e32 v38, v143, v38
	v_max3_i32 v41, v82, v146, v42
	v_max_i32_e32 v42, v124, v49
	v_max3_i32 v124, v127, v130, v131
	v_min_i32_e32 v46, v44, v45
	v_max_i32_e32 v43, v125, v151
	v_max3_i32 v49, v126, v161, v158
	v_max3_i32 v44, v149, v44, v45
	v_max_i32_e32 v45, v38, v124
	v_min_i32_e32 v38, v38, v124
	ds_read_b128 v[124:127], v96
	v_min_i32_e32 v159, v161, v158
	v_min_i32_e32 v152, v130, v131
	v_max_i32_e32 v37, v155, v37
	v_max_i32_e32 v48, v48, v129
	v_min_i32_e32 v47, v34, v46
	v_max_i32_e32 v34, v34, v46
	v_min_i32_e32 v39, v39, v154
	v_max3_i32 v39, v144, v145, v39
	v_max3_i32 v37, v147, v134, v37
	v_max3_i32 v46, v132, v133, v159
	v_max3_i32 v82, v135, v140, v152
	v_max3_i32 v48, v136, v138, v48
	v_max_i32_e32 v47, v148, v47
	v_max3_i32 v34, v142, v141, v34
	v_max3_i32 v40, v137, v139, v40
	v_max3_i32 v35, v150, v35, v36
	v_max_i32_e32 v36, v39, v82
	v_min_i32_e32 v39, v39, v82
	v_max_i32_e32 v82, v41, v48
	v_min_i32_e32 v41, v41, v48
	v_max_i32_e32 v48, v42, v47
	v_min_i32_e32 v42, v42, v47
	v_max_i32_e32 v47, v37, v34
	v_min_i32_e32 v34, v37, v34
	v_max_i32_e32 v37, v43, v44
	v_min_i32_e32 v43, v43, v44
	v_max_i32_e32 v44, v46, v40
	v_min_i32_e32 v40, v46, v40
	v_max_i32_e32 v46, v49, v35
	v_min_i32_e32 v35, v49, v35
	v_max_i32_e32 v49, v36, v47
	v_min_i32_e32 v132, v36, v47
	v_max_i32_e32 v36, v45, v37
	v_min_i32_e32 v133, v45, v37
	v_max_i32_e32 v37, v82, v44
	v_min_i32_e32 v82, v82, v44
	v_max_i32_e32 v44, v48, v46
	ds_read_b128 v[128:131], v96 offset:32
	v_min_i32_e32 v134, v48, v46
	v_max_i32_e32 v135, v39, v34
	v_min_i32_e32 v136, v39, v34
	v_max_i32_e32 v137, v38, v43
	v_min_i32_e32 v138, v38, v43
	v_max_i32_e32 v139, v41, v40
	v_min_i32_e32 v140, v41, v40
	v_max_i32_e32 v141, v42, v35
	v_min_i32_e32 v142, v42, v35
	v_max_i32_e32 v143, v49, v37
	v_min_i32_e32 v144, v49, v37
	v_max_i32_e32 v145, v36, v44
	v_min_i32_e32 v146, v36, v44
	s_waitcnt lgkmcnt(1)
; #define LAS __attribute__((address_space(3)))
; #define MFMA32(a, b, c) __builtin_amdgcn_mfma_f32_32x32x16_bf16((a), (b), (c), 0, 0, 0)
; __device__ __forceinline__ void merge16_desc(int (&a)[16], const int (&b)[16]) {
; #pragma unroll
;     for (int i = 0; i < 16; ++i) a[i] = a[i] > b[15 - i] ? a[i] : b[15 - i];
; #pragma unroll
;     for (int j = 8; j > 0; j >>= 1)
; #pragma unroll
;         for (int i = 0; i < 16; ++i) { const int l = i ^ j; if (l > i) ce_desc(a[i], a[l]); }
; }
; __device__ __forceinline__ void route_task(int task, int tl0, const bf16* QP  , const LAS bf16* KHL, LAS unsigned short* EL, LAS float* GL, int lane) {
;     ...
;         for (int kt = 0; kt < 4; ++kt) {
;             f32x16 X;
; #pragma unroll
;             for (int i = 0; i < 16; ++i) X[i] = 8.f;
;             const LAS bf16* khp = KHL + (half * 128 + 32 * kt + r) * 72 + 8 * hi;
; #pragma unroll
;             for (int ks = 0; ks < 4; ++ks) {
;                 const bf16x8 kh = lds8(khp + 16 * ks);
;                 X = MFMA32(kh, qa[half][ks], X);
;             }
;             int grp[16];
; #pragma unroll
;             for (int i = 0; i < 16; ++i) grp[i] = (int)((__float_as_uint(X[i]) | 127u) - (unsigned)(32 * kt + (i & 3) + 8 * (i >> 2)));
;             sort16_desc(grp);
;             if (kt == 0) {
; #pragma unroll
;                 for (int i = 0; i < 16; ++i) cur[i] = grp[i];
;             } else merge16_desc(cur, grp);
	v_mfma_f32_32x32x16_bf16 v[34:49], v[124:127], v[78:81], v[18:33]
	ds_read_b128 v[78:81], v96 offset:64
	v_max_i32_e32 v147, v132, v82
	v_min_i32_e32 v82, v132, v82
	v_max_i32_e32 v132, v137, v141
	v_max_i32_e32 v124, v133, v134
	v_min_i32_e32 v125, v133, v134
	v_max_i32_e32 v126, v135, v139
	s_waitcnt lgkmcnt(1)
	v_mfma_f32_32x32x16_bf16 v[34:49], v[128:131], v[74:77], v[34:49]
	ds_read_b128 v[74:77], v96 offset:96
	v_min_i32_e32 v128, v137, v141
	v_max_i32_e32 v129, v136, v140
	v_min_i32_e32 v130, v136, v140
	v_min_i32_e32 v127, v135, v139
	v_max_i32_e32 v131, v138, v142
	v_min_i32_e32 v133, v138, v142
	s_waitcnt lgkmcnt(1)
	v_mfma_f32_32x32x16_bf16 v[34:49], v[78:81], v[70:73], v[34:49]
	v_min_i32_e32 v134, v143, v145
	v_min_i32_e32 v70, v144, v146
	v_min_i32_e32 v71, v147, v124
	v_min_i32_e32 v72, v82, v125
	v_min_i32_e32 v73, v126, v132
	v_min_i32_e32 v78, v127, v128
	v_min_i32_e32 v79, v129, v131
	s_waitcnt lgkmcnt(0)
	v_mfma_f32_32x32x16_bf16 v[34:49], v[74:77], v[66:69], v[34:49]
	v_min_i32_e32 v80, v130, v133
	s_nop 10
	v_and_or_b32 v41, v41, s43, 20
	v_and_or_b32 v45, v45, s43, 12
	v_and_or_b32 v35, v35, s43, 30
	v_and_or_b32 v46, v46, s43, 7
	v_and_or_b32 v39, v39, s43, 22
	v_and_or_b32 v40, v40, s43, 21
	v_and_or_b32 v34, v34, s43, 31
	v_and_or_b32 v47, v47, s43, 6
	v_and_or_b32 v38, v38, s43, 23
	v_and_or_b32 v42, v42, s43, 15
	v_and_or_b32 v37, v37, s43, 28
	v_and_or_b32 v48, v48, s43, 5
	v_and_or_b32 v43, v43, s43, 14
	v_and_or_b32 v44, v44, s43, 13
	v_and_or_b32 v36, v36, s43, 29
	v_and_or_b32 v49, v49, s43, 4
	v_min_i32_e32 v66, v41, v45
	v_min_i32_e32 v67, v35, v46
	v_min_i32_e32 v69, v39, v40
	v_min_i32_e32 v74, v34, v47
	v_min_i32_e32 v77, v38, v42
	v_min_i32_e32 v81, v37, v48
	v_min_i32_e32 v136, v43, v44
	v_min_i32_e32 v137, v36, v49
	v_max_i32_e32 v34, v34, v47
	v_max_i32_e32 v39, v39, v40
	v_max_i32_e32 v35, v35, v46
	v_max_i32_e32 v41, v41, v45
	v_max_i32_e32 v36, v36, v49
	v_max_i32_e32 v43, v43, v44
	v_max_i32_e32 v37, v37, v48
	v_max_i32_e32 v38, v38, v42
	v_max_i32_e32 v40, v34, v39
	v_max_i32_e32 v45, v35, v41
	v_max_i32_e32 v44, v36, v43
	v_max_i32_e32 v42, v37, v38
	v_min_i32_e32 v46, v40, v45
	v_min_i32_e32 v47, v44, v42
	v_min_i32_e32 v75, v69, v74
	v_min_i32_e32 v48, v46, v47
	v_max_i32_e32 v46, v46, v47
	v_min_i32_e32 v37, v37, v38
	v_min_i32_e32 v34, v34, v39
	v_max_i32_e32 v39, v136, v137
	v_max_i32_e32 v47, v66, v67
	v_max_i32_e32 v69, v69, v74
	v_max_i32_e32 v74, v77, v81
	v_min_i32_e32 v35, v35, v41
	v_min_i32_e32 v36, v36, v43
	v_min_i32_e32 v68, v66, v67
	v_min_i32_e32 v135, v77, v81
	v_min_i32_e32 v138, v136, v137
	v_max_i32_e32 v38, v37, v34
	v_max_i32_e32 v77, v69, v74
	v_max_i32_e32 v41, v35, v36
	v_min_i32_e32 v34, v37, v34
	v_min_i32_e32 v37, v39, v47
	v_min_i32_e32 v76, v68, v75
	v_min_i32_e32 v139, v135, v138
	v_max_i32_e32 v49, v68, v75
	v_max_i32_e32 v68, v135, v138
	v_max_i32_e32 v40, v40, v45
	v_max_i32_e32 v42, v44, v42
	v_max_i32_e32 v66, v39, v47
	v_max_i32_e32 v43, v77, v41
	v_max_i32_e32 v39, v34, v37
	v_min_i32_e32 v41, v77, v41
	v_min_i32_e32 v69, v69, v74
	v_min_i32_e32 v35, v35, v36
	v_max_i32_e32 v75, v49, v68
	v_min_i32_e32 v44, v40, v42
	v_max_i32_e32 v67, v38, v66
	v_max_i32_e32 v47, v39, v41
	v_max_i32_e32 v36, v69, v35
	v_min_i32_e32 v39, v39, v41
	v_min_i32_e32 v35, v69, v35
	v_min_i32_e32 v34, v34, v37
	v_max_i32_e32 v41, v76, v139
	v_min_i32_e32 v49, v49, v68
	v_min_i32_e32 v45, v46, v44
	v_min_i32_e32 v81, v67, v43
	v_min_i32_e32 v38, v38, v66
	v_max_i32_e32 v37, v35, v34
	v_max_i32_e32 v68, v41, v49
	v_max_i32_e32 v135, v48, v75
	v_min_i32_e32 v136, v45, v81
	v_max_i32_e32 v66, v36, v38
	v_min_i32_e32 v36, v36, v38
	v_max_i32_e32 v69, v37, v68
	v_min_i32_e32 v48, v48, v75
	v_max_i32_e32 v137, v135, v136
	v_max_i32_e32 v74, v47, v66
	v_min_i32_e32 v135, v135, v136
	v_min_i32_e32 v47, v47, v66
	v_max_i32_e32 v38, v39, v36
	v_max_i32_e32 v75, v69, v48
	v_min_i32_e32 v34, v35, v34
	v_min_i32_e32 v35, v41, v49
	v_min_i32_e32 v36, v39, v36
	v_min_i32_e32 v39, v69, v48
	v_max_i32_e32 v44, v46, v44
	v_max_i32_e32 v43, v67, v43
	v_min_i32_e32 v140, v76, v139
	v_min_i32_e32 v77, v137, v74
	v_max_i32_e32 v66, v135, v47
	v_max_i32_e32 v76, v38, v75
	v_min_i32_e32 v47, v135, v47
	v_max_i32_e32 v41, v34, v35
	v_min_i32_e32 v37, v37, v68
	v_min_i32_e32 v48, v36, v39
	v_max_i32_e32 v45, v45, v81
	v_min_i32_e32 v46, v44, v43
	v_min_i32_e32 v38, v38, v75
	v_max_i32_e32 v36, v36, v39
	v_min_i32_e32 v136, v77, v66
	v_max_i32_e32 v135, v76, v47
	v_max_i32_e32 v49, v41, v37
	v_max_i32_e32 v69, v137, v74
	v_min_i32_e32 v67, v45, v46
	v_min_i32_e32 v47, v76, v47
	v_max_i32_e32 v39, v38, v36
	v_min_i32_e32 v138, v136, v135
	v_max_i32_e32 v68, v49, v48
	v_max_i32_e32 v74, v69, v67
	v_min_i32_e32 v37, v41, v37
	v_max_i32_e32 v41, v77, v66
	v_min_i32_e32 v75, v47, v39
	v_max_i32_e32 v43, v44, v43
	v_min_i32_e32 v34, v34, v35
	v_min_i32_e32 v36, v38, v36
	v_min_i32_e32 v48, v49, v48
	v_min_i32_e32 v49, v69, v67
	v_max3_i32 v140, v143, v145, v140
	v_max3_i32 v126, v126, v132, v138
	v_max3_i32 v68, v147, v124, v68
	v_max3_i32 v74, v129, v131, v74
	v_max3_i32 v37, v144, v146, v37
	v_max3_i32 v41, v127, v128, v41
	v_max3_i32 v75, v82, v125, v75
	v_max3_i32 v43, v130, v133, v43
	v_max_i32_e32 v34, v134, v34
	v_max3_i32 v35, v73, v136, v135
	v_max_i32_e32 v36, v71, v36
	v_max3_i32 v38, v79, v45, v46
	v_max_i32_e32 v48, v70, v48
	v_max_i32_e32 v49, v78, v49
	v_max3_i32 v39, v72, v47, v39
	v_max3_i32 v40, v80, v40, v42
	v_min_i32_e32 v81, v68, v74
	v_min_i32_e32 v66, v37, v41
	v_min_i32_e32 v73, v34, v35
	v_min_i32_e32 v45, v36, v38
	v_min_i32_e32 v42, v39, v40
	v_max_i32_e32 v71, v140, v126
; #define LAS __attribute__((address_space(3)))
; #define MFMA32(a, b, c) __builtin_amdgcn_mfma_f32_32x32x16_bf16((a), (b), (c), 0, 0, 0)
; __device__ __forceinline__ void route_task(int task, int tl0, const bf16* QP  , const LAS bf16* KHL, LAS unsigned short* EL, LAS float* GL, int lane) {
;     ...
;         for (int kt = 0; kt < 4; ++kt) {
;             f32x16 X;
; #pragma unroll
;             for (int i = 0; i < 16; ++i) X[i] = 8.f;
;             const LAS bf16* khp = KHL + (half * 128 + 32 * kt + r) * 72 + 8 * hi;
; #pragma unroll
;             for (int ks = 0; ks < 4; ++ks) {
;                 const bf16x8 kh = lds8(khp + 16 * ks);
;                 X = MFMA32(kh, qa[half][ks], X);
;     ...
;         { const unsigned h4 = 4u * (unsigned)hi;
; #pragma unroll
;           for (int i = 0; i < 16; ++i) cur[i] -= (int)h4; }
;         int oth[16];
; #pragma unroll
;         for (int i = 0; i < 16; ++i) oth[i] = __shfl_xor(cur[i], 32);
;         merge16_desc(cur, oth);
; #pragma unroll
;         for (int i = 0; i < 16; ++i) top[half][i] = cur[i];
	v_max_i32_e32 v68, v68, v74
	v_max_i32_e32 v37, v37, v41
	v_max_i32_e32 v41, v75, v43
	v_max_i32_e32 v34, v34, v35
	v_max_i32_e32 v35, v36, v38
	v_max_i32_e32 v38, v48, v49
	v_max_i32_e32 v39, v39, v40
	v_min_i32_e32 v44, v75, v43
	v_max_i32_e32 v72, v71, v68
	v_max_i32_e32 v43, v37, v41
	v_max_i32_e32 v36, v34, v35
	v_max_i32_e32 v40, v38, v39
	v_min_i32_e32 v67, v48, v49
	v_max_i32_e32 v74, v72, v43
	v_max_i32_e32 v48, v36, v40
	v_min_i32_e32 v43, v72, v43
	v_min_i32_e32 v36, v36, v40
	v_max_i32_e32 v40, v43, v36
	v_min_i32_e32 v36, v43, v36
	v_min_i32_e32 v43, v71, v68
	v_min_i32_e32 v37, v37, v41
	v_min_i32_e32 v34, v34, v35
	v_min_i32_e32 v35, v38, v39
	v_min_i32_e32 v132, v140, v126
	v_max_i32_e32 v41, v43, v37
	v_max_i32_e32 v38, v34, v35
	v_min_i32_e32 v37, v43, v37
	v_min_i32_e32 v34, v34, v35
	v_min_i32_e32 v76, v66, v44
	v_min_i32_e32 v47, v67, v42
	v_max_i32_e32 v39, v41, v38
	v_min_i32_e32 v38, v41, v38
	v_max_i32_e32 v35, v37, v34
	v_min_i32_e32 v34, v37, v34
	v_max_i32_e32 v37, v132, v81
	v_max_i32_e32 v41, v66, v44
	v_max_i32_e32 v44, v73, v45
	v_max_i32_e32 v42, v67, v42
	v_min_i32_e32 v124, v132, v81
	v_min_i32_e32 v46, v73, v45
	v_max_i32_e32 v43, v37, v41
	v_min_i32_e32 v37, v37, v41
	v_min_i32_e32 v41, v44, v42
	v_min_i32_e32 v77, v124, v76
	v_min_i32_e32 v69, v46, v47
	v_max_i32_e32 v45, v44, v42
	v_max_i32_e32 v42, v37, v41
	v_min_i32_e32 v37, v37, v41
	v_max_i32_e32 v41, v124, v76
	v_max_i32_e32 v44, v46, v47
	v_min_i32_e32 v70, v77, v69
	v_max_i32_e32 v49, v74, v48
	v_min_i32_e32 v48, v74, v48
	v_max_i32_e32 v66, v43, v45
	v_min_i32_e32 v43, v43, v45
	v_max_i32_e32 v45, v41, v44
	v_min_i32_e32 v41, v41, v44
	v_max_i32_e32 v44, v77, v69
	v_sub_u32_e32 v46, v49, v87
	v_sub_u32_e32 v47, v48, v87
	v_sub_u32_e32 v40, v40, v87
	v_sub_u32_e32 v36, v36, v87
	v_sub_u32_e32 v39, v39, v87
	v_sub_u32_e32 v38, v38, v87
	v_sub_u32_e32 v35, v35, v87
	v_sub_u32_e32 v34, v34, v87
	v_sub_u32_e32 v48, v66, v87
	v_sub_u32_e32 v43, v43, v87
	v_sub_u32_e32 v42, v42, v87
	v_sub_u32_e32 v37, v37, v87
	v_sub_u32_e32 v45, v45, v87
	v_sub_u32_e32 v41, v41, v87
	v_sub_u32_e32 v44, v44, v87
	v_sub_u32_e32 v49, v70, v87
	ds_bpermute_b32 v66, v123, v46
	ds_bpermute_b32 v67, v123, v47
	ds_bpermute_b32 v68, v123, v40
	ds_bpermute_b32 v69, v123, v36
	ds_bpermute_b32 v70, v123, v39
	ds_bpermute_b32 v71, v123, v38
	ds_bpermute_b32 v72, v123, v35
	ds_bpermute_b32 v73, v123, v34
	ds_bpermute_b32 v74, v123, v48
	ds_bpermute_b32 v75, v123, v43
	ds_bpermute_b32 v76, v123, v42
	ds_bpermute_b32 v77, v123, v49
	ds_bpermute_b32 v78, v123, v44
	ds_bpermute_b32 v79, v123, v41
	ds_bpermute_b32 v80, v123, v45
	ds_bpermute_b32 v81, v123, v37
	s_waitcnt lgkmcnt(4)
	v_max_i32_e32 v46, v46, v77
	s_waitcnt lgkmcnt(3)
	v_max_i32_e32 v47, v47, v78
	s_waitcnt lgkmcnt(2)
	v_max_i32_e32 v40, v40, v79
	s_waitcnt lgkmcnt(1)
	v_max_i32_e32 v36, v36, v80
	s_waitcnt lgkmcnt(0)
	v_max_i32_e32 v39, v39, v81
	v_max_i32_e32 v38, v38, v76
	v_max_i32_e32 v35, v35, v75
	v_max_i32_e32 v34, v34, v74
	v_max_i32_e32 v48, v48, v73
	v_max_i32_e32 v43, v43, v72
	v_max_i32_e32 v42, v42, v71
	v_max_i32_e32 v37, v37, v70
	v_max_i32_e32 v45, v45, v69
	v_max_i32_e32 v41, v41, v68
	v_max_i32_e32 v44, v44, v67
	v_max_i32_e32 v49, v49, v66
	v_max_i32_e32 v66, v46, v48
	v_min_i32_e32 v46, v46, v48
	v_max_i32_e32 v48, v47, v43
	v_min_i32_e32 v43, v47, v43
	v_max_i32_e32 v47, v40, v42
	v_min_i32_e32 v40, v40, v42
	v_max_i32_e32 v42, v36, v37
	v_min_i32_e32 v36, v36, v37
	v_max_i32_e32 v37, v39, v45
	v_min_i32_e32 v39, v39, v45
	v_max_i32_e32 v45, v38, v41
	v_min_i32_e32 v38, v38, v41
	v_max_i32_e32 v41, v35, v44
	v_min_i32_e32 v35, v35, v44
	v_max_i32_e32 v44, v34, v49
	v_min_i32_e32 v34, v34, v49
	v_max_i32_e32 v49, v66, v37
	v_min_i32_e32 v37, v66, v37
	v_max_i32_e32 v66, v48, v45
	v_min_i32_e32 v45, v48, v45
	v_max_i32_e32 v48, v47, v41
	v_min_i32_e32 v41, v47, v41
	v_max_i32_e32 v47, v42, v44
	v_max_i32_e32 v80, v66, v47
	v_min_i32_e32 v124, v66, v47
	ds_read_b128 v[66:69], v94 offset:18432
	ds_read_b128 v[70:73], v94 offset:18464
	v_min_i32_e32 v42, v42, v44
	v_max_i32_e32 v44, v46, v39
	v_min_i32_e32 v74, v46, v39
	v_max_i32_e32 v39, v43, v38
	v_min_i32_e32 v75, v43, v38
	v_max_i32_e32 v38, v40, v35
	v_min_i32_e32 v76, v40, v35
	v_max_i32_e32 v35, v36, v34
	v_min_i32_e32 v77, v36, v34
	v_max_i32_e32 v78, v49, v48
	v_min_i32_e32 v82, v49, v48
	v_max_i32_e32 v125, v37, v41
	v_min_i32_e32 v126, v37, v41
	v_max_i32_e32 v127, v45, v42
	v_min_i32_e32 v128, v45, v42
	v_max_i32_e32 v129, v44, v38
	v_min_i32_e32 v130, v44, v38
	v_max_i32_e32 v131, v39, v35
	v_min_i32_e32 v132, v39, v35
	s_waitcnt vmcnt(3) lgkmcnt(1)
	v_mfma_f32_32x32x16_bf16 v[34:49], v[66:69], v[62:65], v[18:33]
	ds_read_b128 v[66:69], v94 offset:18496
	v_max_i32_e32 v133, v74, v76
	v_min_i32_e32 v134, v74, v76
	v_max_i32_e32 v135, v75, v77
	v_min_i32_e32 v136, v75, v77
	v_max_i32_e32 v79, v78, v80
	v_min_i32_e32 v81, v78, v80
	s_waitcnt vmcnt(2) lgkmcnt(1)
	v_mfma_f32_32x32x16_bf16 v[34:49], v[70:73], v[58:61], v[34:49]
	v_max_i32_e32 v80, v82, v124
	v_min_i32_e32 v78, v82, v124
	v_max_i32_e32 v77, v125, v127
	v_min_i32_e32 v76, v125, v127
	v_max_i32_e32 v75, v126, v128
	v_min_i32_e32 v73, v126, v128
	ds_read_b128 v[124:127], v94 offset:18528
	s_waitcnt vmcnt(1) lgkmcnt(1)
	v_mfma_f32_32x32x16_bf16 v[34:49], v[66:69], v[54:57], v[34:49]
	v_max_i32_e32 v71, v129, v131
	v_min_i32_e32 v74, v129, v131
	v_max_i32_e32 v72, v130, v132
	v_min_i32_e32 v70, v130, v132
	v_max_i32_e32 v69, v133, v135
	v_min_i32_e32 v68, v133, v135
	v_max_i32_e32 v67, v134, v136
	s_waitcnt vmcnt(0) lgkmcnt(0)
; #define LAS __attribute__((address_space(3)))
; #define MFMA32(a, b, c) __builtin_amdgcn_mfma_f32_32x32x16_bf16((a), (b), (c), 0, 0, 0)
; __device__ __forceinline__ void route_task(int task, int tl0, const bf16* QP  , const LAS bf16* KHL, LAS unsigned short* EL, LAS float* GL, int lane) {
;     ...
;         for (int kt = 0; kt < 4; ++kt) {
;             f32x16 X;
; #pragma unroll
;             for (int i = 0; i < 16; ++i) X[i] = 8.f;
;             const LAS bf16* khp = KHL + (half * 128 + 32 * kt + r) * 72 + 8 * hi;
; #pragma unroll
;             for (int ks = 0; ks < 4; ++ks) {
;                 const bf16x8 kh = lds8(khp + 16 * ks);
;                 X = MFMA32(kh, qa[half][ks], X);
;             }
;             int grp[16];
; #pragma unroll
;             for (int i = 0; i < 16; ++i) grp[i] = (int)((__float_as_uint(X[i]) | 127u) - (unsigned)(32 * kt + (i & 3) + 8 * (i >> 2)));
;             sort16_desc(grp);
;             if (kt == 0) {
; #pragma unroll
;                 for (int i = 0; i < 16; ++i) cur[i] = grp[i];
;             } else merge16_desc(cur, grp);
	v_mfma_f32_32x32x16_bf16 v[34:49], v[124:127], v[50:53], v[34:49]
	v_min_i32_e32 v66, v134, v136
	s_nop 10
	v_bitop3_b32 v37, v37, s42, 3 bitop3:0x56
	v_bitop3_b32 v48, v48, s42, 26 bitop3:0x56
	v_bitop3_b32 v38, v38, s42, 8 bitop3:0x56
	v_bitop3_b32 v42, v42, s42, 16 bitop3:0x56
	v_bitop3_b32 v47, v47, s42, 25 bitop3:0x56
	v_bitop3_b32 v39, v39, s42, 9 bitop3:0x56
	v_bitop3_b32 v40, v40, s42, 10 bitop3:0x56
	v_bitop3_b32 v43, v43, s42, 17 bitop3:0x56
	v_bitop3_b32 v44, v44, s42, 18 bitop3:0x56
	v_bitop3_b32 v36, v36, s42, 2 bitop3:0x56
	v_bitop3_b32 v49, v49, s42, 27 bitop3:0x56
	v_bitop3_b32 v41, v41, s42, 11 bitop3:0x56
	v_bitop3_b32 v45, v45, s42, 19 bitop3:0x56
	v_bitop3_b32 v35, v35, s42, 1 bitop3:0x56
	v_bitop3_b32 v46, v46, s42, 24 bitop3:0x56
	v_or_b32_e32 v34, 0x7f, v34
	v_max_i32_e32 v82, v37, v48
	v_max_i32_e32 v124, v38, v42
	v_max_i32_e32 v126, v34, v47
	v_max_i32_e32 v127, v39, v40
	v_min_i32_e32 v130, v43, v44
	v_min_i32_e32 v131, v36, v49
	v_min_i32_e32 v133, v41, v45
	v_min_i32_e32 v134, v35, v46
	v_min_i32_e32 v39, v39, v40
	v_min_i32_e32 v34, v34, v47
	v_min_i32_e32 v38, v38, v42
	v_min_i32_e32 v37, v37, v48
	v_max_i32_e32 v35, v35, v46
	v_max_i32_e32 v41, v41, v45
	v_max_i32_e32 v36, v36, v49
	v_max_i32_e32 v43, v43, v44
	v_min_i32_e32 v125, v82, v124
	v_min_i32_e32 v128, v126, v127
	v_max_i32_e32 v132, v130, v131
	v_max_i32_e32 v135, v133, v134
	v_max_i32_e32 v40, v39, v34
	v_max_i32_e32 v42, v38, v37
	v_min_i32_e32 v45, v35, v41
	v_min_i32_e32 v44, v36, v43
	v_min_i32_e32 v129, v125, v128
	v_max_i32_e32 v47, v40, v42
	v_max_i32_e32 v46, v45, v44
	v_min_i32_e32 v40, v40, v42
	v_min_i32_e32 v42, v45, v44
	v_max_i32_e32 v45, v125, v128
	v_max_i32_e32 v125, v132, v135
	v_min_i32_e32 v128, v45, v125
	v_min_i32_e32 v34, v39, v34
	v_max_i32_e32 v39, v126, v127
	v_max_i32_e32 v35, v35, v41
	v_max_i32_e32 v41, v82, v124
	v_max_i32_e32 v148, v45, v125
	ds_read_b128 v[124:127], v97
	v_max_i32_e32 v44, v40, v42
	v_min_i32_e32 v138, v40, v42
	v_min_i32_e32 v40, v133, v134
	v_min_i32_e32 v37, v38, v37
	v_min_i32_e32 v38, v130, v131
	v_max_i32_e32 v36, v36, v43
	v_min_i32_e32 v136, v132, v135
	v_min_i32_e32 v133, v40, v34
	v_min_i32_e32 v134, v37, v38
	v_max_i32_e32 v34, v40, v34
	v_max_i32_e32 v37, v37, v38
	v_min_i32_e32 v40, v39, v35
	v_min_i32_e32 v42, v36, v41
	v_max_i32_e32 v144, v39, v35
	v_max_i32_e32 v145, v36, v41
	v_max_i32_e32 v137, v129, v136
	v_min_i32_e32 v136, v129, v136
	v_max_i32_e32 v140, v133, v134
	v_min_i32_e32 v141, v34, v37
	v_max_i32_e32 v143, v40, v42
	v_min_i32_e32 v146, v144, v145
	v_max_i32_e32 v149, v47, v46
	v_min_i32_e32 v48, v47, v46
	v_max_i32_e32 v139, v138, v136
	v_max_i32_e32 v142, v140, v141
	v_min_i32_e32 v43, v40, v42
	v_max_i32_e32 v34, v34, v37
	v_min_i32_e32 v147, v143, v146
	v_min_i32_e32 v150, v148, v149
	v_min_i32_e32 v49, v137, v48
	v_min_i32_e32 v132, v44, v128
	v_max_i32_e32 v38, v139, v142
	v_min_i32_e32 v37, v43, v34
	v_max_i32_e32 v34, v43, v34
	v_min_i32_e32 v35, v147, v150
	v_max_i32_e32 v39, v137, v48
	v_max_i32_e32 v40, v44, v128
	v_max_i32_e32 v135, v49, v132
	v_max_i32_e32 v82, v38, v37
	v_min_i32_e32 v36, v34, v35
	v_min_i32_e32 v41, v39, v40
	v_max_i32_e32 v129, v135, v82
	v_min_i32_e32 v42, v36, v41
	v_min_i32_e32 v137, v129, v42
	v_max_i32_e32 v159, v129, v42
	ds_read_b128 v[128:131], v97 offset:32
	v_min_i32_e32 v82, v135, v82
	v_min_i32_e32 v132, v49, v132
	v_min_i32_e32 v135, v38, v37
	v_max_i32_e32 v154, v34, v35
	v_max_i32_e32 v155, v39, v40
	v_max_i32_e32 v157, v36, v41
	s_waitcnt lgkmcnt(1)
	v_mfma_f32_32x32x16_bf16 v[34:49], v[124:127], v[62:65], v[18:33]
	ds_read_b128 v[124:127], v97 offset:64
	v_max_i32_e32 v151, v132, v135
	v_max_i32_e32 v152, v82, v151
	v_min_i32_e32 v136, v138, v136
	v_min_i32_e32 v138, v140, v141
	v_min_i32_e32 v82, v82, v151
	v_max_i32_e32 v147, v147, v150
	s_waitcnt lgkmcnt(1)
	v_mfma_f32_32x32x16_bf16 v[34:49], v[128:131], v[58:61], v[34:49]
	ds_read_b128 v[128:131], v97 offset:96
	v_max_i32_e32 v143, v143, v146
	v_min_i32_e32 v133, v133, v134
	v_min_i32_e32 v156, v154, v155
	v_max_i32_e32 v140, v136, v138
	v_min_i32_e32 v139, v139, v142
	v_max_i32_e32 v142, v154, v155
	s_waitcnt lgkmcnt(1)
	v_mfma_f32_32x32x16_bf16 v[34:49], v[124:127], v[54:57], v[34:49]
	v_max_i32_e32 v124, v148, v149
	v_min_i32_e32 v136, v136, v138
	v_max_i32_e32 v141, v140, v139
	v_min_i32_e32 v139, v140, v139
	v_min_i32_e32 v125, v143, v124
	v_min_i32_e32 v158, v156, v157
	v_min_i32_e32 v132, v132, v135
	s_waitcnt lgkmcnt(0)
; #define LAS __attribute__((address_space(3)))
; #define MFMA32(a, b, c) __builtin_amdgcn_mfma_f32_32x32x16_bf16((a), (b), (c), 0, 0, 0)
; __device__ __forceinline__ void merge16_desc(int (&a)[16], const int (&b)[16]) {
; #pragma unroll
;     for (int i = 0; i < 16; ++i) a[i] = a[i] > b[15 - i] ? a[i] : b[15 - i];
; #pragma unroll
;     for (int j = 8; j > 0; j >>= 1)
; #pragma unroll
;         for (int i = 0; i < 16; ++i) { const int l = i ^ j; if (l > i) ce_desc(a[i], a[l]); }
; }
; __device__ __forceinline__ void route_task(int task, int tl0, const bf16* QP  , const LAS bf16* KHL, LAS unsigned short* EL, LAS float* GL, int lane) {
;     ...
;         for (int kt = 0; kt < 4; ++kt) {
;             f32x16 X;
; #pragma unroll
;             for (int i = 0; i < 16; ++i) X[i] = 8.f;
;             const LAS bf16* khp = KHL + (half * 128 + 32 * kt + r) * 72 + 8 * hi;
; #pragma unroll
;             for (int ks = 0; ks < 4; ++ks) {
;                 const bf16x8 kh = lds8(khp + 16 * ks);
;                 X = MFMA32(kh, qa[half][ks], X);
;             }
;             int grp[16];
; #pragma unroll
;             for (int i = 0; i < 16; ++i) grp[i] = (int)((__float_as_uint(X[i]) | 127u) - (unsigned)(32 * kt + (i & 3) + 8 * (i >> 2)));
;             sort16_desc(grp);
;             if (kt == 0) {
; #pragma unroll
;                 for (int i = 0; i < 16; ++i) cur[i] = grp[i];
;             } else merge16_desc(cur, grp);
	v_mfma_f32_32x32x16_bf16 v[34:49], v[128:131], v[50:53], v[34:49]
	v_min_i32_e32 v126, v147, v125
	v_min_i32_e32 v153, v137, v152
	v_min_i32_e32 v160, v158, v159
	v_min_i32_e32 v135, v141, v132
	v_min_i32_e32 v127, v142, v126
	s_nop 6
	v_bitop3_b32 v37, v37, s42, 35 bitop3:0x56
	v_bitop3_b32 v48, v48, s42, 58 bitop3:0x56
	v_bitop3_b32 v38, v38, s42, 40 bitop3:0x56
	v_bitop3_b32 v42, v42, s42, 48 bitop3:0x56
	v_bitop3_b32 v34, v34, s42, 32 bitop3:0x56
	v_bitop3_b32 v47, v47, s42, 57 bitop3:0x56
	v_bitop3_b32 v39, v39, s42, 41 bitop3:0x56
	v_bitop3_b32 v40, v40, s42, 42 bitop3:0x56
	v_bitop3_b32 v43, v43, s42, 49 bitop3:0x56
	v_bitop3_b32 v44, v44, s42, 50 bitop3:0x56
	v_bitop3_b32 v36, v36, s42, 34 bitop3:0x56
	v_bitop3_b32 v49, v49, s42, 59 bitop3:0x56
	v_bitop3_b32 v41, v41, s42, 43 bitop3:0x56
	v_bitop3_b32 v45, v45, s42, 51 bitop3:0x56
	v_bitop3_b32 v35, v35, s42, 33 bitop3:0x56
	v_bitop3_b32 v46, v46, s42, 56 bitop3:0x56
	v_max_i32_e32 v128, v37, v48
	v_max_i32_e32 v129, v38, v42
	v_max_i32_e32 v131, v34, v47
	v_max_i32_e32 v134, v39, v40
	v_min_i32_e32 v146, v43, v44
	v_min_i32_e32 v148, v36, v49
	v_min_i32_e32 v150, v41, v45
	v_min_i32_e32 v151, v35, v46
	v_min_i32_e32 v39, v39, v40
	v_min_i32_e32 v34, v34, v47
	v_min_i32_e32 v38, v38, v42
	v_min_i32_e32 v37, v37, v48
	v_max_i32_e32 v35, v35, v46
	v_max_i32_e32 v41, v41, v45
	v_max_i32_e32 v36, v36, v49
	v_max_i32_e32 v43, v43, v44
	v_min_i32_e32 v130, v128, v129
	v_min_i32_e32 v138, v131, v134
	v_max_i32_e32 v149, v146, v148
	v_max_i32_e32 v154, v150, v151
	v_max_i32_e32 v40, v39, v34
	v_max_i32_e32 v42, v38, v37
	v_min_i32_e32 v45, v35, v41
	v_min_i32_e32 v44, v36, v43
	v_min_i32_e32 v150, v150, v151
	v_min_i32_e32 v34, v39, v34
	v_min_i32_e32 v37, v38, v37
	v_min_i32_e32 v38, v146, v148
	v_max_i32_e32 v131, v131, v134
	v_max_i32_e32 v35, v35, v41
	v_max_i32_e32 v36, v36, v43
	v_max_i32_e32 v43, v128, v129
	v_min_i32_e32 v140, v130, v138
	v_min_i32_e32 v155, v149, v154
	v_max_i32_e32 v47, v40, v42
	v_max_i32_e32 v46, v45, v44
	v_min_i32_e32 v40, v40, v42
	v_min_i32_e32 v42, v45, v44
	v_max_i32_e32 v45, v130, v138
	v_max_i32_e32 v130, v149, v154
	v_min_i32_e32 v39, v150, v34
	v_min_i32_e32 v146, v37, v38
	v_max_i32_e32 v34, v150, v34
	v_max_i32_e32 v37, v37, v38
	v_min_i32_e32 v41, v131, v35
	v_min_i32_e32 v128, v36, v43
	v_max_i32_e32 v35, v131, v35
	v_max_i32_e32 v36, v36, v43
	v_min_i32_e32 v48, v47, v46
	v_max_i32_e32 v44, v40, v42
	v_min_i32_e32 v138, v45, v130
	v_min_i32_e32 v40, v40, v42
	v_min_i32_e32 v42, v140, v155
	v_max_i32_e32 v148, v39, v146
	v_min_i32_e32 v38, v34, v37
	v_min_i32_e32 v129, v41, v128
	v_max_i32_e32 v41, v41, v128
	v_min_i32_e32 v43, v35, v36
	v_max_i32_e32 v45, v45, v130
	v_max_i32_e32 v46, v47, v46
	v_max_i32_e32 v161, v140, v155
	v_max_i32_e32 v140, v40, v42
	v_max_i32_e32 v150, v148, v38
	v_max_i32_e32 v34, v34, v37
	v_min_i32_e32 v128, v41, v43
	v_min_i32_e32 v47, v45, v46
	v_min_i32_e32 v49, v161, v48
	v_min_i32_e32 v149, v44, v138
	v_max_i32_e32 v151, v140, v150
	v_min_i32_e32 v37, v129, v34
	v_max_i32_e32 v34, v129, v34
	v_min_i32_e32 v129, v128, v47
	v_max_i32_e32 v48, v161, v48
	v_max_i32_e32 v44, v44, v138
	v_max_i32_e32 v154, v49, v149
	v_max_i32_e32 v134, v151, v37
	v_min_i32_e32 v130, v34, v129
	v_min_i32_e32 v131, v48, v44
	v_min_i32_e32 v49, v49, v149
	v_min_i32_e32 v37, v151, v37
	v_max_i32_e32 v34, v34, v129
	v_max_i32_e32 v44, v48, v44
	v_min_i32_e32 v40, v40, v42
	v_min_i32_e32 v38, v148, v38
	v_max_i32_e32 v41, v41, v43
	v_max_i32_e32 v43, v45, v46
	v_max_i32_e32 v155, v154, v134
	v_min_i32_e32 v138, v130, v131
	v_min_i32_e32 v134, v154, v134
	v_max_i32_e32 v149, v49, v37
	v_min_i32_e32 v48, v34, v44
	v_max_i32_e32 v129, v130, v131
	v_max_i32_e32 v42, v40, v38
	v_min_i32_e32 v140, v140, v150
	v_max_i32_e32 v34, v34, v44
	v_max_i32_e32 v44, v128, v47
	v_min_i32_e32 v45, v41, v43
	v_min_i32_e32 v161, v155, v138
	v_max_i32_e32 v151, v134, v149
	v_min_i32_e32 v130, v48, v129
	v_max_i32_e32 v131, v155, v138
	v_max_i32_e32 v148, v42, v140
	v_min_i32_e32 v37, v49, v37
	v_min_i32_e32 v46, v44, v45
	v_min_i32_e32 v154, v161, v151
	v_min_i32_e32 v138, v130, v131
	v_min_i32_e32 v49, v148, v37
	v_min_i32_e32 v134, v134, v149
	v_min_i32_e32 v47, v34, v46
	v_min_i32_e32 v42, v42, v140
	v_min_i32_e32 v38, v40, v38
	v_min_i32_e32 v39, v39, v146
	v_max3_i32 v39, v144, v145, v39
	v_max3_i32 v38, v143, v124, v38
	v_max3_i32 v40, v147, v125, v42
	v_max3_i32 v42, v142, v126, v49
	v_max3_i32 v37, v127, v148, v37
	v_max3_i32 v49, v156, v157, v134
	v_max3_i32 v124, v158, v159, v154
	v_max3_i32 v125, v160, v161, v151
	v_max3_i32 v126, v137, v152, v138
	v_max3_i32 v127, v153, v130, v131
	v_max3_i32 v48, v82, v48, v129
	v_max3_i32 v47, v141, v132, v47
	v_max3_i32 v34, v135, v34, v46
	v_max3_i32 v44, v139, v44, v45
	v_max3_i32 v41, v136, v41, v43
	v_max3_i32 v35, v133, v35, v36
	v_max_i32_e32 v36, v39, v126
	v_min_i32_e32 v39, v39, v126
	v_max_i32_e32 v43, v38, v127
	v_min_i32_e32 v38, v38, v127
	v_max_i32_e32 v45, v40, v48
	v_min_i32_e32 v40, v40, v48
	v_max_i32_e32 v46, v42, v47
	v_min_i32_e32 v42, v42, v47
	v_max_i32_e32 v47, v37, v34
	v_min_i32_e32 v34, v37, v34
	v_max_i32_e32 v37, v49, v44
	v_min_i32_e32 v44, v49, v44
	v_max_i32_e32 v48, v124, v41
	v_min_i32_e32 v41, v124, v41
	v_max_i32_e32 v49, v125, v35
	v_min_i32_e32 v35, v125, v35
	ds_read_b128 v[124:127], v94 offset:27648
	ds_read_b128 v[128:131], v94 offset:27680
	v_max_i32_e32 v82, v36, v47
	v_min_i32_e32 v132, v36, v47
	v_max_i32_e32 v36, v43, v37
	v_min_i32_e32 v133, v43, v37
	v_max_i32_e32 v37, v45, v48
	v_max_i32_e32 v43, v46, v49
	v_min_i32_e32 v134, v45, v48
	v_min_i32_e32 v135, v46, v49
	v_max_i32_e32 v136, v39, v34
	v_min_i32_e32 v137, v39, v34
	v_max_i32_e32 v138, v38, v44
	v_min_i32_e32 v139, v38, v44
	v_max_i32_e32 v140, v40, v41
	v_min_i32_e32 v141, v40, v41
	v_max_i32_e32 v142, v42, v35
	v_min_i32_e32 v143, v42, v35
	v_max_i32_e32 v144, v82, v37
	v_min_i32_e32 v82, v82, v37
	v_max_i32_e32 v145, v36, v43
	v_min_i32_e32 v146, v36, v43
	s_waitcnt lgkmcnt(1)
; #define LAS __attribute__((address_space(3)))
; #define MFMA32(a, b, c) __builtin_amdgcn_mfma_f32_32x32x16_bf16((a), (b), (c), 0, 0, 0)
; __device__ __forceinline__ void merge16_desc(int (&a)[16], const int (&b)[16]) {
; #pragma unroll
;     for (int i = 0; i < 16; ++i) a[i] = a[i] > b[15 - i] ? a[i] : b[15 - i];
; #pragma unroll
;     for (int j = 8; j > 0; j >>= 1)
; #pragma unroll
;         for (int i = 0; i < 16; ++i) { const int l = i ^ j; if (l > i) ce_desc(a[i], a[l]); }
; }
; __device__ __forceinline__ void route_task(int task, int tl0, const bf16* QP  , const LAS bf16* KHL, LAS unsigned short* EL, LAS float* GL, int lane) {
;     ...
;         for (int kt = 0; kt < 4; ++kt) {
;             f32x16 X;
; #pragma unroll
;             for (int i = 0; i < 16; ++i) X[i] = 8.f;
;             const LAS bf16* khp = KHL + (half * 128 + 32 * kt + r) * 72 + 8 * hi;
; #pragma unroll
;             for (int ks = 0; ks < 4; ++ks) {
;                 const bf16x8 kh = lds8(khp + 16 * ks);
;                 X = MFMA32(kh, qa[half][ks], X);
;             }
;             int grp[16];
; #pragma unroll
;             for (int i = 0; i < 16; ++i) grp[i] = (int)((__float_as_uint(X[i]) | 127u) - (unsigned)(32 * kt + (i & 3) + 8 * (i >> 2)));
;             sort16_desc(grp);
;             if (kt == 0) {
; #pragma unroll
;                 for (int i = 0; i < 16; ++i) cur[i] = grp[i];
;             } else merge16_desc(cur, grp);
	v_mfma_f32_32x32x16_bf16 v[34:49], v[124:127], v[62:65], v[18:33]
	ds_read_b128 v[124:127], v94 offset:27712
	v_max_i32_e32 v147, v132, v134
	v_min_i32_e32 v132, v132, v134
	v_max_i32_e32 v134, v133, v135
	v_min_i32_e32 v133, v133, v135
	v_max_i32_e32 v135, v136, v140
	v_min_i32_e32 v136, v136, v140
	s_waitcnt lgkmcnt(1)
	v_mfma_f32_32x32x16_bf16 v[34:49], v[128:131], v[58:61], v[34:49]
	ds_read_b128 v[128:131], v94 offset:27744
	v_max_i32_e32 v140, v138, v142
	v_min_i32_e32 v138, v138, v142
	v_max_i32_e32 v142, v137, v141
	v_min_i32_e32 v137, v137, v141
	v_max_i32_e32 v141, v139, v143
	v_min_i32_e32 v139, v139, v143
	s_waitcnt lgkmcnt(1)
	v_mfma_f32_32x32x16_bf16 v[34:49], v[124:127], v[54:57], v[34:49]
	v_min_i32_e32 v143, v144, v145
	v_min_i32_e32 v124, v82, v146
	v_min_i32_e32 v127, v135, v140
	v_min_i32_e32 v125, v147, v134
	v_min_i32_e32 v126, v132, v133
	v_min_i32_e32 v149, v142, v141
	v_min_i32_e32 v148, v136, v138
	s_waitcnt lgkmcnt(0)
	v_mfma_f32_32x32x16_bf16 v[34:49], v[128:131], v[50:53], v[34:49]
	v_min_i32_e32 v150, v137, v139
	s_nop 10
	v_and_or_b32 v37, v37, s43, 60
	v_and_or_b32 v48, v48, s43, 37
	v_and_or_b32 v38, v38, s43, 55
	v_and_or_b32 v42, v42, s43, 47
	v_bitop3_b32 v34, v34, s42, 64 bitop3:0x56
	v_and_or_b32 v47, v47, s43, 38
	v_and_or_b32 v39, v39, s43, 54
	v_and_or_b32 v40, v40, s43, 53
	v_and_or_b32 v43, v43, s43, 46
	v_and_or_b32 v44, v44, s43, 45
	v_and_or_b32 v36, v36, s43, 61
	v_and_or_b32 v49, v49, s43, 36
	v_and_or_b32 v41, v41, s43, 52
	v_and_or_b32 v45, v45, s43, 44
	v_and_or_b32 v35, v35, s43, 62
	v_and_or_b32 v46, v46, s43, 39
	v_max_i32_e32 v128, v37, v48
	v_max_i32_e32 v129, v38, v42
	v_max_i32_e32 v131, v34, v47
	v_max_i32_e32 v151, v39, v40
	v_min_i32_e32 v154, v43, v44
	v_min_i32_e32 v155, v36, v49
	v_min_i32_e32 v157, v41, v45
	v_min_i32_e32 v158, v35, v46
	v_min_i32_e32 v39, v39, v40
	v_min_i32_e32 v34, v34, v47
	v_min_i32_e32 v38, v38, v42
	v_min_i32_e32 v37, v37, v48
	v_max_i32_e32 v35, v35, v46
	v_max_i32_e32 v41, v41, v45
	v_max_i32_e32 v36, v36, v49
	v_max_i32_e32 v43, v43, v44
	v_min_i32_e32 v130, v128, v129
	v_min_i32_e32 v152, v131, v151
	v_max_i32_e32 v156, v154, v155
	v_max_i32_e32 v159, v157, v158
	v_max_i32_e32 v40, v39, v34
	v_max_i32_e32 v42, v38, v37
	v_min_i32_e32 v45, v35, v41
	v_min_i32_e32 v44, v36, v43
	v_min_i32_e32 v157, v157, v158
	v_min_i32_e32 v34, v39, v34
	v_min_i32_e32 v37, v38, v37
	v_min_i32_e32 v38, v154, v155
	v_max_i32_e32 v131, v131, v151
	v_max_i32_e32 v35, v35, v41
	v_max_i32_e32 v36, v36, v43
	v_max_i32_e32 v43, v128, v129
	v_min_i32_e32 v153, v130, v152
	v_min_i32_e32 v160, v156, v159
	v_max_i32_e32 v47, v40, v42
	v_max_i32_e32 v46, v45, v44
	v_min_i32_e32 v40, v40, v42
	v_min_i32_e32 v42, v45, v44
	v_max_i32_e32 v45, v130, v152
	v_max_i32_e32 v130, v156, v159
	v_min_i32_e32 v39, v157, v34
	v_min_i32_e32 v154, v37, v38
	v_max_i32_e32 v34, v157, v34
	v_max_i32_e32 v37, v37, v38
	v_min_i32_e32 v41, v131, v35
	v_min_i32_e32 v128, v36, v43
	v_max_i32_e32 v35, v131, v35
	v_max_i32_e32 v36, v36, v43
	v_min_i32_e32 v48, v47, v46
	v_max_i32_e32 v44, v40, v42
	v_min_i32_e32 v152, v45, v130
	v_min_i32_e32 v40, v40, v42
	v_min_i32_e32 v42, v153, v160
	v_max_i32_e32 v155, v39, v154
	v_min_i32_e32 v38, v34, v37
	v_min_i32_e32 v129, v41, v128
	v_max_i32_e32 v41, v41, v128
	v_min_i32_e32 v43, v35, v36
	v_max_i32_e32 v45, v45, v130
	v_max_i32_e32 v46, v47, v46
	v_max_i32_e32 v161, v153, v160
	v_max_i32_e32 v153, v40, v42
	v_max_i32_e32 v157, v155, v38
	v_max_i32_e32 v34, v34, v37
	v_min_i32_e32 v128, v41, v43
	v_min_i32_e32 v47, v45, v46
	v_min_i32_e32 v49, v161, v48
	v_min_i32_e32 v156, v44, v152
	v_max_i32_e32 v158, v153, v157
	v_min_i32_e32 v37, v129, v34
	v_max_i32_e32 v34, v129, v34
	v_min_i32_e32 v129, v128, v47
	v_max_i32_e32 v48, v161, v48
	v_max_i32_e32 v44, v44, v152
	v_min_i32_e32 v40, v40, v42
	v_min_i32_e32 v38, v155, v38
	v_max_i32_e32 v159, v49, v156
	v_max_i32_e32 v151, v158, v37
	v_min_i32_e32 v130, v34, v129
	v_min_i32_e32 v131, v48, v44
	v_min_i32_e32 v49, v49, v156
	v_min_i32_e32 v37, v158, v37
	v_max_i32_e32 v34, v34, v129
	v_max_i32_e32 v44, v48, v44
	v_max_i32_e32 v42, v40, v38
	v_min_i32_e32 v153, v153, v157
	v_max_i32_e32 v160, v159, v151
	v_min_i32_e32 v152, v130, v131
	v_max_i32_e32 v156, v49, v37
	v_min_i32_e32 v48, v34, v44
	v_max_i32_e32 v129, v130, v131
	v_max_i32_e32 v155, v42, v153
	v_min_i32_e32 v37, v49, v37
	v_min_i32_e32 v151, v159, v151
	v_min_i32_e32 v130, v48, v129
	v_max_i32_e32 v131, v160, v152
	v_min_i32_e32 v49, v155, v37
	v_max_i32_e32 v41, v41, v43
	v_max_i32_e32 v43, v45, v46
	v_min_i32_e32 v42, v42, v153
	v_min_i32_e32 v38, v40, v38
	v_min_i32_e32 v161, v160, v152
	v_max_i32_e32 v158, v151, v156
	v_min_i32_e32 v151, v151, v156
	v_max_i32_e32 v34, v34, v44
	v_max_i32_e32 v44, v128, v47
	v_min_i32_e32 v45, v41, v43
	v_max_i32_e32 v40, v41, v43
	v_max_i32_e32 v38, v143, v38
	v_max3_i32 v41, v82, v146, v42
	v_max_i32_e32 v42, v124, v49
	v_max3_i32 v124, v127, v130, v131
	v_min_i32_e32 v46, v44, v45
	v_max_i32_e32 v43, v125, v151
	v_max3_i32 v49, v126, v161, v158
	v_max3_i32 v44, v149, v44, v45
	v_max_i32_e32 v45, v38, v124
	v_min_i32_e32 v38, v38, v124
	ds_read_b128 v[124:127], v98
	v_min_i32_e32 v159, v161, v158
	v_min_i32_e32 v152, v130, v131
	v_max_i32_e32 v37, v155, v37
	v_max_i32_e32 v48, v48, v129
	v_min_i32_e32 v47, v34, v46
	v_max_i32_e32 v34, v34, v46
	v_min_i32_e32 v39, v39, v154
	v_max3_i32 v39, v144, v145, v39
	v_max3_i32 v37, v147, v134, v37
	v_max3_i32 v46, v132, v133, v159
	v_max3_i32 v82, v135, v140, v152
	v_max3_i32 v48, v136, v138, v48
	v_max_i32_e32 v47, v148, v47
	v_max3_i32 v34, v142, v141, v34
	v_max3_i32 v40, v137, v139, v40
	v_max3_i32 v35, v150, v35, v36
	v_max_i32_e32 v36, v39, v82
	v_min_i32_e32 v39, v39, v82
	v_max_i32_e32 v82, v41, v48
	v_min_i32_e32 v41, v41, v48
	v_max_i32_e32 v48, v42, v47
	v_min_i32_e32 v42, v42, v47
	v_max_i32_e32 v47, v37, v34
	v_min_i32_e32 v34, v37, v34
	v_max_i32_e32 v37, v43, v44
	v_min_i32_e32 v43, v43, v44
	v_max_i32_e32 v44, v46, v40
	v_min_i32_e32 v40, v46, v40
	v_max_i32_e32 v46, v49, v35
	v_min_i32_e32 v35, v49, v35
	v_max_i32_e32 v49, v36, v47
	v_min_i32_e32 v132, v36, v47
	v_max_i32_e32 v36, v45, v37
	v_min_i32_e32 v133, v45, v37
	v_max_i32_e32 v37, v82, v44
	v_min_i32_e32 v82, v82, v44
	v_max_i32_e32 v44, v48, v46
	ds_read_b128 v[128:131], v98 offset:32
	v_min_i32_e32 v134, v48, v46
	v_max_i32_e32 v135, v39, v34
	v_min_i32_e32 v136, v39, v34
	v_max_i32_e32 v137, v38, v43
	v_min_i32_e32 v138, v38, v43
	v_max_i32_e32 v139, v41, v40
	v_min_i32_e32 v140, v41, v40
	v_max_i32_e32 v141, v42, v35
	v_min_i32_e32 v142, v42, v35
	v_max_i32_e32 v143, v49, v37
	v_min_i32_e32 v144, v49, v37
	v_max_i32_e32 v145, v36, v44
	v_min_i32_e32 v146, v36, v44
	s_waitcnt lgkmcnt(1)
; #define LAS __attribute__((address_space(3)))
; #define MFMA32(a, b, c) __builtin_amdgcn_mfma_f32_32x32x16_bf16((a), (b), (c), 0, 0, 0)
; __device__ __forceinline__ void merge16_desc(int (&a)[16], const int (&b)[16]) {
; #pragma unroll
;     for (int i = 0; i < 16; ++i) a[i] = a[i] > b[15 - i] ? a[i] : b[15 - i];
; #pragma unroll
;     for (int j = 8; j > 0; j >>= 1)
; #pragma unroll
;         for (int i = 0; i < 16; ++i) { const int l = i ^ j; if (l > i) ce_desc(a[i], a[l]); }
; }
; __device__ __forceinline__ void route_task(int task, int tl0, const bf16* QP  , const LAS bf16* KHL, LAS unsigned short* EL, LAS float* GL, int lane) {
;     ...
;         for (int kt = 0; kt < 4; ++kt) {
;             f32x16 X;
; #pragma unroll
;             for (int i = 0; i < 16; ++i) X[i] = 8.f;
;             const LAS bf16* khp = KHL + (half * 128 + 32 * kt + r) * 72 + 8 * hi;
; #pragma unroll
;             for (int ks = 0; ks < 4; ++ks) {
;                 const bf16x8 kh = lds8(khp + 16 * ks);
;                 X = MFMA32(kh, qa[half][ks], X);
;             }
;             int grp[16];
; #pragma unroll
;             for (int i = 0; i < 16; ++i) grp[i] = (int)((__float_as_uint(X[i]) | 127u) - (unsigned)(32 * kt + (i & 3) + 8 * (i >> 2)));
;             sort16_desc(grp);
;             if (kt == 0) {
; #pragma unroll
;                 for (int i = 0; i < 16; ++i) cur[i] = grp[i];
;             } else merge16_desc(cur, grp);
	v_mfma_f32_32x32x16_bf16 v[34:49], v[124:127], v[62:65], v[18:33]
	v_max_i32_e32 v147, v132, v82
	s_nop 5
	ds_read_b128 v[18:21], v98 offset:64
	ds_read_b128 v[22:25], v98 offset:96
	s_waitcnt lgkmcnt(2)
	v_mfma_f32_32x32x16_bf16 v[34:49], v[128:131], v[58:61], v[34:49]
	v_min_i32_e32 v26, v132, v82
	v_max_i32_e32 v27, v133, v134
	v_min_i32_e32 v30, v135, v139
	v_min_i32_e32 v32, v137, v141
	v_max_i32_e32 v33, v136, v140
	v_max_i32_e32 v59, v138, v142
	v_min_i32_e32 v28, v133, v134
	s_waitcnt lgkmcnt(1)
	v_mfma_f32_32x32x16_bf16 v[34:49], v[18:21], v[54:57], v[34:49]
	v_min_i32_e32 v19, v147, v27
	v_min_i32_e32 v54, v30, v32
	v_min_i32_e32 v55, v33, v59
	v_max_i32_e32 v29, v135, v139
	v_max_i32_e32 v31, v137, v141
	v_min_i32_e32 v58, v136, v140
	v_min_i32_e32 v60, v138, v142
	s_waitcnt lgkmcnt(0)
	v_mfma_f32_32x32x16_bf16 v[34:49], v[22:25], v[50:53], v[34:49]
	v_min_i32_e32 v18, v144, v146
	v_min_i32_e32 v61, v143, v145
	v_min_i32_e32 v20, v26, v28
	v_min_i32_e32 v21, v29, v31
	v_min_i32_e32 v56, v58, v60
	s_nop 6
	v_or_b32_e32 v22, 0x7f, v41
	v_or_b32_e32 v23, 0x7f, v45
	v_or_b32_e32 v25, 0x7f, v35
	v_or_b32_e32 v35, 0x7f, v46
	v_and_or_b32 v39, v39, s43, 22
	v_and_or_b32 v40, v40, s43, 21
	v_and_or_b32 v34, v34, s43, 31
	v_and_or_b32 v47, v47, s43, 6
	v_and_or_b32 v38, v38, s43, 23
	v_and_or_b32 v42, v42, s43, 15
	v_and_or_b32 v37, v37, s43, 28
	v_and_or_b32 v48, v48, s43, 5
	v_and_or_b32 v43, v43, s43, 14
	v_and_or_b32 v44, v44, s43, 13
	v_and_or_b32 v36, v36, s43, 29
	v_and_or_b32 v49, v49, s43, 4
	v_add_u32_e32 v22, 0xffffff95, v22
	v_add_u32_e32 v23, 0xffffff8d, v23
	v_add_u32_e32 v25, 0xffffff9f, v25
	v_add_u32_e32 v35, 0xffffff88, v35
	v_min_i32_e32 v24, v22, v23
	v_min_i32_e32 v41, v25, v35
	v_min_i32_e32 v46, v39, v40
	v_min_i32_e32 v50, v34, v47
	v_min_i32_e32 v53, v38, v42
	v_min_i32_e32 v57, v37, v48
	v_min_i32_e32 v63, v43, v44
	v_min_i32_e32 v64, v36, v49
	v_max_i32_e32 v34, v34, v47
	v_max_i32_e32 v39, v39, v40
	v_max_i32_e32 v25, v25, v35
	v_max_i32_e32 v22, v22, v23
	v_max_i32_e32 v36, v36, v49
	v_max_i32_e32 v43, v43, v44
	v_max_i32_e32 v37, v37, v48
	v_max_i32_e32 v38, v38, v42
	v_min_i32_e32 v45, v24, v41
	v_min_i32_e32 v51, v46, v50
	v_max_i32_e32 v40, v34, v39
	v_max_i32_e32 v23, v25, v22
	v_max_i32_e32 v44, v36, v43
	v_max_i32_e32 v42, v37, v38
	v_min_i32_e32 v37, v37, v38
	v_min_i32_e32 v34, v34, v39
	v_max_i32_e32 v39, v63, v64
	v_max_i32_e32 v24, v24, v41
	v_max_i32_e32 v46, v46, v50
	v_max_i32_e32 v50, v53, v57
	v_min_i32_e32 v22, v25, v22
	v_min_i32_e32 v25, v36, v43
	v_min_i32_e32 v62, v53, v57
	v_min_i32_e32 v65, v63, v64
	v_min_i32_e32 v35, v40, v23
	v_min_i32_e32 v47, v44, v42
	v_max_i32_e32 v23, v40, v23
	v_max_i32_e32 v40, v44, v42
	v_max_i32_e32 v38, v37, v34
	v_max_i32_e32 v41, v39, v24
	v_max_i32_e32 v53, v46, v50
	v_max_i32_e32 v36, v22, v25
	v_min_i32_e32 v46, v46, v50
	v_min_i32_e32 v22, v22, v25
	v_min_i32_e32 v52, v45, v51
	v_min_i32_e32 v82, v62, v65
	v_min_i32_e32 v48, v35, v47
	v_max_i32_e32 v45, v45, v51
	v_max_i32_e32 v49, v62, v65
	v_max_i32_e32 v35, v35, v47
	v_min_i32_e32 v42, v23, v40
	v_max_i32_e32 v47, v38, v41
	v_max_i32_e32 v43, v53, v36
	v_min_i32_e32 v34, v37, v34
	v_min_i32_e32 v24, v39, v24
	v_max_i32_e32 v25, v46, v22
	v_min_i32_e32 v38, v38, v41
	v_max_i32_e32 v51, v45, v49
	v_min_i32_e32 v44, v35, v42
	v_min_i32_e32 v57, v47, v43
	v_max_i32_e32 v37, v34, v24
	v_min_i32_e32 v36, v53, v36
	v_max_i32_e32 v41, v25, v38
	v_min_i32_e32 v25, v25, v38
	v_min_i32_e32 v22, v46, v22
	v_min_i32_e32 v24, v34, v24
	v_max_i32_e32 v38, v52, v82
	v_min_i32_e32 v45, v45, v49
	v_max_i32_e32 v62, v48, v51
	v_min_i32_e32 v63, v44, v57
	v_max_i32_e32 v39, v37, v36
	v_max_i32_e32 v34, v22, v24
	v_max_i32_e32 v46, v38, v45
	v_max_i32_e32 v64, v62, v63
	v_max_i32_e32 v50, v39, v41
	v_min_i32_e32 v62, v62, v63
	v_min_i32_e32 v39, v39, v41
	v_min_i32_e32 v36, v37, v36
	v_max_i32_e32 v49, v34, v46
	v_min_i32_e32 v48, v48, v51
	v_min_i32_e32 v22, v22, v24
	v_min_i32_e32 v24, v38, v45
	v_min_i32_e32 v53, v64, v50
	v_max_i32_e32 v41, v62, v39
	v_max_i32_e32 v37, v36, v25
	v_max_i32_e32 v51, v49, v48
	v_max_i32_e32 v38, v22, v24
	v_min_i32_e32 v34, v34, v46
	v_min_i32_e32 v25, v36, v25
	v_min_i32_e32 v36, v49, v48
	v_min_i32_e32 v124, v52, v82
	v_max_i32_e32 v52, v37, v51
	v_min_i32_e32 v39, v62, v39
	v_max_i32_e32 v45, v38, v34
	v_min_i32_e32 v46, v25, v36
	v_max_i32_e32 v35, v35, v42
	v_max_i32_e32 v42, v47, v43
	v_min_i32_e32 v34, v38, v34
	v_max_i32_e32 v38, v53, v41
	v_min_i32_e32 v37, v37, v51
	v_max_i32_e32 v25, v25, v36
	v_max_i32_e32 v48, v45, v46
	v_max_i32_e32 v44, v44, v57
	v_min_i32_e32 v43, v35, v42
	v_max3_i32 v30, v30, v32, v38
	v_min_i32_e32 v38, v52, v39
	v_max_i32_e32 v36, v37, v25
	v_min_i32_e32 v25, v37, v25
	v_min_i32_e32 v63, v53, v41
	v_max_i32_e32 v62, v52, v39
	v_max3_i32 v27, v147, v27, v48
	v_max_i32_e32 v48, v64, v50
	v_min_i32_e32 v47, v44, v43
	v_min_i32_e32 v39, v38, v36
	v_max_i32_e32 v19, v19, v25
	v_max3_i32 v25, v55, v44, v43
	v_min_i32_e32 v43, v45, v46
	v_min_i32_e32 v65, v63, v62
	v_max_i32_e32 v49, v48, v47
	v_max3_i32 v26, v26, v28, v39
	v_max_i32_e32 v28, v35, v42
	v_min_i32_e32 v22, v22, v24
	v_max_i32_e32 v18, v18, v43
	v_min_i32_e32 v43, v48, v47
	v_max3_i32 v124, v143, v145, v124
	v_max3_i32 v29, v29, v31, v65
	v_max3_i32 v33, v33, v59, v49
	v_max3_i32 v34, v144, v146, v34
	v_max3_i32 v28, v58, v60, v28
	v_max_i32_e32 v22, v61, v22
	v_max3_i32 v21, v21, v63, v62
	v_max_i32_e32 v43, v54, v43
	v_max3_i32 v20, v20, v38, v36
	v_max3_i32 v23, v56, v23, v40
	v_min_i32_e32 v31, v124, v29
	v_min_i32_e32 v49, v27, v33
	v_min_i32_e32 v32, v34, v30
	v_min_i32_e32 v35, v26, v28
; __device__ __forceinline__ void route_task(int task, int tl0, const bf16* QP  , const LAS bf16* KHL, LAS unsigned short* EL, LAS float* GL, int lane) {
;     ...
;         { const unsigned h4 = 4u * (unsigned)hi;
; #pragma unroll
;           for (int i = 0; i < 16; ++i) cur[i] -= (int)h4; }
;         int oth[16];
; #pragma unroll
;         for (int i = 0; i < 16; ++i) oth[i] = __shfl_xor(cur[i], 32);
;         merge16_desc(cur, oth);
; #pragma unroll
;         for (int i = 0; i < 16; ++i) top[half][i] = cur[i];
;     }
;     unsigned P1[4], P2[4];
; #pragma unroll
;     for (int q = 0; q < 4; ++q) { P1[q] = 0u; P2[q] = 0u;
; #pragma unroll
;         for (int s = 0; s < 4; ++s) { P1[q] |= (127u - ((unsigned)top[0][4 * q + s] & 127u)) << (8 * s); P2[q] |= (127u - ((unsigned)top[1][4 * q + s] & 127u)) << (8 * s); } }
	v_min_i32_e32 v24, v22, v21
	v_min_i32_e32 v37, v19, v25
	v_min_i32_e32 v44, v18, v43
	v_min_i32_e32 v36, v20, v23
	v_max_i32_e32 v29, v124, v29
	v_max_i32_e32 v27, v27, v33
	v_max_i32_e32 v30, v34, v30
	v_max_i32_e32 v26, v26, v28
	v_max_i32_e32 v21, v22, v21
	v_max_i32_e32 v19, v19, v25
	v_max_i32_e32 v18, v18, v43
	v_max_i32_e32 v20, v20, v23
	v_max_i32_e32 v33, v29, v27
	v_max_i32_e32 v28, v30, v26
	v_max_i32_e32 v22, v21, v19
	v_max_i32_e32 v23, v18, v20
	v_max_i32_e32 v34, v33, v28
	v_max_i32_e32 v25, v22, v23
	v_min_i32_e32 v28, v33, v28
	v_min_i32_e32 v22, v22, v23
	v_min_i32_e32 v27, v29, v27
	v_min_i32_e32 v26, v30, v26
	v_min_i32_e32 v19, v21, v19
	v_min_i32_e32 v18, v18, v20
	v_max_i32_e32 v23, v28, v22
	v_min_i32_e32 v22, v28, v22
	v_max_i32_e32 v28, v27, v26
	v_max_i32_e32 v20, v19, v18
	v_min_i32_e32 v26, v27, v26
	v_min_i32_e32 v18, v19, v18
	v_min_i32_e32 v42, v24, v37
	v_max_i32_e32 v19, v26, v18
	v_min_i32_e32 v18, v26, v18
	v_max_i32_e32 v26, v31, v49
	v_max_i32_e32 v27, v32, v35
	v_max_i32_e32 v24, v24, v37
	v_max_i32_e32 v29, v44, v36
	v_min_i32_e32 v50, v31, v49
	v_min_i32_e32 v39, v32, v35
	v_min_i32_e32 v38, v44, v36
	v_max_i32_e32 v21, v28, v20
	v_min_i32_e32 v20, v28, v20
	v_max_i32_e32 v28, v26, v27
	v_max_i32_e32 v30, v24, v29
	v_min_i32_e32 v26, v26, v27
	v_min_i32_e32 v24, v24, v29
	v_min_i32_e32 v41, v50, v39
	v_min_i32_e32 v40, v42, v38
	v_max_i32_e32 v27, v26, v24
	v_min_i32_e32 v24, v26, v24
	v_max_i32_e32 v26, v50, v39
	v_max_i32_e32 v29, v42, v38
	v_min_i32_e32 v45, v41, v40
	v_max_i32_e32 v43, v34, v25
	v_min_i32_e32 v25, v34, v25
	v_max_i32_e32 v31, v28, v30
	v_min_i32_e32 v28, v28, v30
	v_max_i32_e32 v30, v26, v29
	v_min_i32_e32 v26, v26, v29
	v_max_i32_e32 v29, v41, v40
	v_sub_u32_e32 v32, v43, v87
	v_sub_u32_e32 v25, v25, v87
	v_sub_u32_e32 v23, v23, v87
	v_sub_u32_e32 v22, v22, v87
	v_sub_u32_e32 v21, v21, v87
	v_sub_u32_e32 v20, v20, v87
	v_sub_u32_e32 v19, v19, v87
	v_sub_u32_e32 v18, v18, v87
	v_sub_u32_e32 v31, v31, v87
	v_sub_u32_e32 v28, v28, v87
	v_sub_u32_e32 v27, v27, v87
	v_sub_u32_e32 v24, v24, v87
	v_sub_u32_e32 v30, v30, v87
	v_sub_u32_e32 v26, v26, v87
	v_sub_u32_e32 v29, v29, v87
	v_sub_u32_e32 v33, v45, v87
	ds_bpermute_b32 v34, v123, v32
	ds_bpermute_b32 v35, v123, v25
	ds_bpermute_b32 v36, v123, v23
	ds_bpermute_b32 v37, v123, v22
	ds_bpermute_b32 v38, v123, v21
	ds_bpermute_b32 v39, v123, v20
	ds_bpermute_b32 v40, v123, v19
	ds_bpermute_b32 v41, v123, v18
	ds_bpermute_b32 v42, v123, v31
	ds_bpermute_b32 v43, v123, v28
	ds_bpermute_b32 v44, v123, v27
	ds_bpermute_b32 v45, v123, v33
	ds_bpermute_b32 v46, v123, v29
	ds_bpermute_b32 v47, v123, v26
	ds_bpermute_b32 v48, v123, v30
	ds_bpermute_b32 v49, v123, v24
	s_waitcnt lgkmcnt(4)
	v_max_i32_e32 v32, v32, v45
	s_waitcnt lgkmcnt(3)
	v_max_i32_e32 v25, v25, v46
	s_waitcnt lgkmcnt(2)
	v_max_i32_e32 v23, v23, v47
	s_waitcnt lgkmcnt(1)
	v_max_i32_e32 v22, v22, v48
	s_waitcnt lgkmcnt(0)
	v_max_i32_e32 v21, v21, v49
	v_max_i32_e32 v20, v20, v44
	v_max_i32_e32 v19, v19, v43
	v_max_i32_e32 v18, v18, v42
	v_max_i32_e32 v31, v31, v41
	v_max_i32_e32 v28, v28, v40
	v_max_i32_e32 v27, v27, v39
	v_max_i32_e32 v24, v24, v38
	v_max_i32_e32 v30, v30, v37
	v_max_i32_e32 v26, v26, v36
	v_max_i32_e32 v29, v29, v35
	v_max_i32_e32 v33, v33, v34
	v_max_i32_e32 v34, v32, v31
	v_min_i32_e32 v31, v32, v31
	v_max_i32_e32 v32, v25, v28
	v_min_i32_e32 v25, v25, v28
	v_max_i32_e32 v28, v23, v27
	v_min_i32_e32 v23, v23, v27
	v_max_i32_e32 v27, v22, v24
	v_min_i32_e32 v22, v22, v24
	v_max_i32_e32 v24, v21, v30
	v_min_i32_e32 v21, v21, v30
	v_max_i32_e32 v30, v20, v26
	v_min_i32_e32 v20, v20, v26
	v_max_i32_e32 v26, v19, v29
	v_min_i32_e32 v19, v19, v29
	v_max_i32_e32 v29, v18, v33
	v_min_i32_e32 v18, v18, v33
	v_max_i32_e32 v33, v34, v24
	v_min_i32_e32 v24, v34, v24
	v_max_i32_e32 v34, v32, v30
	v_min_i32_e32 v30, v32, v30
	v_max_i32_e32 v32, v28, v26
	v_min_i32_e32 v26, v28, v26
	v_max_i32_e32 v28, v27, v29
	v_min_i32_e32 v27, v27, v29
	v_max_i32_e32 v29, v31, v21
	v_min_i32_e32 v21, v31, v21
	v_max_i32_e32 v31, v25, v20
	v_min_i32_e32 v20, v25, v20
	v_max_i32_e32 v25, v23, v19
	v_min_i32_e32 v19, v23, v19
	v_max_i32_e32 v23, v22, v18
	v_min_i32_e32 v18, v22, v18
	v_max_i32_e32 v22, v33, v32
	v_min_i32_e32 v32, v33, v32
	v_max_i32_e32 v33, v34, v28
	v_min_i32_e32 v28, v34, v28
	v_max_i32_e32 v34, v24, v26
	v_min_i32_e32 v24, v24, v26
	v_max_i32_e32 v35, v30, v27
	v_min_i32_e32 v27, v30, v27
	v_max_i32_e32 v30, v29, v25
	v_min_i32_e32 v25, v29, v25
	v_max_i32_e32 v29, v31, v23
	v_min_i32_e32 v23, v31, v23
	v_max_i32_e32 v31, v21, v19
	v_min_i32_e32 v19, v21, v19
	v_max_i32_e32 v21, v20, v18
	v_min_i32_e32 v18, v20, v18
	v_max_i32_e32 v26, v22, v33
	v_min_i32_e32 v33, v22, v33
	v_lshlrev_b32_e32 v20, 8, v81
	v_lshlrev_b32_e32 v22, 16, v80
	v_max_i32_e32 v36, v32, v28
	v_max_i32_e32 v40, v19, v18
	v_min_i32_e32 v41, v19, v18
	v_and_b32_e32 v18, 0x7f, v79
	v_and_b32_e32 v20, 0x7f00, v20
	v_and_b32_e32 v22, 0x7f0000, v22
	v_max_i32_e32 v39, v31, v21
	v_min_i32_e32 v31, v31, v21
	v_lshlrev_b32_e32 v21, 8, v33
	v_or3_b32 v18, v20, v18, v22
	v_lshlrev_b32_e32 v20, 16, v36
	v_and_b32_e32 v19, 0x7f, v26
	v_and_b32_e32 v21, 0x7f00, v21
	v_and_b32_e32 v20, 0x7f0000, v20
	v_or3_b32 v20, v21, v19, v20
	v_lshlrev_b32_e32 v19, 24, v78
	v_min_i32_e32 v28, v32, v28
	v_and_b32_e32 v19, 0x7f000000, v19
	v_bitop3_b32 v19, v18, s68, v19 bitop3:0x36
	v_lshlrev_b32_e32 v18, 24, v28
	v_max_i32_e32 v32, v34, v35
	v_min_i32_e32 v34, v34, v35
	v_max_i32_e32 v35, v24, v27
	v_min_i32_e32 v27, v24, v27
	v_and_b32_e32 v18, 0x7f000000, v18
	v_lshlrev_b32_e32 v22, 8, v76
	v_lshlrev_b32_e32 v24, 16, v75
; __device__ __forceinline__ void route_task(int task, int tl0, const bf16* QP  , const LAS bf16* KHL, LAS unsigned short* EL, LAS float* GL, int lane) {
;     ...
;     unsigned P1[4], P2[4];
; #pragma unroll
;     for (int q = 0; q < 4; ++q) { P1[q] = 0u; P2[q] = 0u;
; #pragma unroll
;         for (int s = 0; s < 4; ++s) { P1[q] |= (127u - ((unsigned)top[0][4 * q + s] & 127u)) << (8 * s); P2[q] |= (127u - ((unsigned)top[1][4 * q + s] & 127u)) << (8 * s); } }
;     int bk[16];
;     {
;         int hi2 = hi; asm volatile("" : "+v"(hi2));
;         const bool h1 = hi2 != 0;
;         constexpr int A1[16] = {1, 1, 1, 1, 1, 1, 1, 1, 2, 2, 2, 2, 2, 3, 3, 3}, B1[16] = {0, 1, 2, 3, 4, 5, 6, 7, 0, 1, 2, 3, 4, 0, 1, 2};
; #pragma unroll
;         for (int i = 0; i < 16; ++i) { const float ta = __int_as_float(h1 ? top[0][A1[i]] : top[0][0]), tb = __int_as_float(h1 ? top[1][B1[i]] : top[1][i]); const unsigned code = h1 ? (unsigned)(A1[i] * 16 + B1[i]) : (unsigned)i;
;             bk[i] = (int)((__float_as_uint(ta + tb) | 255u) - code); }
;         sort16_desc(bk);
	v_bitop3_b32 v18, v20, s68, v18 bitop3:0x36
	v_and_b32_e32 v20, 0x7f, v77
	v_and_b32_e32 v22, 0x7f00, v22
	v_and_b32_e32 v24, 0x7f0000, v24
	v_max_i32_e32 v37, v30, v29
	v_min_i32_e32 v29, v30, v29
	v_max_i32_e32 v30, v25, v23
	v_min_i32_e32 v38, v25, v23
	v_lshlrev_b32_e32 v23, 8, v34
	v_or3_b32 v20, v22, v20, v24
	v_lshlrev_b32_e32 v22, 16, v35
	v_and_b32_e32 v21, 0x7f, v32
	v_and_b32_e32 v23, 0x7f00, v23
	v_and_b32_e32 v22, 0x7f0000, v22
	v_or3_b32 v22, v23, v21, v22
	v_lshlrev_b32_e32 v21, 24, v73
	v_and_b32_e32 v21, 0x7f000000, v21
	v_bitop3_b32 v21, v20, s68, v21 bitop3:0x36
	v_lshlrev_b32_e32 v20, 24, v27
	v_and_b32_e32 v20, 0x7f000000, v20
	v_lshlrev_b32_e32 v24, 8, v74
	v_lshlrev_b32_e32 v42, 16, v72
	v_bitop3_b32 v20, v22, s68, v20 bitop3:0x36
	v_and_b32_e32 v22, 0x7f, v71
	v_and_b32_e32 v24, 0x7f00, v24
	v_and_b32_e32 v42, 0x7f0000, v42
	v_lshlrev_b32_e32 v25, 8, v29
	v_or3_b32 v22, v24, v22, v42
	v_lshlrev_b32_e32 v24, 16, v30
	v_and_b32_e32 v23, 0x7f, v37
	v_and_b32_e32 v25, 0x7f00, v25
	v_and_b32_e32 v24, 0x7f0000, v24
	v_or3_b32 v24, v25, v23, v24
	v_lshlrev_b32_e32 v23, 24, v70
	v_and_b32_e32 v23, 0x7f000000, v23
	v_bitop3_b32 v23, v22, s68, v23 bitop3:0x36
	v_lshlrev_b32_e32 v22, 24, v38
	v_and_b32_e32 v22, 0x7f000000, v22
	v_lshlrev_b32_e32 v42, 8, v68
	v_lshlrev_b32_e32 v44, 16, v67
	v_bitop3_b32 v22, v24, s68, v22 bitop3:0x36
	v_and_b32_e32 v24, 0x7f, v69
	v_and_b32_e32 v42, 0x7f00, v42
	v_and_b32_e32 v44, 0x7f0000, v44
	v_lshlrev_b32_e32 v43, 8, v31
	v_or3_b32 v24, v42, v24, v44
	v_lshlrev_b32_e32 v42, 16, v40
	v_and_b32_e32 v25, 0x7f, v39
	v_and_b32_e32 v43, 0x7f00, v43
	v_and_b32_e32 v42, 0x7f0000, v42
	v_or3_b32 v42, v43, v25, v42
	v_lshlrev_b32_e32 v25, 24, v66
	v_and_b32_e32 v25, 0x7f000000, v25
	v_bitop3_b32 v25, v24, s68, v25 bitop3:0x36
	v_lshlrev_b32_e32 v24, 24, v41
	v_and_b32_e32 v24, 0x7f000000, v24
	v_bitop3_b32 v24, v42, s68, v24 bitop3:0x36
	v_mov_b32_e32 v42, v86
	v_add_f32_e32 v62, v74, v26
	v_cmp_eq_u32_e32 vcc, 0, v42
	v_add_f32_e32 v63, v72, v26
	v_add_f32_e32 v64, v70, v26
	v_cndmask_b32_e32 v42, v81, v79, vcc
	v_add_f32_e32 v44, v42, v26
	v_cndmask_b32_e64 v43, -16, 0, vcc
	v_or_b32_e32 v44, 0xff, v44
	v_add_f32_e32 v45, v42, v33
	v_add_u32_e32 v43, v44, v43
	v_cndmask_b32_e64 v44, v99, -1, vcc
	v_or_b32_e32 v45, 0xff, v45
	v_add_f32_e32 v46, v42, v36
	v_add_u32_e32 v44, v45, v44
	v_cndmask_b32_e64 v45, v100, -2, vcc
	v_or_b32_e32 v46, 0xff, v46
	v_add_f32_e32 v47, v42, v28
	v_add_u32_e32 v45, v46, v45
	v_cndmask_b32_e64 v46, v101, -3, vcc
	v_or_b32_e32 v47, 0xff, v47
	v_add_f32_e32 v48, v42, v32
	v_add_u32_e32 v46, v47, v46
	v_cndmask_b32_e64 v47, v102, -4, vcc
	v_or_b32_e32 v48, 0xff, v48
	v_add_f32_e32 v34, v42, v34
	v_add_f32_e32 v35, v42, v35
	v_add_f32_e32 v27, v42, v27
	v_cndmask_b32_e32 v42, v80, v79, vcc
	v_cndmask_b32_e32 v32, v32, v39, vcc
	v_add_u32_e32 v47, v48, v47
	v_cndmask_b32_e64 v48, v103, -5, vcc
	v_or_b32_e32 v34, 0xff, v34
	v_add_f32_e32 v32, v42, v32
	v_add_u32_e32 v34, v34, v48
	v_cndmask_b32_e64 v48, v104, -6, vcc
	v_or_b32_e32 v35, 0xff, v35
	v_cndmask_b32_e32 v37, v26, v37, vcc
	v_cndmask_b32_e64 v39, v116, -12, vcc
	v_or_b32_e32 v32, 0xff, v32
	v_add_u32_e32 v35, v35, v48
	v_cndmask_b32_e64 v48, v105, -7, vcc
	v_or_b32_e32 v27, 0xff, v27
	v_add_f32_e32 v37, v42, v37
	v_cndmask_b32_e32 v29, v33, v29, vcc
	v_add_u32_e32 v32, v32, v39
	v_cndmask_b32_e32 v39, v78, v79, vcc
	v_cndmask_b32_e32 v31, v26, v31, vcc
	v_add_u32_e32 v27, v27, v48
	v_cndmask_b32_e64 v48, v106, -8, vcc
	v_or_b32_e32 v37, 0xff, v37
	v_add_f32_e32 v29, v42, v29
	v_cndmask_b32_e32 v30, v36, v30, vcc
	v_cndmask_b32_e32 v38, v28, v38, vcc
	v_add_f32_e32 v31, v39, v31
	v_cndmask_b32_e32 v40, v33, v40, vcc
	v_add_u32_e32 v37, v37, v48
	v_cndmask_b32_e64 v48, v107, -9, vcc
	v_or_b32_e32 v29, 0xff, v29
	v_add_f32_e32 v30, v42, v30
	v_add_f32_e32 v38, v42, v38
	v_cndmask_b32_e64 v42, v117, -13, vcc
	v_or_b32_e32 v31, 0xff, v31
	v_add_f32_e32 v40, v39, v40
	v_cndmask_b32_e32 v41, v36, v41, vcc
	v_add_u32_e32 v29, v29, v48
	v_cndmask_b32_e64 v48, v114, -10, vcc
	v_or_b32_e32 v30, 0xff, v30
	v_add_u32_e32 v31, v31, v42
	v_cndmask_b32_e64 v42, v118, -14, vcc
	v_or_b32_e32 v40, 0xff, v40
	v_add_f32_e32 v39, v39, v41
	v_add_u32_e32 v30, v30, v48
	v_cndmask_b32_e64 v48, v115, -11, vcc
	v_or_b32_e32 v38, 0xff, v38
	v_add_u32_e32 v40, v40, v42
	v_cndmask_b32_e64 v42, v119, -15, vcc
	v_or_b32_e32 v39, 0xff, v39
	v_add_u32_e32 v38, v38, v48
	v_add_u32_e32 v39, v39, v42
	v_max_i32_e32 v41, v43, v31
	v_min_i32_e32 v31, v43, v31
	v_max_i32_e32 v42, v44, v32
	v_min_i32_e32 v32, v44, v32
	v_max_i32_e32 v43, v45, v39
	v_min_i32_e32 v39, v45, v39
	v_max_i32_e32 v44, v46, v40
	v_min_i32_e32 v40, v46, v40
	v_max_i32_e32 v45, v47, v37
	v_min_i32_e32 v37, v47, v37
	v_max_i32_e32 v46, v34, v35
	v_min_i32_e32 v34, v34, v35
	v_max_i32_e32 v35, v27, v38
	v_min_i32_e32 v27, v27, v38
	v_max_i32_e32 v38, v29, v30
	v_min_i32_e32 v29, v29, v30
	v_max_i32_e32 v30, v41, v46
	v_min_i32_e32 v41, v41, v46
	v_max_i32_e32 v46, v42, v35
	v_min_i32_e32 v35, v42, v35
	v_max_i32_e32 v42, v43, v38
	v_min_i32_e32 v38, v43, v38
	v_max_i32_e32 v43, v44, v45
	v_min_i32_e32 v44, v44, v45
	v_max_i32_e32 v45, v34, v31
	v_min_i32_e32 v31, v34, v31
	v_max_i32_e32 v34, v37, v40
	v_min_i32_e32 v37, v37, v40
	v_max_i32_e32 v40, v29, v39
	v_min_i32_e32 v29, v29, v39
	v_max_i32_e32 v39, v27, v32
	v_min_i32_e32 v27, v27, v32
	v_max_i32_e32 v32, v30, v46
	v_min_i32_e32 v30, v30, v46
	v_max_i32_e32 v46, v42, v43
	v_min_i32_e32 v42, v42, v43
	v_max_i32_e32 v43, v44, v41
	v_min_i32_e32 v41, v44, v41
	v_max_i32_e32 v44, v45, v34
	v_min_i32_e32 v34, v45, v34
; #define CAND(a, b) (int)((__float_as_uint(__int_as_float(top[0][a]) + __int_as_float(top[1][b])) | 255u) - (unsigned)((a) * 16 + (b)))
; __device__ __forceinline__ void route_task(int task, int tl0, const bf16* QP  , const LAS bf16* KHL, LAS unsigned short* EL, LAS float* GL, int lane) {
;     ...
;         sort16_desc(bk);
;         int oth[16];
; #pragma unroll
;         for (int i = 0; i < 16; ++i) oth[i] = __shfl_xor(bk[i], 32);
;         merge16_desc(bk, oth);
;     }
;     ...
;     {
;         int gk[16];
;         gk[0] = CAND(3, 3); gk[1] = CAND(4, 0); gk[2] = CAND(4, 1); gk[3] = CAND(4, 2); gk[4] = CAND(5, 0); gk[5] = CAND(5, 1); gk[6] = CAND(6, 0); gk[7] = CAND(6, 1);
;         gk[8] = CAND(7, 0); gk[9] = CAND(7, 1); gk[10] = CAND(8, 0); gk[11] = CAND(9, 0); gk[12] = CAND(10, 0); gk[13] = CAND(11, 0); gk[14] = CAND(12, 0); gk[15] = CAND(13, 0);
;         sort16_desc(gk);
	v_max_i32_e32 v45, v35, v38
	v_min_i32_e32 v35, v35, v38
	v_max_i32_e32 v38, v40, v39
	v_min_i32_e32 v39, v40, v39
	v_max_i32_e32 v40, v27, v31
	v_min_i32_e32 v27, v27, v31
	v_max_i32_e32 v31, v37, v29
	v_min_i32_e32 v29, v37, v29
	v_max_i32_e32 v37, v32, v46
	v_min_i32_e32 v32, v32, v46
	v_max_i32_e32 v46, v30, v42
	v_min_i32_e32 v30, v30, v42
	v_max_i32_e32 v42, v43, v38
	v_min_i32_e32 v38, v43, v38
	v_max_i32_e32 v43, v41, v39
	v_min_i32_e32 v39, v41, v39
	v_max_i32_e32 v41, v44, v45
	v_min_i32_e32 v44, v44, v45
	v_max_i32_e32 v45, v34, v35
	v_min_i32_e32 v34, v34, v35
	v_max_i32_e32 v35, v40, v31
	v_min_i32_e32 v31, v40, v31
	v_max_i32_e32 v40, v27, v29
	v_min_i32_e32 v27, v27, v29
	v_max_i32_e32 v29, v46, v32
	v_min_i32_e32 v32, v46, v32
	v_max_i32_e32 v46, v30, v35
	v_min_i32_e32 v30, v30, v35
	v_max_i32_e32 v35, v42, v41
	v_min_i32_e32 v41, v42, v41
	v_max_i32_e32 v42, v43, v44
	v_min_i32_e32 v43, v43, v44
	v_max_i32_e32 v44, v45, v38
	v_min_i32_e32 v38, v45, v38
	v_max_i32_e32 v45, v34, v39
	v_min_i32_e32 v34, v34, v39
	v_max_i32_e32 v39, v40, v31
	v_min_i32_e32 v31, v40, v31
	v_max_i32_e32 v40, v29, v35
	v_min_i32_e32 v29, v29, v35
	v_max_i32_e32 v35, v32, v41
	v_min_i32_e32 v32, v32, v41
	v_max_i32_e32 v41, v42, v44
	v_min_i32_e32 v42, v42, v44
	v_max_i32_e32 v44, v43, v38
	v_min_i32_e32 v38, v43, v38
	v_max_i32_e32 v43, v45, v39
	v_min_i32_e32 v39, v45, v39
	v_max_i32_e32 v45, v34, v31
	v_min_i32_e32 v31, v34, v31
	v_max_i32_e32 v34, v35, v29
	v_min_i32_e32 v29, v35, v29
	v_max_i32_e32 v35, v46, v32
	v_min_i32_e32 v32, v46, v32
	v_max_i32_e32 v46, v43, v30
	v_min_i32_e32 v30, v43, v30
	v_max_i32_e32 v43, v45, v39
	v_min_i32_e32 v39, v45, v39
	v_max_i32_e32 v45, v35, v41
	v_min_i32_e32 v35, v35, v41
	v_max_i32_e32 v41, v32, v42
	v_min_i32_e32 v32, v32, v42
	v_max_i32_e32 v42, v44, v46
	v_min_i32_e32 v44, v44, v46
	v_max_i32_e32 v46, v38, v30
	v_min_i32_e32 v30, v38, v30
	v_max_i32_e32 v38, v45, v29
	v_min_i32_e32 v29, v45, v29
	v_max_i32_e32 v45, v35, v41
	v_min_i32_e32 v35, v35, v41
	v_max_i32_e32 v41, v42, v32
	v_min_i32_e32 v32, v42, v32
	v_max_i32_e32 v42, v44, v46
	v_min_i32_e32 v44, v44, v46
	v_max_i32_e32 v46, v43, v30
	v_min_i32_e32 v30, v43, v30
	v_max_i32_e32 v43, v35, v41
	v_min_i32_e32 v35, v35, v41
	v_max_i32_e32 v41, v32, v42
	v_min_i32_e32 v32, v32, v42
	ds_bpermute_b32 v54, v123, v41
	ds_bpermute_b32 v55, v123, v32
	ds_bpermute_b32 v56, v123, v44
	ds_bpermute_b32 v57, v123, v27
	ds_bpermute_b32 v58, v123, v31
	ds_bpermute_b32 v59, v123, v39
	ds_bpermute_b32 v60, v123, v30
	ds_bpermute_b32 v61, v123, v46
	ds_bpermute_b32 v42, v123, v37
	ds_bpermute_b32 v47, v123, v40
	ds_bpermute_b32 v48, v123, v34
	ds_bpermute_b32 v49, v123, v38
	ds_bpermute_b32 v50, v123, v29
	ds_bpermute_b32 v51, v123, v45
	ds_bpermute_b32 v52, v123, v43
	ds_bpermute_b32 v53, v123, v35
	s_waitcnt lgkmcnt(12)
	v_max_i32_e32 v37, v37, v57
	s_waitcnt lgkmcnt(11)
	v_max_i32_e32 v40, v40, v58
	s_waitcnt lgkmcnt(10)
	v_max_i32_e32 v34, v34, v59
	s_waitcnt lgkmcnt(9)
	v_max_i32_e32 v38, v38, v60
	s_waitcnt lgkmcnt(8)
	v_max_i32_e32 v29, v29, v61
	v_max_i32_e32 v45, v45, v56
	v_max_i32_e32 v43, v43, v55
	v_max_i32_e32 v35, v35, v54
	v_add_f32_e32 v28, v78, v28
	v_add_f32_e32 v54, v77, v26
	v_add_f32_e32 v55, v77, v33
	v_add_f32_e32 v36, v77, v36
	v_add_f32_e32 v56, v76, v26
	v_add_f32_e32 v57, v76, v33
	v_add_f32_e32 v58, v75, v26
	v_add_f32_e32 v59, v75, v33
	v_add_f32_e32 v60, v73, v26
	v_add_f32_e32 v33, v73, v33
	v_add_f32_e32 v61, v71, v26
	v_add_f32_e32 v65, v69, v26
	v_add_f32_e32 v68, v68, v26
	v_or_b32_e32 v28, 0xff, v28
	v_or_b32_e32 v54, 0xff, v54
	v_or_b32_e32 v55, 0xff, v55
	v_or_b32_e32 v36, 0xff, v36
	v_or_b32_e32 v56, 0xff, v56
	v_or_b32_e32 v57, 0xff, v57
	v_or_b32_e32 v58, 0xff, v58
	v_or_b32_e32 v59, 0xff, v59
	v_or_b32_e32 v60, 0xff, v60
	v_or_b32_e32 v33, 0xff, v33
	v_or_b32_e32 v61, 0xff, v61
	v_or_b32_e32 v62, 0xff, v62
	v_or_b32_e32 v63, 0xff, v63
	v_or_b32_e32 v64, 0xff, v64
	v_or_b32_e32 v65, 0xff, v65
	v_or_b32_e32 v68, 0xff, v68
	v_subrev_u32_e32 v28, 51, v28
	v_subrev_u32_e32 v54, 64, v54
	v_add_u32_e32 v55, 0xffffffbf, v55
	v_add_u32_e32 v36, 0xffffffbe, v36
	v_add_u32_e32 v56, 0xffffffb0, v56
	v_add_u32_e32 v57, 0xffffffaf, v57
	v_add_u32_e32 v58, 0xffffffa0, v58
	v_add_u32_e32 v59, 0xffffff9f, v59
	v_add_u32_e32 v60, 0xffffff90, v60
	v_add_u32_e32 v33, 0xffffff8f, v33
	v_add_u32_e32 v61, 0xffffff80, v61
	v_add_u32_e32 v62, 0xffffff70, v62
	v_add_u32_e32 v63, 0xffffff60, v63
	v_add_u32_e32 v64, 0xffffff50, v64
	v_add_u32_e32 v65, 0xffffff40, v65
	v_add_u32_e32 v68, 0xffffff30, v68
	v_max_i32_e32 v69, v28, v64
	v_min_i32_e32 v28, v28, v64
	v_max_i32_e32 v64, v54, v63
	v_min_i32_e32 v54, v54, v63
	v_max_i32_e32 v63, v55, v68
	v_min_i32_e32 v55, v55, v68
	v_max_i32_e32 v68, v36, v65
	v_min_i32_e32 v36, v36, v65
	v_max_i32_e32 v65, v56, v60
	v_min_i32_e32 v56, v56, v60
	v_max_i32_e32 v60, v57, v58
	v_min_i32_e32 v57, v57, v58
	v_max_i32_e32 v58, v59, v62
	v_min_i32_e32 v59, v59, v62
	v_max_i32_e32 v62, v33, v61
	v_min_i32_e32 v33, v33, v61
	v_max_i32_e32 v61, v69, v60
	v_min_i32_e32 v60, v69, v60
	v_max_i32_e32 v69, v64, v58
	v_min_i32_e32 v58, v64, v58
	v_max_i32_e32 v64, v63, v62
	v_min_i32_e32 v62, v63, v62
	v_max_i32_e32 v63, v68, v65
	v_min_i32_e32 v65, v68, v65
	v_max_i32_e32 v68, v57, v28
	v_min_i32_e32 v28, v57, v28
	v_max_i32_e32 v57, v56, v36
	v_min_i32_e32 v36, v56, v36
	v_max_i32_e32 v56, v33, v55
	v_min_i32_e32 v33, v33, v55
	v_max_i32_e32 v55, v59, v54
	v_min_i32_e32 v54, v59, v54
	v_max_i32_e32 v59, v61, v69
	v_min_i32_e32 v61, v61, v69
	v_max_i32_e32 v69, v64, v63
	v_min_i32_e32 v63, v64, v63
	v_max_i32_e32 v64, v65, v60
	v_min_i32_e32 v60, v65, v60
	v_max_i32_e32 v65, v68, v57
	v_min_i32_e32 v57, v68, v57
	v_max_i32_e32 v68, v58, v62
	v_min_i32_e32 v58, v58, v62
	v_max_i32_e32 v62, v56, v55
	v_min_i32_e32 v55, v56, v55
	v_max_i32_e32 v56, v54, v28
	v_min_i32_e32 v28, v54, v28
	v_max_i32_e32 v54, v36, v33
	v_min_i32_e32 v33, v36, v33
	v_min_i32_e32 v36, v59, v69
	v_max_i32_e32 v70, v61, v63
	v_min_i32_e32 v61, v61, v63
	v_max_i32_e32 v63, v64, v62
	v_min_i32_e32 v62, v64, v62
	v_max_i32_e32 v64, v60, v55
	v_min_i32_e32 v55, v60, v55
	v_max_i32_e32 v60, v65, v68
	v_min_i32_e32 v65, v65, v68
	v_max_i32_e32 v68, v57, v58
	v_min_i32_e32 v57, v57, v58
	v_max_i32_e32 v58, v56, v54
	v_min_i32_e32 v54, v56, v54
	v_max_i32_e32 v56, v28, v33
	v_min_i32_e32 v28, v28, v33
	v_max_i32_e32 v33, v70, v36
	v_min_i32_e32 v36, v70, v36
	v_max_i32_e32 v70, v61, v58
	v_min_i32_e32 v58, v61, v58
	v_max_i32_e32 v61, v63, v60
	v_min_i32_e32 v60, v63, v60
	v_max_i32_e32 v63, v64, v65
	v_min_i32_e32 v64, v64, v65
	v_max_i32_e32 v65, v68, v62
	v_min_i32_e32 v62, v68, v62
	v_max_i32_e32 v68, v57, v55
	v_min_i32_e32 v55, v57, v55
	v_max_i32_e32 v57, v56, v54
	s_waitcnt lgkmcnt(0)
; #define CAND(a, b) (int)((__float_as_uint(__int_as_float(top[0][a]) + __int_as_float(top[1][b])) | 255u) - (unsigned)((a) * 16 + (b)))
; __device__ __forceinline__ void route_task(int task, int tl0, const bf16* QP  , const LAS bf16* KHL, LAS unsigned short* EL, LAS float* GL, int lane) {
;     ...
;         sort16_desc(bk);
;         int oth[16];
; #pragma unroll
;         for (int i = 0; i < 16; ++i) oth[i] = __shfl_xor(bk[i], 32);
;         merge16_desc(bk, oth);
;     }
;     ...
;     {
;         int gk[16];
;         gk[0] = CAND(3, 3); gk[1] = CAND(4, 0); gk[2] = CAND(4, 1); gk[3] = CAND(4, 2); gk[4] = CAND(5, 0); gk[5] = CAND(5, 1); gk[6] = CAND(6, 0); gk[7] = CAND(6, 1);
;         gk[8] = CAND(7, 0); gk[9] = CAND(7, 1); gk[10] = CAND(8, 0); gk[11] = CAND(9, 0); gk[12] = CAND(10, 0); gk[13] = CAND(11, 0); gk[14] = CAND(12, 0); gk[15] = CAND(13, 0);
;         sort16_desc(gk);
;         merge16_desc(bk, gk);
;     }
;     {
;         const int c14 = CAND(14, 0), c15 = CAND(15, 0);
;         const int n14 = max(bk[14], c14), n15 = max(min(bk[14], c14), max(bk[15], c15));
;         bk[14] = n14; bk[15] = n15;
;     }
	v_max_i32_e32 v41, v41, v53
	v_max_i32_e32 v32, v32, v52
	v_max_i32_e32 v44, v44, v51
	v_max_i32_e32 v46, v46, v50
	v_max_i32_e32 v30, v30, v49
	v_max_i32_e32 v39, v39, v48
	v_max_i32_e32 v31, v31, v47
	v_max_i32_e32 v27, v27, v42
	v_min_i32_e32 v54, v56, v54
	v_max_i32_e32 v56, v33, v61
	v_min_i32_e32 v33, v33, v61
	v_max_i32_e32 v61, v36, v60
	v_min_i32_e32 v36, v36, v60
	v_max_i32_e32 v60, v63, v65
	v_min_i32_e32 v63, v63, v65
	v_max_i32_e32 v65, v64, v62
	v_min_i32_e32 v62, v64, v62
	v_max_i32_e32 v64, v68, v57
	v_max_i32_e32 v42, v37, v41
	v_min_i32_e32 v37, v37, v41
	v_max_i32_e32 v41, v40, v32
	v_min_i32_e32 v32, v40, v32
	v_max_i32_e32 v40, v34, v44
	v_min_i32_e32 v34, v34, v44
	v_max_i32_e32 v44, v38, v46
	v_min_i32_e32 v38, v38, v46
	v_max_i32_e32 v46, v29, v30
	v_min_i32_e32 v29, v29, v30
	v_max_i32_e32 v30, v45, v39
	v_min_i32_e32 v39, v45, v39
	v_max_i32_e32 v45, v43, v31
	v_min_i32_e32 v31, v43, v31
	v_max_i32_e32 v43, v35, v27
	v_min_i32_e32 v27, v35, v27
	v_min_i32_e32 v57, v68, v57
	v_max_i32_e32 v68, v55, v54
	v_max_i32_e32 v71, v70, v36
	v_min_i32_e32 v36, v70, v36
	v_max_i32_e32 v70, v64, v58
	v_min_i32_e32 v58, v64, v58
	v_max_i32_e32 v35, v42, v46
	v_min_i32_e32 v42, v42, v46
	v_max_i32_e32 v46, v41, v30
	v_min_i32_e32 v30, v41, v30
	v_max_i32_e32 v41, v40, v45
	v_min_i32_e32 v40, v40, v45
	v_max_i32_e32 v45, v44, v43
	v_min_i32_e32 v43, v44, v43
	v_max_i32_e32 v44, v37, v29
	v_min_i32_e32 v29, v37, v29
	v_max_i32_e32 v37, v32, v39
	v_min_i32_e32 v32, v32, v39
	v_max_i32_e32 v39, v34, v31
	v_min_i32_e32 v31, v34, v31
	v_max_i32_e32 v34, v38, v27
	v_min_i32_e32 v27, v38, v27
	v_min_i32_e32 v54, v55, v54
	v_min_i32_e32 v55, v61, v33
	v_max_i32_e32 v64, v68, v57
	v_min_i32_e32 v57, v68, v57
	v_max_i32_e32 v68, v71, v60
	v_min_i32_e32 v60, v71, v60
	v_max_i32_e32 v71, v36, v63
	v_min_i32_e32 v36, v36, v63
	v_max_i32_e32 v63, v65, v70
	v_min_i32_e32 v65, v65, v70
	v_max_i32_e32 v70, v62, v58
	v_max_i32_e32 v38, v35, v41
	v_min_i32_e32 v35, v35, v41
	v_max_i32_e32 v41, v46, v45
	v_min_i32_e32 v45, v46, v45
	v_max_i32_e32 v46, v42, v40
	v_min_i32_e32 v40, v42, v40
	v_max_i32_e32 v42, v30, v43
	v_min_i32_e32 v30, v30, v43
	v_max_i32_e32 v43, v44, v39
	v_min_i32_e32 v39, v44, v39
	v_max_i32_e32 v44, v37, v34
	v_min_i32_e32 v34, v37, v34
	v_max_i32_e32 v37, v29, v31
	v_min_i32_e32 v29, v29, v31
	v_max_i32_e32 v31, v32, v27
	v_min_i32_e32 v27, v32, v27
	v_min_i32_e32 v58, v62, v58
	v_max_i32_e32 v62, v68, v55
	v_min_i32_e32 v55, v68, v55
	v_max_i32_e32 v68, v60, v71
	v_min_i32_e32 v60, v60, v71
	v_max_i32_e32 v71, v63, v36
	v_min_i32_e32 v36, v63, v36
	v_max_i32_e32 v63, v65, v70
	v_min_i32_e32 v32, v38, v41
	v_min_i32_e32 v47, v35, v45
	v_min_i32_e32 v48, v46, v42
	v_min_i32_e32 v49, v40, v30
	v_min_i32_e32 v50, v43, v44
	v_min_i32_e32 v51, v39, v34
	v_min_i32_e32 v52, v37, v31
	v_min_i32_e32 v53, v29, v27
	v_min_i32_e32 v65, v65, v70
	v_max_i32_e32 v70, v64, v58
	v_min_i32_e32 v58, v64, v58
	v_min_i32_e32 v64, v60, v71
	v_min_i32_e32 v72, v36, v63
	v_max3_i32 v28, v38, v41, v28
	v_max_i32_e32 v32, v32, v54
	v_max3_i32 v35, v35, v45, v57
	v_max_i32_e32 v38, v47, v58
	v_max3_i32 v41, v46, v42, v70
	v_max_i32_e32 v42, v48, v65
	v_max3_i32 v30, v40, v30, v72
	v_max3_i32 v36, v49, v36, v63
	v_max3_i32 v40, v43, v44, v64
	v_max3_i32 v43, v50, v60, v71
	v_max3_i32 v34, v39, v34, v68
	v_max_i32_e32 v39, v51, v55
	v_max3_i32 v31, v37, v31, v62
	v_max3_i32 v33, v52, v61, v33
	v_max3_i32 v27, v29, v27, v56
	v_max3_i32 v29, v53, v59, v69
	v_max_i32_e32 v37, v28, v40
	v_min_i32_e32 v28, v28, v40
	v_max_i32_e32 v40, v32, v43
	v_min_i32_e32 v32, v32, v43
	v_max_i32_e32 v43, v35, v34
	v_min_i32_e32 v34, v35, v34
	v_max_i32_e32 v35, v38, v39
	v_min_i32_e32 v38, v38, v39
	v_max_i32_e32 v39, v41, v31
	v_min_i32_e32 v31, v41, v31
	v_max_i32_e32 v41, v42, v33
	v_min_i32_e32 v33, v42, v33
	v_max_i32_e32 v42, v30, v27
	v_min_i32_e32 v27, v30, v27
	v_max_i32_e32 v30, v36, v29
	v_min_i32_e32 v29, v36, v29
	v_max_i32_e32 v36, v37, v39
	v_min_i32_e32 v37, v37, v39
	v_max_i32_e32 v39, v40, v41
	v_min_i32_e32 v40, v40, v41
	v_max_i32_e32 v41, v43, v42
	v_min_i32_e32 v42, v43, v42
	v_max_i32_e32 v43, v35, v30
	v_min_i32_e32 v30, v35, v30
	v_max_i32_e32 v35, v28, v31
	v_min_i32_e32 v28, v28, v31
	v_max_i32_e32 v31, v32, v33
	v_min_i32_e32 v32, v32, v33
	v_max_i32_e32 v33, v34, v27
	v_min_i32_e32 v27, v34, v27
	v_max_i32_e32 v34, v38, v29
	v_min_i32_e32 v29, v38, v29
	v_max_i32_e32 v38, v36, v41
	v_min_i32_e32 v36, v36, v41
	v_max_i32_e32 v41, v39, v43
	v_min_i32_e32 v39, v39, v43
	v_max_i32_e32 v43, v37, v42
	v_min_i32_e32 v37, v37, v42
	v_max_i32_e32 v42, v40, v30
	v_min_i32_e32 v30, v40, v30
	v_max_i32_e32 v40, v35, v33
	v_min_i32_e32 v33, v35, v33
	v_max_i32_e32 v35, v31, v34
	v_min_i32_e32 v31, v31, v34
	v_max_i32_e32 v34, v28, v27
	v_min_i32_e32 v27, v28, v27
	v_max_i32_e32 v28, v32, v29
	v_min_i32_e32 v29, v32, v29
	v_max_i32_e32 v32, v38, v41
	v_min_i32_e32 v38, v38, v41
	v_max_i32_e32 v41, v36, v39
	v_min_i32_e32 v36, v36, v39
	v_max_i32_e32 v39, v43, v42
	v_min_i32_e32 v42, v43, v42
	v_max_i32_e32 v43, v37, v30
	v_min_i32_e32 v30, v37, v30
	v_max_i32_e32 v37, v40, v35
	v_min_i32_e32 v35, v40, v35
	v_max_i32_e32 v40, v33, v31
	v_min_i32_e32 v31, v33, v31
	v_max_i32_e32 v33, v34, v28
	v_min_i32_e32 v28, v34, v28
	v_max_i32_e32 v34, v27, v29
	v_min_i32_e32 v27, v27, v29
	v_add_f32_e32 v29, v67, v26
	v_or_b32_e32 v29, 0xff, v29
	v_add_f32_e32 v26, v66, v26
	v_add_u32_e32 v29, 0xffffff20, v29
	v_or_b32_e32 v26, 0xff, v26
	v_add_u32_e32 v26, 0xffffff10, v26
	v_max_i32_e32 v44, v34, v29
	v_min_i32_e32 v29, v34, v29
	v_max3_i32 v26, v29, v27, v26
; __device__ __forceinline__ void route_task(int task, int tl0, const bf16* QP  , const LAS bf16* KHL, LAS unsigned short* EL, LAS float* GL, int lane) {
;     ...
;     int my[8];
; #pragma unroll
;     for (int i = 0; i < 8; ++i) { int lo_ = bk[i], hi_ = bk[8 + i]; asm volatile("" : "+v"(lo_), "+v"(hi_)); my[i] = hi ? hi_ : lo_; }
;     int bv[8];
; #pragma unroll
;     for (int i = 0; i < 8; ++i) {
;         const unsigned cd = 255u - ((unsigned)my[i] & 255u), ca = cd >> 4, cb = cd & 15u;
;         const unsigned wa = (ca >> 2) == 0u ? P1[0] : (ca >> 2) == 1u ? P1[1] : (ca >> 2) == 2u ? P1[2] : P1[3];
;         const unsigned wb = (cb >> 2) == 0u ? P2[0] : (cb >> 2) == 1u ? P2[1] : (cb >> 2) == 2u ? P2[2] : P2[3];
;         bv[i] = (int)((((wa >> (8u * (ca & 3u))) & 255u) << 7) | ((wb >> (8u * (cb & 3u))) & 255u));
;     }
	v_mov_b32_e32 v27, v32
	s_nop 0
	v_cndmask_b32_e64 v27, v37, v27, s[6:7]
	v_not_b32_e32 v29, v27
	v_bfe_u32 v45, v29, 6, 2
	v_cmp_eq_u32_e32 vcc, 2, v45
	v_cndmask_b32_e64 v30, v26, v30, s[6:7]
	v_bitop3_b32 v26, v27, s3, v27 bitop3:0xc
	v_cndmask_b32_e32 v46, v25, v23, vcc
	v_cmp_eq_u32_e32 vcc, 1, v45
	v_cndmask_b32_e64 v34, v35, v38, s[6:7]
	v_not_b32_e32 v35, v34
	v_cndmask_b32_e32 v45, v46, v21, vcc
	v_cmp_gt_u32_e32 vcc, 64, v26
	v_cndmask_b32_e64 v37, v40, v41, s[6:7]
	v_cndmask_b32_e64 v41, v44, v43, s[6:7]
	v_cndmask_b32_e32 v26, v45, v19, vcc
	v_bfe_u32 v45, v29, 2, 2
	v_cmp_eq_u32_e32 vcc, 2, v45
	v_bitop3_b32 v44, v27, 15, v27 bitop3:0xc
	v_bfe_u32 v47, v35, 6, 2
	v_cndmask_b32_e32 v46, v24, v22, vcc
	v_cmp_eq_u32_e32 vcc, 1, v45
	v_not_b32_e32 v38, v37
	v_bfe_u32 v49, v38, 6, 2
	v_cndmask_b32_e32 v45, v46, v20, vcc
	v_cmp_gt_u32_e32 vcc, 4, v44
	v_bitop3_b32 v46, v34, 15, v34 bitop3:0xc
	v_cndmask_b32_e64 v31, v31, v36, s[6:7]
	v_cndmask_b32_e32 v44, v45, v18, vcc
	v_cmp_eq_u32_e32 vcc, 2, v47
	v_bitop3_b32 v45, v34, s3, v34 bitop3:0xc
	v_not_b32_e32 v36, v31
	v_cndmask_b32_e32 v48, v25, v23, vcc
	v_cmp_eq_u32_e32 vcc, 1, v47
	v_bfe_u32 v51, v36, 6, 2
	v_cndmask_b32_e64 v33, v33, v39, s[6:7]
	v_cndmask_b32_e32 v47, v48, v21, vcc
	v_cmp_gt_u32_e32 vcc, 64, v45
	v_not_b32_e32 v39, v33
	v_bfe_u32 v53, v39, 6, 2
	v_cndmask_b32_e32 v45, v47, v19, vcc
	v_bfe_u32 v47, v35, 2, 2
	v_cmp_eq_u32_e32 vcc, 2, v47
	v_cndmask_b32_e64 v28, v28, v42, s[6:7]
	v_not_b32_e32 v40, v28
	v_cndmask_b32_e32 v48, v24, v22, vcc
	v_cmp_eq_u32_e32 vcc, 1, v47
	v_bfe_u32 v55, v40, 6, 2
	v_not_b32_e32 v42, v41
	v_cndmask_b32_e32 v47, v48, v20, vcc
	v_cmp_gt_u32_e32 vcc, 4, v46
	v_bitop3_b32 v48, v37, 15, v37 bitop3:0xc
	v_bfe_u32 v57, v42, 6, 2
	v_cndmask_b32_e32 v46, v47, v18, vcc
	v_cmp_eq_u32_e32 vcc, 2, v49
	v_bitop3_b32 v47, v37, s3, v37 bitop3:0xc
	v_not_b32_e32 v43, v30
	v_cndmask_b32_e32 v50, v25, v23, vcc
	v_cmp_eq_u32_e32 vcc, 1, v49
	v_bfe_u32 v59, v43, 6, 2
	s_nop 0
	v_cndmask_b32_e32 v49, v50, v21, vcc
	v_cmp_gt_u32_e32 vcc, 64, v47
	s_nop 1
	v_cndmask_b32_e32 v47, v49, v19, vcc
	v_bfe_u32 v49, v38, 2, 2
	v_cmp_eq_u32_e32 vcc, 2, v49
	s_nop 1
	v_cndmask_b32_e32 v50, v24, v22, vcc
	v_cmp_eq_u32_e32 vcc, 1, v49
	s_nop 1
	v_cndmask_b32_e32 v49, v50, v20, vcc
	v_cmp_gt_u32_e32 vcc, 4, v48
	v_bitop3_b32 v50, v31, 15, v31 bitop3:0xc
	s_nop 0
	v_cndmask_b32_e32 v48, v49, v18, vcc
	v_cmp_eq_u32_e32 vcc, 2, v51
	v_bitop3_b32 v49, v31, s3, v31 bitop3:0xc
	s_nop 0
	v_cndmask_b32_e32 v52, v25, v23, vcc
	v_cmp_eq_u32_e32 vcc, 1, v51
	s_nop 1
	v_cndmask_b32_e32 v51, v52, v21, vcc
	v_cmp_gt_u32_e32 vcc, 64, v49
	s_nop 1
	v_cndmask_b32_e32 v49, v51, v19, vcc
	v_bfe_u32 v51, v36, 2, 2
	v_cmp_eq_u32_e32 vcc, 2, v51
	s_nop 1
	v_cndmask_b32_e32 v52, v24, v22, vcc
	v_cmp_eq_u32_e32 vcc, 1, v51
	s_nop 1
	v_cndmask_b32_e32 v51, v52, v20, vcc
	v_cmp_gt_u32_e32 vcc, 4, v50
	v_bitop3_b32 v52, v33, 15, v33 bitop3:0xc
	s_nop 0
	v_cndmask_b32_e32 v50, v51, v18, vcc
	v_cmp_eq_u32_e32 vcc, 2, v53
	v_bitop3_b32 v51, v33, s3, v33 bitop3:0xc
	s_nop 0
	v_cndmask_b32_e32 v54, v25, v23, vcc
	v_cmp_eq_u32_e32 vcc, 1, v53
	s_nop 1
	v_cndmask_b32_e32 v53, v54, v21, vcc
	v_cmp_gt_u32_e32 vcc, 64, v51
	s_nop 1
	v_cndmask_b32_e32 v51, v53, v19, vcc
	v_bfe_u32 v53, v39, 2, 2
	v_cmp_eq_u32_e32 vcc, 2, v53
	s_nop 1
	v_cndmask_b32_e32 v54, v24, v22, vcc
	v_cmp_eq_u32_e32 vcc, 1, v53
	s_nop 1
	v_cndmask_b32_e32 v53, v54, v20, vcc
	v_cmp_gt_u32_e32 vcc, 4, v52
	v_bitop3_b32 v54, v28, 15, v28 bitop3:0xc
	s_nop 0
	v_cndmask_b32_e32 v52, v53, v18, vcc
	v_cmp_eq_u32_e32 vcc, 2, v55
	v_bitop3_b32 v53, v28, s3, v28 bitop3:0xc
	s_nop 0
	v_cndmask_b32_e32 v56, v25, v23, vcc
	v_cmp_eq_u32_e32 vcc, 1, v55
	s_nop 1
	v_cndmask_b32_e32 v55, v56, v21, vcc
	v_cmp_gt_u32_e32 vcc, 64, v53
	s_nop 1
	v_cndmask_b32_e32 v53, v55, v19, vcc
	v_bfe_u32 v55, v40, 2, 2
	v_cmp_eq_u32_e32 vcc, 2, v55
	s_nop 1
	v_cndmask_b32_e32 v56, v24, v22, vcc
	v_cmp_eq_u32_e32 vcc, 1, v55
	s_nop 1
	v_cndmask_b32_e32 v55, v56, v20, vcc
	v_cmp_gt_u32_e32 vcc, 4, v54
	v_bitop3_b32 v56, v41, 15, v41 bitop3:0xc
	s_nop 0
	v_cndmask_b32_e32 v54, v55, v18, vcc
	v_cmp_eq_u32_e32 vcc, 2, v57
	v_bitop3_b32 v55, v41, s3, v41 bitop3:0xc
	s_nop 0
	v_cndmask_b32_e32 v58, v25, v23, vcc
	v_cmp_eq_u32_e32 vcc, 1, v57
	s_nop 1
	v_cndmask_b32_e32 v57, v58, v21, vcc
	v_cmp_gt_u32_e32 vcc, 64, v55
	s_nop 1
	v_cndmask_b32_e32 v55, v57, v19, vcc
	v_bfe_u32 v57, v42, 2, 2
	v_cmp_eq_u32_e32 vcc, 2, v57
	s_nop 1
	v_cndmask_b32_e32 v58, v24, v22, vcc
	v_cmp_eq_u32_e32 vcc, 1, v57
	s_nop 1
	v_cndmask_b32_e32 v57, v58, v20, vcc
	v_cmp_gt_u32_e32 vcc, 4, v56
	v_bitop3_b32 v58, v30, 15, v30 bitop3:0xc
	s_nop 0
	v_cndmask_b32_e32 v56, v57, v18, vcc
	v_cmp_eq_u32_e32 vcc, 2, v59
	v_bitop3_b32 v57, v30, s3, v30 bitop3:0xc
	s_nop 0
	v_cndmask_b32_e32 v23, v25, v23, vcc
	v_cmp_eq_u32_e32 vcc, 1, v59
	v_sub_f32_e32 v25, v31, v32
	v_mul_f32_e32 v25, 0x3fb8aa3b, v25
	v_cndmask_b32_e32 v21, v23, v21, vcc
	v_cmp_gt_u32_e32 vcc, 64, v57
	v_lshrrev_b32_e32 v23, 1, v39
	v_and_b32_e32 v23, 24, v23
	v_cndmask_b32_e32 v19, v21, v19, vcc
	v_bfe_u32 v21, v43, 2, 2
	v_cmp_eq_u32_e32 vcc, 2, v21
	v_lshrrev_b32_e32 v23, v23, v51
	v_lshlrev_b32_e32 v23, 7, v23
	v_cndmask_b32_e32 v22, v24, v22, vcc
	v_cmp_eq_u32_e32 vcc, 1, v21
	v_lshrrev_b32_e32 v21, 1, v42
	v_and_b32_e32 v21, 24, v21
	v_cndmask_b32_e32 v20, v22, v20, vcc
	v_cmp_gt_u32_e32 vcc, 4, v58
	v_lshrrev_b32_e32 v21, v21, v55
	v_lshrrev_b32_e32 v22, 1, v40
	v_cndmask_b32_e32 v18, v20, v18, vcc
	v_lshlrev_b32_e32 v20, 3, v42
	v_lshlrev_b32_e32 v21, 7, v21
	v_and_b32_e32 v22, 24, v22
	v_lshrrev_b32_e32 v20, v20, v56
; #define LAS __attribute__((address_space(3)))
; __device__ __forceinline__ void peer_u_item(int p, int j, const LAS unsigned short* EL  , const unsigned char* __restrict__ XQ, const unsigned char* __restrict__ U8, LAS int* ACC  , int lane, int wave) {
;     asm volatile("" : "+v"(lane));
;     const int gidx = lane >> 3; const unsigned coff = (unsigned)(p * 128 + (lane & 7) * 16), toff = (unsigned)(p * (16384 * 128) + (lane & 7) * 16);
; #pragma unroll 1
;     for (int it = 0; it < 8; ++it) {
;         const int t = j * 64 + it * 8 + wave;
;         unsigned E[8];
;         { const LAS v4u* ep = (const LAS v4u*)(EL + (it * 8 + wave) * 128 + 16 * gidx); const v4u e0 = ep[0], e1 = ep[1];
;           E[0] = e0.x; E[1] = e0.y; E[2] = e0.z; E[3] = e0.w; E[4] = e1.x; E[5] = e1.y; E[6] = e1.z; E[7] = e1.w; }
;         uint4 uu[16];
; #pragma unroll
;         for (int i = 0; i < 16; ++i) uu[i] = *(const uint4*)(U8 + (size_t)(PE_ID(E, i) * 128u + toff));
;         const uint4 xh = *(const uint4*)(XQ + (size_t)t * 512 + coff), xl = *(const uint4*)(XQ + 8 * MiB + (size_t)t * 512 + coff);
; __device__ __forceinline__ void route_task(int task, int tl0, const bf16* QP  , const LAS bf16* KHL, LAS unsigned short* EL, LAS float* GL, int lane) {
;     ...
;     float e[8], se = 0.f;
; #pragma unroll
;     for (int i = 0; i < 8; ++i) { e[i] = __expf(__int_as_float(my[i]) - __int_as_float(bk[0])); se += e[i]; }
;     se += __shfl_xor(se, 32);
;     const float inv = 1.f / se;
;     {
;         int l2 = lane; asm volatile("" : "+v"(l2));
;         const int o2 = (tl0 + ((l2 & 31) >> 3)) * 128 + (l2 & 7) * 16 + 8 * (l2 >> 5);
;         LAS v4u* ip = (LAS v4u*)(EL + o2); typedef float f4v __attribute__((ext_vector_type(4))); LAS f4v* gp = (LAS f4v*)(GL + o2);
;         ip[0] = (v4u){(unsigned)bv[0] | ((unsigned)bv[1] << 16), (unsigned)bv[2] | ((unsigned)bv[3] << 16), (unsigned)bv[4] | ((unsigned)bv[5] << 16), (unsigned)bv[6] | ((unsigned)bv[7] << 16)};
;         gp[0] = (f4v){e[0] * inv, e[1] * inv, e[2] * inv, e[3] * inv}; gp[1] = (f4v){e[4] * inv, e[5] * inv, e[6] * inv, e[7] * inv};
;     }
	v_and_b32_e32 v21, 0x7f80, v21
	v_lshrrev_b32_e32 v22, v22, v53
	v_and_or_b32 v21, v20, s3, v21
	v_lshlrev_b32_e32 v20, 3, v40
	v_lshlrev_b32_e32 v22, 7, v22
	v_lshrrev_b32_e32 v20, v20, v54
	v_and_b32_e32 v22, 0x7f80, v22
	v_and_or_b32 v20, v20, s3, v22
	v_lshlrev_b32_e32 v22, 3, v39
	v_lshrrev_b32_e32 v22, v22, v52
	v_and_b32_e32 v23, 0x7f80, v23
	v_and_or_b32 v39, v22, s3, v23
	v_lshrrev_b32_e32 v23, 1, v36
	v_and_b32_e32 v23, 24, v23
	v_lshrrev_b32_e32 v23, v23, v49
	v_lshlrev_b32_e32 v22, 3, v36
	v_lshlrev_b32_e32 v23, 7, v23
	v_lshrrev_b32_e32 v22, v22, v50
	v_and_b32_e32 v23, 0x7f80, v23
	v_and_or_b32 v36, v22, s3, v23
	v_lshrrev_b32_e32 v23, 1, v38
	v_and_b32_e32 v23, 24, v23
	v_lshrrev_b32_e32 v23, v23, v47
	v_lshlrev_b32_e32 v22, 3, v38
	v_lshlrev_b32_e32 v23, 7, v23
	v_lshrrev_b32_e32 v22, v22, v48
	v_and_b32_e32 v23, 0x7f80, v23
	v_and_or_b32 v38, v22, s3, v23
	v_lshrrev_b32_e32 v23, 1, v35
	v_and_b32_e32 v23, 24, v23
	v_lshrrev_b32_e32 v23, v23, v45
	v_lshlrev_b32_e32 v22, 3, v35
	v_lshlrev_b32_e32 v23, 7, v23
	v_lshrrev_b32_e32 v22, v22, v46
	v_and_b32_e32 v23, 0x7f80, v23
	v_and_or_b32 v35, v22, s3, v23
	v_lshrrev_b32_e32 v23, 1, v29
	v_and_b32_e32 v23, 24, v23
	v_lshrrev_b32_e32 v23, v23, v26
	v_lshlrev_b32_e32 v22, 3, v29
	v_lshlrev_b32_e32 v23, 7, v23
	v_lshrrev_b32_e32 v22, v22, v44
	v_and_b32_e32 v23, 0x7f80, v23
	v_and_or_b32 v40, v22, s3, v23
	v_sub_f32_e32 v22, v27, v32
	v_mul_f32_e32 v22, 0x3fb8aa3b, v22
	v_sub_f32_e32 v23, v34, v32
	v_exp_f32_e32 v22, v22
	v_mul_f32_e32 v23, 0x3fb8aa3b, v23
	v_sub_f32_e32 v24, v37, v32
	v_exp_f32_e32 v23, v23
	v_mul_f32_e32 v24, 0x3fb8aa3b, v24
	v_exp_f32_e32 v24, v24
	v_exp_f32_e32 v25, v25
	v_add_f32_e32 v26, 0, v22
	v_add_f32_e32 v26, v23, v26
	v_add_f32_e32 v26, v24, v26
	v_add_f32_e32 v31, v25, v26
	v_sub_f32_e32 v26, v33, v32
	v_mul_f32_e32 v26, 0x3fb8aa3b, v26
	v_sub_f32_e32 v27, v28, v32
	v_exp_f32_e32 v26, v26
	v_mul_f32_e32 v27, 0x3fb8aa3b, v27
	v_sub_f32_e32 v28, v41, v32
	v_exp_f32_e32 v27, v27
	v_mul_f32_e32 v28, 0x3fb8aa3b, v28
	v_sub_f32_e32 v29, v30, v32
	v_exp_f32_e32 v28, v28
	v_mul_f32_e32 v29, 0x3fb8aa3b, v29
	v_exp_f32_e32 v29, v29
	v_add_f32_e32 v30, v26, v31
	v_add_f32_e32 v30, v27, v30
	v_add_f32_e32 v30, v28, v30
	v_add_f32_e32 v30, v29, v30
	ds_bpermute_b32 v31, v123, v30
	v_lshrrev_b32_e32 v42, 1, v43
	v_and_b32_e32 v32, 24, v42
	v_lshrrev_b32_e32 v19, v32, v19
	v_lshlrev_b32_e32 v19, 7, v19
	s_waitcnt lgkmcnt(0)
	v_add_f32_e32 v30, v30, v31
	v_div_scale_f32 v31, s[12:13], v30, v30, 1.0
	v_rcp_f32_e32 v32, v31
	v_lshlrev_b32_e32 v33, 3, v43
	v_and_b32_e32 v19, 0x7f80, v19
	v_lshrrev_b32_e32 v18, v33, v18
	v_and_or_b32 v33, v18, s3, v19
	v_fma_f32 v18, -v31, v32, 1.0
	v_fmac_f32_e32 v32, v18, v32
	v_div_scale_f32 v18, vcc, 1.0, v30, 1.0
	v_mul_f32_e32 v19, v18, v32
	v_fma_f32 v34, -v31, v19, v18
	v_fmac_f32_e32 v19, v34, v32
	v_fma_f32 v18, -v31, v19, v18
	v_div_fmas_f32 v18, v18, v32, v19
	v_div_fixup_f32 v30, v18, v30, 1.0
	v_mov_b32_e32 v18, v1
	v_lshl_or_b32 v20, v20, 16, v39
	v_lshrrev_b32_e32 v19, 3, v18
	v_and_or_b32 v19, v19, 3, s57
	v_lshlrev_b32_e32 v31, 4, v18
	v_ashrrev_i32_e32 v18, 2, v18
	v_lshlrev_b32_e32 v19, 7, v19
	v_and_b32_e32 v31, 0x70, v31
	v_and_b32_e32 v18, -8, v18
	v_add3_u32 v18, v18, v31, v19
	v_lshl_add_u32 v31, v18, 1, s11
	v_lshl_add_u32 v32, v18, 2, s69
	v_lshl_or_b32 v18, v35, 16, v40
	v_lshl_or_b32 v19, v36, 16, v38
	v_lshl_or_b32 v21, v33, 16, v21
	ds_write_b128 v31, v[18:21]
	v_pk_mul_f32 v[20:21], v[24:25], v[30:31] op_sel_hi:[1,0]
	v_pk_mul_f32 v[18:19], v[22:23], v[30:31] op_sel_hi:[1,0]
	ds_write_b128 v32, v[18:21]
	v_pk_mul_f32 v[20:21], v[28:29], v[30:31] op_sel_hi:[1,0]
	v_pk_mul_f32 v[18:19], v[26:27], v[30:31] op_sel_hi:[1,0]
	ds_write_b128 v32, v[18:21] offset:16
	v_xor_b32_e32 v18, 4, v112
	v_cmp_lt_i32_e32 vcc, v18, v122
	s_waitcnt lgkmcnt(0)
	s_barrier
	v_cndmask_b32_e32 v18, v112, v18, vcc
	v_lshlrev_b32_e32 v30, 2, v18
	v_xor_b32_e32 v18, 2, v112
	v_cmp_lt_i32_e32 vcc, v18, v122
	s_nop 1
	v_cndmask_b32_e32 v18, v112, v18, vcc
	v_lshlrev_b32_e32 v31, 2, v18
	v_xor_b32_e32 v18, 1, v112
	v_cmp_lt_i32_e32 vcc, v18, v122
	s_nop 1
	v_cndmask_b32_e32 v18, v112, v18, vcc
	v_lshlrev_b32_e32 v32, 2, v18
	v_lshlrev_b32_e32 v56, 4, v1
	v_and_b32_e32 v56, 0x70, v56
	v_lshrrev_b32_e32 v59, 3, v1
	v_lshlrev_b32_e32 v59, 5, v59
	v_add_u32_e32 v59, s66, v59
	v_add_u32_e32 v59, -16, v59
	v_lshl_add_u32 v60, v1, 3, s64
	v_and_b32_e32 v38, 4, v1
	v_cmp_ne_u32_e64 s[10:11], 0, v38
	v_and_b32_e32 v38, 2, v1
	v_cmp_ne_u32_e64 s[12:13], 0, v38
	v_and_b32_e32 v38, 1, v1
	v_cmp_ne_u32_e64 s[14:15], 0, v38
	s_movk_i32 s94, 0x80
	s_mov_b32 s42, 0
	s_mov_b32 s43, 0
	s_mov_b32 s44, 1
	s_mov_b32 s45, 0
	s_lshl_b32 s32, s42, 11
	v_add_u32_e32 v39, s32, v59
	ds_read_b128 v[202:205], v39
	ds_read_b128 v[206:209], v39 offset:16
	s_lshl_b32 s46, s42, 3
	s_add_i32 s46, s46, s40
	s_lshl_b32 s46, s46, 9
	s_lshl_b32 s32, s43, 7
	s_add_i32 s46, s46, s32
	v_add_u32_e32 v57, s46, v56
	global_load_dwordx4 v[186:189], v57, s[34:35]
	global_load_dwordx4 v[190:193], v57, s[36:37]
	v_mov_b32_e32 v58, v56
	s_waitcnt lgkmcnt(0)
	v_and_b32_e32 v38, 0xffff, v202
	v_lshl_add_u32 v38, v38, 7, v58
	global_load_dwordx4 v[122:125], v38, s[96:97]
	v_lshrrev_b32_e32 v38, 16, v202
	v_lshl_add_u32 v38, v38, 7, v58
	global_load_dwordx4 v[126:129], v38, s[96:97]
	v_and_b32_e32 v38, 0xffff, v203
	v_lshl_add_u32 v38, v38, 7, v58
	global_load_dwordx4 v[130:133], v38, s[96:97]
	v_lshrrev_b32_e32 v38, 16, v203
	v_lshl_add_u32 v38, v38, 7, v58
	global_load_dwordx4 v[134:137], v38, s[96:97]
	v_and_b32_e32 v38, 0xffff, v204
	v_lshl_add_u32 v38, v38, 7, v58
	global_load_dwordx4 v[138:141], v38, s[96:97]
	v_lshrrev_b32_e32 v38, 16, v204
	v_lshl_add_u32 v38, v38, 7, v58
	global_load_dwordx4 v[142:145], v38, s[96:97]
	v_and_b32_e32 v38, 0xffff, v205
	v_lshl_add_u32 v38, v38, 7, v58
	global_load_dwordx4 v[146:149], v38, s[96:97]
	v_lshrrev_b32_e32 v38, 16, v205
	v_lshl_add_u32 v38, v38, 7, v58
	global_load_dwordx4 v[150:153], v38, s[96:97]
	v_and_b32_e32 v38, 0xffff, v206
	v_lshl_add_u32 v38, v38, 7, v58
	global_load_dwordx4 v[154:157], v38, s[96:97]
	v_lshrrev_b32_e32 v38, 16, v206
	v_lshl_add_u32 v38, v38, 7, v58
	global_load_dwordx4 v[158:161], v38, s[96:97]
	v_and_b32_e32 v38, 0xffff, v207
	v_lshl_add_u32 v38, v38, 7, v58
	global_load_dwordx4 v[162:165], v38, s[96:97]
	v_lshrrev_b32_e32 v38, 16, v207
	v_lshl_add_u32 v38, v38, 7, v58
	global_load_dwordx4 v[166:169], v38, s[96:97]
	v_and_b32_e32 v38, 0xffff, v208
	v_lshl_add_u32 v38, v38, 7, v58
	global_load_dwordx4 v[170:173], v38, s[96:97]
	v_lshrrev_b32_e32 v38, 16, v208
	v_lshl_add_u32 v38, v38, 7, v58
	global_load_dwordx4 v[174:177], v38, s[96:97]
	v_and_b32_e32 v38, 0xffff, v209
	v_lshl_add_u32 v38, v38, 7, v58
	global_load_dwordx4 v[178:181], v38, s[96:97]
	v_lshrrev_b32_e32 v38, 16, v209
	v_lshl_add_u32 v38, v38, 7, v58
	global_load_dwordx4 v[182:185], v38, s[96:97]
	s_mov_b32 s47, 15
